# strategy 7.11: scalar back-edge block (counter, pointer bumps, exit test) moved from the head of the first load segment to the tail of the last load segment in all 8 K-loops, on top of v069
# baseline (speedup 1.0000x reference)
; #define PG8_STAGE(bufoff, gbase, voff) do { _Pragma("unroll") for (int _i = 0; _i < 2; ++_i) \
;         __builtin_amdgcn_global_load_lds((const unsigned*)((const char*)(gbase) + (voff)[_i]), (PG8_LAS unsigned*)(lds + (bufoff) + ldsw + _i * 8192), 16, 0, 0); } while (0)
; #define PG8_LDA(dst, b, h) do { _Pragma("unroll") for (int m = 0; m < 4; ++m) _Pragma("unroll") for (int k = 0; k < 2; ++k) dst[m][k] = *(const PG8_LAS bf16x8*)(lds + PG8_SA(b, h) + aoff + m * 2048 + k * 1024); } while (0)
; #define PG8_LDB(dst, b, h) do { _Pragma("unroll") for (int n = 0; n < 2; ++n) _Pragma("unroll") for (int k = 0; k < 2; ++k) dst[n][k] = *(const PG8_LAS bf16x8*)(lds + PG8_SB(b, h) + boff + n * 2048 + k * 1024); } while (0)
; #define PG8_MMA(ai, bj, At, Bt) do { __builtin_amdgcn_s_setprio(1); _Pragma("unroll") for (int m = 0; m < 4; ++m) _Pragma("unroll") for (int n = 0; n < 2; ++n) _Pragma("unroll") for (int k = 0; k < 2; ++k) \
;         acc[ai][bj][m][n] = __builtin_amdgcn_mfma_f32_16x16x32_bf16(Bt[n][k], At[m][k], acc[ai][bj][m][n], 0, 0, 0); __builtin_amdgcn_s_setprio(0); } while (0)
; #define PG8_WAIT_V(n) asm volatile("s_waitcnt vmcnt(" #n ")" ::: "memory")
; #define PG8_WAIT_L(n) asm volatile("s_waitcnt lgkmcnt(" #n ")" ::: "memory")
; #define PG8_BAR __builtin_amdgcn_s_barrier()
; #define PG8_SCHED __builtin_amdgcn_sched_barrier(0)
; template <class Epi, class Sched, bool ALIGN_EPI = false, bool SP2 = false>
; __device__ __forceinline__ void gemm_phase(PG8_LAS unsigned char* lds, const Gemm g, const Sched& S, const Epi& E, int tid_in) {
;     ...
;         for (int t = 0; t < nt; t += 2) {
;             const bool last = (t == nt - 2);
;             const char* a1 = cA + (size_t)(t + 1) * kstep;
;             const char* a2 = last ? nA : cA + (size_t)(t + 2) * kstep; const char* b2 = last ? nB : cB + (size_t)(t + 2) * kstep;
;             const char* a3 = a2 + kstep; const char* b3 = b2 + kstep;
;             if (last && has_next) S.a_ready(nxt);
;             if constexpr (SP2) {
;             PG8_LDB(B0, 0, 0); PG8_LDB(B1, 0, 1); PG8_SCHED; PG8_LDA(At, 0, 0); PG8_STAGE(PG8_SA(1, 1), a1 + hstepA, voffA);
;             PG8_WAIT_V(8); PG8_WAIT_L(0); PG8_BAR; PG8_MMA(0, 0, At, B0); PG8_MMA(0, 1, At, B1); PG8_BAR; PG8_SCHED;
;             PG8_LDA(At, 0, 1); PG8_STAGE(PG8_SB(0, 0), b2, voffB); PG8_STAGE(PG8_SB(0, 1), b2 + hstep, voffB); PG8_STAGE(PG8_SA(0, 0), a2, voffA);
.LBB0_282:
	s_add_u32 s26, s24, 0xfff80080
	s_addc_u32 s27, s25, -1
	s_add_i32 s45, 0, 0x10000
	s_cmp_eq_u32 s23, 28
	s_cselect_b32 s29, s19, s27
	s_cselect_b32 s28, s18, s26
	s_cselect_b32 s27, s21, s17
	s_cselect_b32 s26, s20, s15
	s_add_i32 s48, 0, 0x14000
	v_add_u32_e32 v158, s45, v152
	v_add_u32_e32 v186, s48, v152
	ds_read_b128 v[142:145], v158
	ds_read_b128 v[146:149], v158 offset:1024
	ds_read_b128 v[154:157], v158 offset:2048
	ds_read_b128 v[158:161], v158 offset:3072
	ds_read_b128 v[162:165], v186
	ds_read_b128 v[166:169], v186 offset:1024
	ds_read_b128 v[182:185], v186 offset:2048
	ds_read_b128 v[186:189], v186 offset:3072
	v_lshl_add_u64 v[222:223], s[24:25], 0, v[138:139]
	s_add_i32 m0, s33, 0xc000
	ds_read_b128 v[190:193], v153
	ds_read_b128 v[194:197], v153 offset:1024
	ds_read_b128 v[198:201], v153 offset:2048
	ds_read_b128 v[202:205], v153 offset:3072
	ds_read_b128 v[206:209], v153 offset:4096
	ds_read_b128 v[210:213], v153 offset:5120
	ds_read_b128 v[214:217], v153 offset:6144
	ds_read_b128 v[218:221], v153 offset:7168
	global_load_lds_dwordx4 v[222:223], off
	v_lshl_add_u64 v[222:223], s[24:25], 0, v[140:141]
	s_add_i32 m0, s33, 0xe000
	s_nop 0
	global_load_lds_dwordx4 v[222:223], off
	s_waitcnt vmcnt(8)
	s_waitcnt lgkmcnt(0)
	s_barrier
	s_setprio 1
	s_waitcnt lgkmcnt(0)
	v_mfma_f32_16x16x32_bf16 v[126:129], v[142:145], v[190:193], v[126:129]
	v_mfma_f32_16x16x32_bf16 v[118:121], v[154:157], v[190:193], v[118:121]
	v_mfma_f32_16x16x32_bf16 v[110:113], v[142:145], v[198:201], v[110:113]
	v_mfma_f32_16x16x32_bf16 v[102:105], v[154:157], v[198:201], v[102:105]
	v_mfma_f32_16x16x32_bf16 v[94:97], v[142:145], v[206:209], v[94:97]
	v_mfma_f32_16x16x32_bf16 v[86:89], v[154:157], v[206:209], v[86:89]
	v_mfma_f32_16x16x32_bf16 v[78:81], v[142:145], v[214:217], v[78:81]
	v_mfma_f32_16x16x32_bf16 v[70:73], v[154:157], v[214:217], v[70:73]
	v_mfma_f32_16x16x32_bf16 v[126:129], v[146:149], v[194:197], v[126:129]
	v_mfma_f32_16x16x32_bf16 v[118:121], v[158:161], v[194:197], v[118:121]
	v_mfma_f32_16x16x32_bf16 v[110:113], v[146:149], v[202:205], v[110:113]
	v_mfma_f32_16x16x32_bf16 v[102:105], v[158:161], v[202:205], v[102:105]
	v_mfma_f32_16x16x32_bf16 v[94:97], v[146:149], v[210:213], v[94:97]
	v_mfma_f32_16x16x32_bf16 v[86:89], v[158:161], v[210:213], v[86:89]
	v_mfma_f32_16x16x32_bf16 v[78:81], v[146:149], v[218:221], v[78:81]
	v_mfma_f32_16x16x32_bf16 v[70:73], v[158:161], v[218:221], v[70:73]
	s_setprio 0
	s_setprio 1
	v_mfma_f32_16x16x32_bf16 v[122:125], v[162:165], v[190:193], v[122:125]
	v_mfma_f32_16x16x32_bf16 v[114:117], v[182:185], v[190:193], v[114:117]
	v_mfma_f32_16x16x32_bf16 v[106:109], v[162:165], v[198:201], v[106:109]
	v_mfma_f32_16x16x32_bf16 v[98:101], v[182:185], v[198:201], v[98:101]
	v_mfma_f32_16x16x32_bf16 v[90:93], v[162:165], v[206:209], v[90:93]
	v_mfma_f32_16x16x32_bf16 v[82:85], v[182:185], v[206:209], v[82:85]
	v_mfma_f32_16x16x32_bf16 v[74:77], v[162:165], v[214:217], v[74:77]
	v_mfma_f32_16x16x32_bf16 v[66:69], v[182:185], v[214:217], v[66:69]
	v_mfma_f32_16x16x32_bf16 v[122:125], v[166:169], v[194:197], v[122:125]
	v_mfma_f32_16x16x32_bf16 v[114:117], v[186:189], v[194:197], v[114:117]
	v_mfma_f32_16x16x32_bf16 v[106:109], v[166:169], v[202:205], v[106:109]
	v_mfma_f32_16x16x32_bf16 v[98:101], v[186:189], v[202:205], v[98:101]
	v_mfma_f32_16x16x32_bf16 v[90:93], v[166:169], v[210:213], v[90:93]
	v_mfma_f32_16x16x32_bf16 v[82:85], v[186:189], v[210:213], v[82:85]
	v_mfma_f32_16x16x32_bf16 v[74:77], v[166:169], v[218:221], v[74:77]
	v_mfma_f32_16x16x32_bf16 v[66:69], v[186:189], v[218:221], v[66:69]
	s_setprio 0
	s_barrier
	s_add_i32 s45, s45, s31
	v_lshl_add_u64 v[222:223], s[26:27], 0, v[0:1]
	s_mov_b32 m0, s45
	ds_read_b128 v[190:193], v153 offset:16384
	ds_read_b128 v[194:197], v153 offset:17408
	ds_read_b128 v[198:201], v153 offset:18432
	ds_read_b128 v[202:205], v153 offset:19456
	ds_read_b128 v[206:209], v153 offset:20480
	ds_read_b128 v[210:213], v153 offset:21504
	ds_read_b128 v[214:217], v153 offset:22528
	ds_read_b128 v[218:221], v153 offset:23552
	global_load_lds_dwordx4 v[222:223], off
	s_add_i32 m0, s45, 0x2000
	s_add_u32 s46, s26, 0x80000
	v_lshl_add_u64 v[224:225], s[26:27], 0, v[130:131]
	s_addc_u32 s47, s27, 0
	s_add_i32 s45, s48, s31
	global_load_lds_dwordx4 v[224:225], off
	v_lshl_add_u64 v[226:227], s[46:47], 0, v[0:1]
	s_mov_b32 m0, s45
	v_lshl_add_u64 v[228:229], s[28:29], 0, v[132:133]
	global_load_lds_dwordx4 v[226:227], off
	v_lshl_add_u64 v[226:227], s[46:47], 0, v[130:131]
	s_add_i32 m0, s45, 0x2000
	s_nop 0
	global_load_lds_dwordx4 v[226:227], off
	s_waitcnt vmcnt(6)
	s_waitcnt lgkmcnt(0)
	s_barrier
; #define PG8_STAGE(bufoff, gbase, voff) do { _Pragma("unroll") for (int _i = 0; _i < 2; ++_i) \
;         __builtin_amdgcn_global_load_lds((const unsigned*)((const char*)(gbase) + (voff)[_i]), (PG8_LAS unsigned*)(lds + (bufoff) + ldsw + _i * 8192), 16, 0, 0); } while (0)
; #define PG8_LDA(dst, b, h) do { _Pragma("unroll") for (int m = 0; m < 4; ++m) _Pragma("unroll") for (int k = 0; k < 2; ++k) dst[m][k] = *(const PG8_LAS bf16x8*)(lds + PG8_SA(b, h) + aoff + m * 2048 + k * 1024); } while (0)
; #define PG8_LDB(dst, b, h) do { _Pragma("unroll") for (int n = 0; n < 2; ++n) _Pragma("unroll") for (int k = 0; k < 2; ++k) dst[n][k] = *(const PG8_LAS bf16x8*)(lds + PG8_SB(b, h) + boff + n * 2048 + k * 1024); } while (0)
; #define PG8_MMA(ai, bj, At, Bt) do { __builtin_amdgcn_s_setprio(1); _Pragma("unroll") for (int m = 0; m < 4; ++m) _Pragma("unroll") for (int n = 0; n < 2; ++n) _Pragma("unroll") for (int k = 0; k < 2; ++k) \
;         acc[ai][bj][m][n] = __builtin_amdgcn_mfma_f32_16x16x32_bf16(Bt[n][k], At[m][k], acc[ai][bj][m][n], 0, 0, 0); __builtin_amdgcn_s_setprio(0); } while (0)
; #define PG8_WAIT_V(n) asm volatile("s_waitcnt vmcnt(" #n ")" ::: "memory")
; #define PG8_WAIT_L(n) asm volatile("s_waitcnt lgkmcnt(" #n ")" ::: "memory")
; #define PG8_BAR __builtin_amdgcn_s_barrier()
; #define PG8_SCHED __builtin_amdgcn_sched_barrier(0)
; template <class Epi, class Sched, bool ALIGN_EPI = false, bool SP2 = false>
; __device__ __forceinline__ void gemm_phase(PG8_LAS unsigned char* lds, const Gemm g, const Sched& S, const Epi& E, int tid_in) {
;     ...
;             PG8_LDA(At, 0, 1); PG8_STAGE(PG8_SB(0, 0), b2, voffB); PG8_STAGE(PG8_SB(0, 1), b2 + hstep, voffB); PG8_STAGE(PG8_SA(0, 0), a2, voffA);
;             PG8_WAIT_V(8); PG8_WAIT_L(0); PG8_BAR; PG8_MMA(1, 0, At, B0); PG8_MMA(1, 1, At, B1); PG8_BAR; PG8_SCHED;
;             PG8_LDB(B0, 1, 0); PG8_LDB(B1, 1, 1); PG8_SCHED; PG8_LDA(At, 1, 0); PG8_STAGE(PG8_SA(0, 1), a2 + hstepA, voffA);
;             PG8_WAIT_V(8); PG8_WAIT_L(0); PG8_BAR; PG8_MMA(0, 0, At, B0); PG8_MMA(0, 1, At, B1); PG8_BAR; PG8_SCHED;
	s_setprio 1
	s_waitcnt lgkmcnt(0)
	v_mfma_f32_16x16x32_bf16 v[62:65], v[142:145], v[190:193], v[62:65]
	v_mfma_f32_16x16x32_bf16 v[54:57], v[154:157], v[190:193], v[54:57]
	v_mfma_f32_16x16x32_bf16 v[46:49], v[142:145], v[198:201], v[46:49]
	v_mfma_f32_16x16x32_bf16 v[38:41], v[154:157], v[198:201], v[38:41]
	v_mfma_f32_16x16x32_bf16 v[30:33], v[142:145], v[206:209], v[30:33]
	v_mfma_f32_16x16x32_bf16 v[22:25], v[154:157], v[206:209], v[22:25]
	v_mfma_f32_16x16x32_bf16 v[14:17], v[142:145], v[214:217], v[14:17]
	v_mfma_f32_16x16x32_bf16 v[6:9], v[154:157], v[214:217], v[6:9]
	v_mfma_f32_16x16x32_bf16 v[62:65], v[146:149], v[194:197], v[62:65]
	v_mfma_f32_16x16x32_bf16 v[54:57], v[158:161], v[194:197], v[54:57]
	v_mfma_f32_16x16x32_bf16 v[46:49], v[146:149], v[202:205], v[46:49]
	v_mfma_f32_16x16x32_bf16 v[38:41], v[158:161], v[202:205], v[38:41]
	v_mfma_f32_16x16x32_bf16 v[30:33], v[146:149], v[210:213], v[30:33]
	v_mfma_f32_16x16x32_bf16 v[22:25], v[158:161], v[210:213], v[22:25]
	v_mfma_f32_16x16x32_bf16 v[14:17], v[146:149], v[218:221], v[14:17]
	v_mfma_f32_16x16x32_bf16 v[6:9], v[158:161], v[218:221], v[6:9]
	s_setprio 0
	s_setprio 1
	v_mfma_f32_16x16x32_bf16 v[58:61], v[162:165], v[190:193], v[58:61]
	v_mfma_f32_16x16x32_bf16 v[50:53], v[182:185], v[190:193], v[50:53]
	v_mfma_f32_16x16x32_bf16 v[42:45], v[162:165], v[198:201], v[42:45]
	v_mfma_f32_16x16x32_bf16 v[34:37], v[182:185], v[198:201], v[34:37]
	v_mfma_f32_16x16x32_bf16 v[26:29], v[162:165], v[206:209], v[26:29]
	v_mfma_f32_16x16x32_bf16 v[18:21], v[182:185], v[206:209], v[18:21]
	v_mfma_f32_16x16x32_bf16 v[10:13], v[162:165], v[214:217], v[10:13]
	v_mfma_f32_16x16x32_bf16 v[2:5], v[182:185], v[214:217], v[2:5]
	v_mfma_f32_16x16x32_bf16 v[58:61], v[166:169], v[194:197], v[58:61]
	v_mfma_f32_16x16x32_bf16 v[50:53], v[186:189], v[194:197], v[50:53]
	v_mfma_f32_16x16x32_bf16 v[42:45], v[166:169], v[202:205], v[42:45]
	v_mfma_f32_16x16x32_bf16 v[34:37], v[186:189], v[202:205], v[34:37]
	v_mfma_f32_16x16x32_bf16 v[26:29], v[166:169], v[210:213], v[26:29]
	v_mfma_f32_16x16x32_bf16 v[18:21], v[186:189], v[210:213], v[18:21]
	v_mfma_f32_16x16x32_bf16 v[10:13], v[166:169], v[218:221], v[10:13]
	v_mfma_f32_16x16x32_bf16 v[2:5], v[186:189], v[218:221], v[2:5]
	s_setprio 0
	s_barrier
	v_lshl_add_u64 v[226:227], s[28:29], 0, v[134:135]
	s_mov_b32 m0, s33
	s_nop 0
	global_load_lds_dwordx4 v[226:227], off
	s_mov_b32 m0, s34
	s_nop 0
	global_load_lds_dwordx4 v[228:229], off
	s_add_i32 s45, 0, 0x18000
	s_add_i32 s46, 0, 0x1c000
	v_add_u32_e32 v158, s45, v152
	v_add_u32_e32 v186, s46, v152
	ds_read_b128 v[142:145], v158
	ds_read_b128 v[146:149], v158 offset:1024
	ds_read_b128 v[154:157], v158 offset:2048
	ds_read_b128 v[158:161], v158 offset:3072
	ds_read_b128 v[162:165], v186
	ds_read_b128 v[166:169], v186 offset:1024
	ds_read_b128 v[182:185], v186 offset:2048
	ds_read_b128 v[186:189], v186 offset:3072
	s_add_u32 s28, s28, 0x80000
	s_addc_u32 s29, s29, 0
	s_mov_b32 m0, s35
	v_lshl_add_u64 v[240:241], s[28:29], 0, v[134:135]
	ds_read_b128 v[190:193], v153 offset:32768
	ds_read_b128 v[194:197], v153 offset:33792
	ds_read_b128 v[198:201], v153 offset:34816
	ds_read_b128 v[202:205], v153 offset:35840
	ds_read_b128 v[206:209], v153 offset:36864
	ds_read_b128 v[210:213], v153 offset:37888
	ds_read_b128 v[214:217], v153 offset:38912
	ds_read_b128 v[218:221], v153 offset:39936
	global_load_lds_dwordx4 v[240:241], off
	v_lshl_add_u64 v[240:241], s[28:29], 0, v[132:133]
	s_mov_b32 m0, s36
	s_nop 0
	global_load_lds_dwordx4 v[240:241], off
	s_waitcnt vmcnt(8)
	s_waitcnt lgkmcnt(0)
	s_barrier
	s_setprio 1
	s_waitcnt lgkmcnt(0)
	v_mfma_f32_16x16x32_bf16 v[126:129], v[142:145], v[190:193], v[126:129]
	v_mfma_f32_16x16x32_bf16 v[118:121], v[154:157], v[190:193], v[118:121]
	v_mfma_f32_16x16x32_bf16 v[110:113], v[142:145], v[198:201], v[110:113]
	v_mfma_f32_16x16x32_bf16 v[102:105], v[154:157], v[198:201], v[102:105]
	v_mfma_f32_16x16x32_bf16 v[94:97], v[142:145], v[206:209], v[94:97]
	v_mfma_f32_16x16x32_bf16 v[86:89], v[154:157], v[206:209], v[86:89]
	v_mfma_f32_16x16x32_bf16 v[78:81], v[142:145], v[214:217], v[78:81]
	v_mfma_f32_16x16x32_bf16 v[70:73], v[154:157], v[214:217], v[70:73]
	v_mfma_f32_16x16x32_bf16 v[126:129], v[146:149], v[194:197], v[126:129]
	v_mfma_f32_16x16x32_bf16 v[118:121], v[158:161], v[194:197], v[118:121]
	v_mfma_f32_16x16x32_bf16 v[110:113], v[146:149], v[202:205], v[110:113]
	v_mfma_f32_16x16x32_bf16 v[102:105], v[158:161], v[202:205], v[102:105]
	v_mfma_f32_16x16x32_bf16 v[94:97], v[146:149], v[210:213], v[94:97]
	v_mfma_f32_16x16x32_bf16 v[86:89], v[158:161], v[210:213], v[86:89]
	v_mfma_f32_16x16x32_bf16 v[78:81], v[146:149], v[218:221], v[78:81]
	v_mfma_f32_16x16x32_bf16 v[70:73], v[158:161], v[218:221], v[70:73]
	s_setprio 0
	s_setprio 1
	v_mfma_f32_16x16x32_bf16 v[122:125], v[162:165], v[190:193], v[122:125]
	v_mfma_f32_16x16x32_bf16 v[114:117], v[182:185], v[190:193], v[114:117]
	v_mfma_f32_16x16x32_bf16 v[106:109], v[162:165], v[198:201], v[106:109]
	v_mfma_f32_16x16x32_bf16 v[98:101], v[182:185], v[198:201], v[98:101]
	v_mfma_f32_16x16x32_bf16 v[90:93], v[162:165], v[206:209], v[90:93]
	v_mfma_f32_16x16x32_bf16 v[82:85], v[182:185], v[206:209], v[82:85]
	v_mfma_f32_16x16x32_bf16 v[74:77], v[162:165], v[214:217], v[74:77]
	v_mfma_f32_16x16x32_bf16 v[66:69], v[182:185], v[214:217], v[66:69]
	v_mfma_f32_16x16x32_bf16 v[122:125], v[166:169], v[194:197], v[122:125]
	v_mfma_f32_16x16x32_bf16 v[114:117], v[186:189], v[194:197], v[114:117]
	v_mfma_f32_16x16x32_bf16 v[106:109], v[166:169], v[202:205], v[106:109]
	v_mfma_f32_16x16x32_bf16 v[98:101], v[186:189], v[202:205], v[98:101]
	v_mfma_f32_16x16x32_bf16 v[90:93], v[166:169], v[210:213], v[90:93]
	v_mfma_f32_16x16x32_bf16 v[82:85], v[186:189], v[210:213], v[82:85]
	v_mfma_f32_16x16x32_bf16 v[74:77], v[166:169], v[218:221], v[74:77]
	v_mfma_f32_16x16x32_bf16 v[66:69], v[186:189], v[218:221], v[66:69]
	s_setprio 0
	s_barrier
; #define PG8_STAGE(bufoff, gbase, voff) do { _Pragma("unroll") for (int _i = 0; _i < 2; ++_i) \
;         __builtin_amdgcn_global_load_lds((const unsigned*)((const char*)(gbase) + (voff)[_i]), (PG8_LAS unsigned*)(lds + (bufoff) + ldsw + _i * 8192), 16, 0, 0); } while (0)
; #define PG8_LDA(dst, b, h) do { _Pragma("unroll") for (int m = 0; m < 4; ++m) _Pragma("unroll") for (int k = 0; k < 2; ++k) dst[m][k] = *(const PG8_LAS bf16x8*)(lds + PG8_SA(b, h) + aoff + m * 2048 + k * 1024); } while (0)
; #define PG8_MMA(ai, bj, At, Bt) do { __builtin_amdgcn_s_setprio(1); _Pragma("unroll") for (int m = 0; m < 4; ++m) _Pragma("unroll") for (int n = 0; n < 2; ++n) _Pragma("unroll") for (int k = 0; k < 2; ++k) \
;         acc[ai][bj][m][n] = __builtin_amdgcn_mfma_f32_16x16x32_bf16(Bt[n][k], At[m][k], acc[ai][bj][m][n], 0, 0, 0); __builtin_amdgcn_s_setprio(0); } while (0)
; #define PG8_WAIT_V(n) asm volatile("s_waitcnt vmcnt(" #n ")" ::: "memory")
; #define PG8_WAIT_L(n) asm volatile("s_waitcnt lgkmcnt(" #n ")" ::: "memory")
; #define PG8_BAR __builtin_amdgcn_s_barrier()
; #define PG8_SCHED __builtin_amdgcn_sched_barrier(0)
; template <class Epi, class Sched, bool ALIGN_EPI = false, bool SP2 = false>
; __device__ __forceinline__ void gemm_phase(PG8_LAS unsigned char* lds, const Gemm g, const Sched& S, const Epi& E, int tid_in) {
;     ...
;         for (int t = 0; t < nt; t += 2) {
;             const bool last = (t == nt - 2);
;             const char* a1 = cA + (size_t)(t + 1) * kstep;
;             const char* a2 = last ? nA : cA + (size_t)(t + 2) * kstep; const char* b2 = last ? nB : cB + (size_t)(t + 2) * kstep;
;     ...
;             PG8_LDA(At, 1, 1); PG8_STAGE(PG8_SB(1, 0), b3, voffB); PG8_STAGE(PG8_SB(1, 1), b3 + hstep, voffB); PG8_STAGE(PG8_SA(1, 0), a3, voffA);
;             PG8_WAIT_V(8); PG8_WAIT_L(0); PG8_BAR; PG8_MMA(1, 0, At, B0); PG8_MMA(1, 1, At, B1); PG8_BAR; PG8_SCHED;
	s_add_i32 s28, s45, s31
	v_lshl_add_u64 v[222:223], v[222:223], 0, s[90:91]
	s_mov_b32 m0, s28
	ds_read_b128 v[190:193], v153 offset:49152
	ds_read_b128 v[194:197], v153 offset:50176
	ds_read_b128 v[198:201], v153 offset:51200
	ds_read_b128 v[202:205], v153 offset:52224
	ds_read_b128 v[206:209], v153 offset:53248
	ds_read_b128 v[210:213], v153 offset:54272
	ds_read_b128 v[214:217], v153 offset:55296
	ds_read_b128 v[218:221], v153 offset:56320
	global_load_lds_dwordx4 v[222:223], off
	s_add_i32 m0, s28, 0x2000
	s_add_u32 s26, s26, 0x80080
	v_lshl_add_u64 v[222:223], v[224:225], 0, s[90:91]
	s_addc_u32 s27, s27, 0
	s_add_i32 s28, s46, s31
	global_load_lds_dwordx4 v[222:223], off
	v_lshl_add_u64 v[222:223], s[26:27], 0, v[0:1]
	s_mov_b32 m0, s28
	s_nop 0
	global_load_lds_dwordx4 v[222:223], off
	v_lshl_add_u64 v[222:223], s[26:27], 0, v[130:131]
	s_add_i32 m0, s28, 0x2000
	s_nop 0
	global_load_lds_dwordx4 v[222:223], off
	v_lshl_add_u64 v[222:223], v[226:227], 0, s[90:91]
	s_mov_b32 m0, s39
	s_nop 0
	global_load_lds_dwordx4 v[222:223], off
	v_lshl_add_u64 v[222:223], v[228:229], 0, s[90:91]
	s_mov_b32 m0, s40
	s_nop 0
	global_load_lds_dwordx4 v[222:223], off
	s_add_i32 s23, s23, 2
	s_add_u32 s24, s24, 0x100
	s_addc_u32 s25, s25, 0
	s_add_u32 s15, s15, 0x100
	s_addc_u32 s17, s17, 0
	s_cmp_gt_u32 s23, 29
	s_waitcnt vmcnt(8)
	s_waitcnt lgkmcnt(0)
	s_barrier
	s_setprio 1
	s_waitcnt lgkmcnt(0)
	v_mfma_f32_16x16x32_bf16 v[62:65], v[142:145], v[190:193], v[62:65]
	v_mfma_f32_16x16x32_bf16 v[54:57], v[154:157], v[190:193], v[54:57]
	v_mfma_f32_16x16x32_bf16 v[46:49], v[142:145], v[198:201], v[46:49]
	v_mfma_f32_16x16x32_bf16 v[38:41], v[154:157], v[198:201], v[38:41]
	v_mfma_f32_16x16x32_bf16 v[30:33], v[142:145], v[206:209], v[30:33]
	v_mfma_f32_16x16x32_bf16 v[22:25], v[154:157], v[206:209], v[22:25]
	v_mfma_f32_16x16x32_bf16 v[14:17], v[142:145], v[214:217], v[14:17]
	v_mfma_f32_16x16x32_bf16 v[6:9], v[154:157], v[214:217], v[6:9]
	v_mfma_f32_16x16x32_bf16 v[62:65], v[146:149], v[194:197], v[62:65]
	v_mfma_f32_16x16x32_bf16 v[54:57], v[158:161], v[194:197], v[54:57]
	v_mfma_f32_16x16x32_bf16 v[46:49], v[146:149], v[202:205], v[46:49]
	v_mfma_f32_16x16x32_bf16 v[38:41], v[158:161], v[202:205], v[38:41]
	v_mfma_f32_16x16x32_bf16 v[30:33], v[146:149], v[210:213], v[30:33]
	v_mfma_f32_16x16x32_bf16 v[22:25], v[158:161], v[210:213], v[22:25]
	v_mfma_f32_16x16x32_bf16 v[14:17], v[146:149], v[218:221], v[14:17]
	v_mfma_f32_16x16x32_bf16 v[6:9], v[158:161], v[218:221], v[6:9]
	s_setprio 0
	s_setprio 1
	v_mfma_f32_16x16x32_bf16 v[58:61], v[162:165], v[190:193], v[58:61]
	v_mfma_f32_16x16x32_bf16 v[50:53], v[182:185], v[190:193], v[50:53]
	v_mfma_f32_16x16x32_bf16 v[42:45], v[162:165], v[198:201], v[42:45]
	v_mfma_f32_16x16x32_bf16 v[34:37], v[182:185], v[198:201], v[34:37]
	v_mfma_f32_16x16x32_bf16 v[26:29], v[162:165], v[206:209], v[26:29]
	v_mfma_f32_16x16x32_bf16 v[18:21], v[182:185], v[206:209], v[18:21]
	v_mfma_f32_16x16x32_bf16 v[10:13], v[162:165], v[214:217], v[10:13]
	v_mfma_f32_16x16x32_bf16 v[2:5], v[182:185], v[214:217], v[2:5]
	v_mfma_f32_16x16x32_bf16 v[58:61], v[166:169], v[194:197], v[58:61]
	v_mfma_f32_16x16x32_bf16 v[50:53], v[186:189], v[194:197], v[50:53]
	v_mfma_f32_16x16x32_bf16 v[42:45], v[166:169], v[202:205], v[42:45]
	v_mfma_f32_16x16x32_bf16 v[34:37], v[186:189], v[202:205], v[34:37]
	v_mfma_f32_16x16x32_bf16 v[26:29], v[166:169], v[210:213], v[26:29]
	v_mfma_f32_16x16x32_bf16 v[18:21], v[186:189], v[210:213], v[18:21]
	v_mfma_f32_16x16x32_bf16 v[10:13], v[166:169], v[218:221], v[10:13]
	v_mfma_f32_16x16x32_bf16 v[2:5], v[186:189], v[218:221], v[2:5]
	s_setprio 0
	s_barrier
	s_cbranch_scc0 .LBB0_282
	s_and_b64 vcc, exec, s[12:13]
	s_cbranch_vccz .LBB0_285
	s_barrier

; #define PG8_STAGE(bufoff, gbase, voff) do { _Pragma("unroll") for (int _i = 0; _i < 2; ++_i) \
;         __builtin_amdgcn_global_load_lds((const unsigned*)((const char*)(gbase) + (voff)[_i]), (PG8_LAS unsigned*)(lds + (bufoff) + ldsw + _i * 8192), 16, 0, 0); } while (0)
; #define PG8_LDA(dst, b, h) do { _Pragma("unroll") for (int m = 0; m < 4; ++m) _Pragma("unroll") for (int k = 0; k < 2; ++k) dst[m][k] = *(const PG8_LAS bf16x8*)(lds + PG8_SA(b, h) + aoff + m * 2048 + k * 1024); } while (0)
; #define PG8_LDB(dst, b, h) do { _Pragma("unroll") for (int n = 0; n < 2; ++n) _Pragma("unroll") for (int k = 0; k < 2; ++k) dst[n][k] = *(const PG8_LAS bf16x8*)(lds + PG8_SB(b, h) + boff + n * 2048 + k * 1024); } while (0)
; #define PG8_MMA(ai, bj, At, Bt) do { __builtin_amdgcn_s_setprio(1); _Pragma("unroll") for (int m = 0; m < 4; ++m) _Pragma("unroll") for (int n = 0; n < 2; ++n) _Pragma("unroll") for (int k = 0; k < 2; ++k) \
;         acc[ai][bj][m][n] = __builtin_amdgcn_mfma_f32_16x16x32_bf16(Bt[n][k], At[m][k], acc[ai][bj][m][n], 0, 0, 0); __builtin_amdgcn_s_setprio(0); } while (0)
; #define PG8_WAIT_V(n) asm volatile("s_waitcnt vmcnt(" #n ")" ::: "memory")
; #define PG8_WAIT_L(n) asm volatile("s_waitcnt lgkmcnt(" #n ")" ::: "memory")
; #define PG8_BAR __builtin_amdgcn_s_barrier()
; #define PG8_SCHED __builtin_amdgcn_sched_barrier(0)
; template <class Epi, class Sched, bool ALIGN_EPI = false, bool SP2 = false>
; __device__ __forceinline__ void gemm_phase(PG8_LAS unsigned char* lds, const Gemm g, const Sched& S, const Epi& E, int tid_in) {
;     ...
;         for (int t = 0; t < nt; t += 2) {
;             const bool last = (t == nt - 2);
;             const char* a1 = cA + (size_t)(t + 1) * kstep;
;             const char* a2 = last ? nA : cA + (size_t)(t + 2) * kstep; const char* b2 = last ? nB : cB + (size_t)(t + 2) * kstep;
;             const char* a3 = a2 + kstep; const char* b3 = b2 + kstep;
;             if (last && has_next) S.a_ready(nxt);
;             if constexpr (SP2) {
;             PG8_LDB(B0, 0, 0); PG8_LDB(B1, 0, 1); PG8_SCHED; PG8_LDA(At, 0, 0); PG8_STAGE(PG8_SA(1, 1), a1 + hstepA, voffA);
;             PG8_WAIT_V(8); PG8_WAIT_L(0); PG8_BAR; PG8_MMA(0, 0, At, B0); PG8_MMA(0, 1, At, B1); PG8_BAR; PG8_SCHED;
;             PG8_LDA(At, 0, 1); PG8_STAGE(PG8_SB(0, 0), b2, voffB); PG8_STAGE(PG8_SB(0, 1), b2 + hstep, voffB); PG8_STAGE(PG8_SA(0, 0), a2, voffA);
.LBB0_352:
	s_add_i32 s82, s28, 2
	s_add_u32 s26, s8, 0x100
	s_addc_u32 s27, s9, 0
	s_add_i32 s4, 0, 0x10000
	s_cmp_eq_u32 s70, s28
	s_cselect_b32 s31, s46, s27
	s_cselect_b32 s30, s47, s26
	s_cselect_b32 s29, s67, s79
	s_cselect_b32 s28, s68, s76
	s_add_i32 s5, 0, 0x14000
	v_add_u32_e32 v152, s4, v146
	v_add_u32_e32 v168, s5, v146
	ds_read_b128 v[136:139], v152
	ds_read_b128 v[140:143], v152 offset:1024
	ds_read_b128 v[148:151], v152 offset:2048
	ds_read_b128 v[152:155], v152 offset:3072
	ds_read_b128 v[156:159], v168
	ds_read_b128 v[160:163], v168 offset:1024
	ds_read_b128 v[164:167], v168 offset:2048
	ds_read_b128 v[182:185], v168 offset:3072
	v_lshl_add_u64 v[168:169], s[8:9], 0, v[132:133]
	s_add_i32 m0, s34, 0xc000
	ds_read_b128 v[186:189], v147
	ds_read_b128 v[190:193], v147 offset:1024
	ds_read_b128 v[194:197], v147 offset:2048
	ds_read_b128 v[198:201], v147 offset:3072
	ds_read_b128 v[202:205], v147 offset:4096
	ds_read_b128 v[206:209], v147 offset:5120
	ds_read_b128 v[210:213], v147 offset:6144
	ds_read_b128 v[214:217], v147 offset:7168
	global_load_lds_dwordx4 v[168:169], off
	v_lshl_add_u64 v[168:169], s[8:9], 0, v[134:135]
	s_add_i32 m0, s34, 0xe000
	s_nop 0
	global_load_lds_dwordx4 v[168:169], off
	s_waitcnt vmcnt(8)
	s_waitcnt lgkmcnt(0)
	s_barrier
	s_setprio 1
	s_waitcnt lgkmcnt(0)
	v_mfma_f32_16x16x32_bf16 v[126:129], v[136:139], v[186:189], v[126:129]
	v_mfma_f32_16x16x32_bf16 v[122:125], v[148:151], v[186:189], v[122:125]
	v_mfma_f32_16x16x32_bf16 v[118:121], v[136:139], v[194:197], v[118:121]
	v_mfma_f32_16x16x32_bf16 v[114:117], v[148:151], v[194:197], v[114:117]
	v_mfma_f32_16x16x32_bf16 v[110:113], v[136:139], v[202:205], v[110:113]
	v_mfma_f32_16x16x32_bf16 v[106:109], v[148:151], v[202:205], v[106:109]
	v_mfma_f32_16x16x32_bf16 v[102:105], v[136:139], v[210:213], v[102:105]
	v_mfma_f32_16x16x32_bf16 v[98:101], v[148:151], v[210:213], v[98:101]
	v_mfma_f32_16x16x32_bf16 v[126:129], v[140:143], v[190:193], v[126:129]
	v_mfma_f32_16x16x32_bf16 v[122:125], v[152:155], v[190:193], v[122:125]
	v_mfma_f32_16x16x32_bf16 v[118:121], v[140:143], v[198:201], v[118:121]
	v_mfma_f32_16x16x32_bf16 v[114:117], v[152:155], v[198:201], v[114:117]
	v_mfma_f32_16x16x32_bf16 v[110:113], v[140:143], v[206:209], v[110:113]
	v_mfma_f32_16x16x32_bf16 v[106:109], v[152:155], v[206:209], v[106:109]
	v_mfma_f32_16x16x32_bf16 v[102:105], v[140:143], v[214:217], v[102:105]
	v_mfma_f32_16x16x32_bf16 v[98:101], v[152:155], v[214:217], v[98:101]
	s_setprio 0
	s_setprio 1
	v_mfma_f32_16x16x32_bf16 v[94:97], v[156:159], v[186:189], v[94:97]
	v_mfma_f32_16x16x32_bf16 v[90:93], v[164:167], v[186:189], v[90:93]
	v_mfma_f32_16x16x32_bf16 v[86:89], v[156:159], v[194:197], v[86:89]
	v_mfma_f32_16x16x32_bf16 v[82:85], v[164:167], v[194:197], v[82:85]
	v_mfma_f32_16x16x32_bf16 v[78:81], v[156:159], v[202:205], v[78:81]
	v_mfma_f32_16x16x32_bf16 v[74:77], v[164:167], v[202:205], v[74:77]
	v_mfma_f32_16x16x32_bf16 v[70:73], v[156:159], v[210:213], v[70:73]
	v_mfma_f32_16x16x32_bf16 v[66:69], v[164:167], v[210:213], v[66:69]
	v_mfma_f32_16x16x32_bf16 v[94:97], v[160:163], v[190:193], v[94:97]
	v_mfma_f32_16x16x32_bf16 v[90:93], v[182:185], v[190:193], v[90:93]
	v_mfma_f32_16x16x32_bf16 v[86:89], v[160:163], v[198:201], v[86:89]
	v_mfma_f32_16x16x32_bf16 v[82:85], v[182:185], v[198:201], v[82:85]
	v_mfma_f32_16x16x32_bf16 v[78:81], v[160:163], v[206:209], v[78:81]
	v_mfma_f32_16x16x32_bf16 v[74:77], v[182:185], v[206:209], v[74:77]
	v_mfma_f32_16x16x32_bf16 v[70:73], v[160:163], v[214:217], v[70:73]
	v_mfma_f32_16x16x32_bf16 v[66:69], v[182:185], v[214:217], v[66:69]
	s_setprio 0
	s_barrier
	s_add_i32 s8, s4, s33
	v_lshl_add_u64 v[168:169], s[28:29], 0, v[0:1]
	s_mov_b32 m0, s8
	ds_read_b128 v[186:189], v147 offset:16384
	ds_read_b128 v[190:193], v147 offset:17408
	ds_read_b128 v[194:197], v147 offset:18432
	ds_read_b128 v[198:201], v147 offset:19456
	ds_read_b128 v[202:205], v147 offset:20480
	ds_read_b128 v[206:209], v147 offset:21504
	ds_read_b128 v[210:213], v147 offset:22528
	ds_read_b128 v[214:217], v147 offset:23552
	global_load_lds_dwordx4 v[168:169], off
	s_add_i32 m0, s8, 0x2000
	s_add_u32 s8, s28, 0x160000
	v_lshl_add_u64 v[218:219], s[28:29], 0, v[130:131]
	s_addc_u32 s9, s29, 0
	s_add_i32 s55, s5, s33
	global_load_lds_dwordx4 v[218:219], off
	v_lshl_add_u64 v[220:221], s[8:9], 0, v[0:1]
	s_mov_b32 m0, s55
	v_lshl_add_u64 v[222:223], s[30:31], 0, v[130:131]
	global_load_lds_dwordx4 v[220:221], off
	v_lshl_add_u64 v[220:221], s[8:9], 0, v[130:131]
	s_add_i32 m0, s55, 0x2000
	s_nop 0
	global_load_lds_dwordx4 v[220:221], off
	s_waitcnt vmcnt(6)
	s_waitcnt lgkmcnt(0)
	s_barrier
; #define PG8_STAGE(bufoff, gbase, voff) do { _Pragma("unroll") for (int _i = 0; _i < 2; ++_i) \
;         __builtin_amdgcn_global_load_lds((const unsigned*)((const char*)(gbase) + (voff)[_i]), (PG8_LAS unsigned*)(lds + (bufoff) + ldsw + _i * 8192), 16, 0, 0); } while (0)
; #define PG8_LDA(dst, b, h) do { _Pragma("unroll") for (int m = 0; m < 4; ++m) _Pragma("unroll") for (int k = 0; k < 2; ++k) dst[m][k] = *(const PG8_LAS bf16x8*)(lds + PG8_SA(b, h) + aoff + m * 2048 + k * 1024); } while (0)
; #define PG8_LDB(dst, b, h) do { _Pragma("unroll") for (int n = 0; n < 2; ++n) _Pragma("unroll") for (int k = 0; k < 2; ++k) dst[n][k] = *(const PG8_LAS bf16x8*)(lds + PG8_SB(b, h) + boff + n * 2048 + k * 1024); } while (0)
; #define PG8_MMA(ai, bj, At, Bt) do { __builtin_amdgcn_s_setprio(1); _Pragma("unroll") for (int m = 0; m < 4; ++m) _Pragma("unroll") for (int n = 0; n < 2; ++n) _Pragma("unroll") for (int k = 0; k < 2; ++k) \
;         acc[ai][bj][m][n] = __builtin_amdgcn_mfma_f32_16x16x32_bf16(Bt[n][k], At[m][k], acc[ai][bj][m][n], 0, 0, 0); __builtin_amdgcn_s_setprio(0); } while (0)
; #define PG8_WAIT_V(n) asm volatile("s_waitcnt vmcnt(" #n ")" ::: "memory")
; #define PG8_WAIT_L(n) asm volatile("s_waitcnt lgkmcnt(" #n ")" ::: "memory")
; #define PG8_BAR __builtin_amdgcn_s_barrier()
; #define PG8_SCHED __builtin_amdgcn_sched_barrier(0)
; template <class Epi, class Sched, bool ALIGN_EPI = false, bool SP2 = false>
; __device__ __forceinline__ void gemm_phase(PG8_LAS unsigned char* lds, const Gemm g, const Sched& S, const Epi& E, int tid_in) {
;     ...
;             PG8_LDA(At, 0, 1); PG8_STAGE(PG8_SB(0, 0), b2, voffB); PG8_STAGE(PG8_SB(0, 1), b2 + hstep, voffB); PG8_STAGE(PG8_SA(0, 0), a2, voffA);
;             PG8_WAIT_V(8); PG8_WAIT_L(0); PG8_BAR; PG8_MMA(1, 0, At, B0); PG8_MMA(1, 1, At, B1); PG8_BAR; PG8_SCHED;
;             PG8_LDB(B0, 1, 0); PG8_LDB(B1, 1, 1); PG8_SCHED; PG8_LDA(At, 1, 0); PG8_STAGE(PG8_SA(0, 1), a2 + hstepA, voffA);
;             PG8_WAIT_V(8); PG8_WAIT_L(0); PG8_BAR; PG8_MMA(0, 0, At, B0); PG8_MMA(0, 1, At, B1); PG8_BAR; PG8_SCHED;
	s_setprio 1
	s_waitcnt lgkmcnt(0)
	v_mfma_f32_16x16x32_bf16 v[62:65], v[136:139], v[186:189], v[62:65]
	v_mfma_f32_16x16x32_bf16 v[58:61], v[148:151], v[186:189], v[58:61]
	v_mfma_f32_16x16x32_bf16 v[54:57], v[136:139], v[194:197], v[54:57]
	v_mfma_f32_16x16x32_bf16 v[50:53], v[148:151], v[194:197], v[50:53]
	v_mfma_f32_16x16x32_bf16 v[46:49], v[136:139], v[202:205], v[46:49]
	v_mfma_f32_16x16x32_bf16 v[42:45], v[148:151], v[202:205], v[42:45]
	v_mfma_f32_16x16x32_bf16 v[38:41], v[136:139], v[210:213], v[38:41]
	v_mfma_f32_16x16x32_bf16 v[34:37], v[148:151], v[210:213], v[34:37]
	v_mfma_f32_16x16x32_bf16 v[62:65], v[140:143], v[190:193], v[62:65]
	v_mfma_f32_16x16x32_bf16 v[58:61], v[152:155], v[190:193], v[58:61]
	v_mfma_f32_16x16x32_bf16 v[54:57], v[140:143], v[198:201], v[54:57]
	v_mfma_f32_16x16x32_bf16 v[50:53], v[152:155], v[198:201], v[50:53]
	v_mfma_f32_16x16x32_bf16 v[46:49], v[140:143], v[206:209], v[46:49]
	v_mfma_f32_16x16x32_bf16 v[42:45], v[152:155], v[206:209], v[42:45]
	v_mfma_f32_16x16x32_bf16 v[38:41], v[140:143], v[214:217], v[38:41]
	v_mfma_f32_16x16x32_bf16 v[34:37], v[152:155], v[214:217], v[34:37]
	s_setprio 0
	s_setprio 1
	v_mfma_f32_16x16x32_bf16 v[30:33], v[156:159], v[186:189], v[30:33]
	v_mfma_f32_16x16x32_bf16 v[26:29], v[164:167], v[186:189], v[26:29]
	v_mfma_f32_16x16x32_bf16 v[22:25], v[156:159], v[194:197], v[22:25]
	v_mfma_f32_16x16x32_bf16 v[18:21], v[164:167], v[194:197], v[18:21]
	v_mfma_f32_16x16x32_bf16 v[14:17], v[156:159], v[202:205], v[14:17]
	v_mfma_f32_16x16x32_bf16 v[10:13], v[164:167], v[202:205], v[10:13]
	v_mfma_f32_16x16x32_bf16 v[6:9], v[156:159], v[210:213], v[6:9]
	v_mfma_f32_16x16x32_bf16 v[2:5], v[164:167], v[210:213], v[2:5]
	v_mfma_f32_16x16x32_bf16 v[30:33], v[160:163], v[190:193], v[30:33]
	v_mfma_f32_16x16x32_bf16 v[26:29], v[182:185], v[190:193], v[26:29]
	v_mfma_f32_16x16x32_bf16 v[22:25], v[160:163], v[198:201], v[22:25]
	v_mfma_f32_16x16x32_bf16 v[18:21], v[182:185], v[198:201], v[18:21]
	v_mfma_f32_16x16x32_bf16 v[14:17], v[160:163], v[206:209], v[14:17]
	v_mfma_f32_16x16x32_bf16 v[10:13], v[182:185], v[206:209], v[10:13]
	v_mfma_f32_16x16x32_bf16 v[6:9], v[160:163], v[214:217], v[6:9]
	v_mfma_f32_16x16x32_bf16 v[2:5], v[182:185], v[214:217], v[2:5]
	s_setprio 0
	s_barrier
	v_lshl_add_u64 v[220:221], s[30:31], 0, v[0:1]
	s_mov_b32 m0, s34
	s_nop 0
	global_load_lds_dwordx4 v[220:221], off
	s_mov_b32 m0, s35
	s_nop 0
	global_load_lds_dwordx4 v[222:223], off
	s_add_i32 s63, 0, 0x18000
	s_add_i32 s55, 0, 0x1c000
	v_add_u32_e32 v152, s63, v146
	v_add_u32_e32 v182, s55, v146
	ds_read_b128 v[136:139], v152
	ds_read_b128 v[140:143], v152 offset:1024
	ds_read_b128 v[148:151], v152 offset:2048
	ds_read_b128 v[152:155], v152 offset:3072
	ds_read_b128 v[156:159], v182
	ds_read_b128 v[160:163], v182 offset:1024
	ds_read_b128 v[164:167], v182 offset:2048
	ds_read_b128 v[182:185], v182 offset:3072
	s_add_u32 s8, s30, 0x160000
	s_addc_u32 s9, s31, 0
	s_mov_b32 m0, s36
	v_lshl_add_u64 v[224:225], s[8:9], 0, v[0:1]
	ds_read_b128 v[186:189], v147 offset:32768
	ds_read_b128 v[190:193], v147 offset:33792
	ds_read_b128 v[194:197], v147 offset:34816
	ds_read_b128 v[198:201], v147 offset:35840
	ds_read_b128 v[202:205], v147 offset:36864
	ds_read_b128 v[206:209], v147 offset:37888
	ds_read_b128 v[210:213], v147 offset:38912
	ds_read_b128 v[214:217], v147 offset:39936
	global_load_lds_dwordx4 v[224:225], off
	v_lshl_add_u64 v[224:225], s[8:9], 0, v[130:131]
	s_mov_b32 m0, s37
	s_nop 0
	global_load_lds_dwordx4 v[224:225], off
	s_waitcnt vmcnt(8)
	s_waitcnt lgkmcnt(0)
	s_barrier
	s_setprio 1
	s_waitcnt lgkmcnt(0)
	v_mfma_f32_16x16x32_bf16 v[126:129], v[136:139], v[186:189], v[126:129]
	v_mfma_f32_16x16x32_bf16 v[122:125], v[148:151], v[186:189], v[122:125]
	v_mfma_f32_16x16x32_bf16 v[118:121], v[136:139], v[194:197], v[118:121]
	v_mfma_f32_16x16x32_bf16 v[114:117], v[148:151], v[194:197], v[114:117]
	v_mfma_f32_16x16x32_bf16 v[110:113], v[136:139], v[202:205], v[110:113]
	v_mfma_f32_16x16x32_bf16 v[106:109], v[148:151], v[202:205], v[106:109]
	v_mfma_f32_16x16x32_bf16 v[102:105], v[136:139], v[210:213], v[102:105]
	v_mfma_f32_16x16x32_bf16 v[98:101], v[148:151], v[210:213], v[98:101]
	v_mfma_f32_16x16x32_bf16 v[126:129], v[140:143], v[190:193], v[126:129]
	v_mfma_f32_16x16x32_bf16 v[122:125], v[152:155], v[190:193], v[122:125]
	v_mfma_f32_16x16x32_bf16 v[118:121], v[140:143], v[198:201], v[118:121]
	v_mfma_f32_16x16x32_bf16 v[114:117], v[152:155], v[198:201], v[114:117]
	v_mfma_f32_16x16x32_bf16 v[110:113], v[140:143], v[206:209], v[110:113]
	v_mfma_f32_16x16x32_bf16 v[106:109], v[152:155], v[206:209], v[106:109]
	v_mfma_f32_16x16x32_bf16 v[102:105], v[140:143], v[214:217], v[102:105]
	v_mfma_f32_16x16x32_bf16 v[98:101], v[152:155], v[214:217], v[98:101]
	s_setprio 0
	s_setprio 1
	v_mfma_f32_16x16x32_bf16 v[94:97], v[156:159], v[186:189], v[94:97]
	v_mfma_f32_16x16x32_bf16 v[90:93], v[164:167], v[186:189], v[90:93]
	v_mfma_f32_16x16x32_bf16 v[86:89], v[156:159], v[194:197], v[86:89]
	v_mfma_f32_16x16x32_bf16 v[82:85], v[164:167], v[194:197], v[82:85]
	v_mfma_f32_16x16x32_bf16 v[78:81], v[156:159], v[202:205], v[78:81]
	v_mfma_f32_16x16x32_bf16 v[74:77], v[164:167], v[202:205], v[74:77]
	v_mfma_f32_16x16x32_bf16 v[70:73], v[156:159], v[210:213], v[70:73]
	v_mfma_f32_16x16x32_bf16 v[66:69], v[164:167], v[210:213], v[66:69]
	v_mfma_f32_16x16x32_bf16 v[94:97], v[160:163], v[190:193], v[94:97]
	v_mfma_f32_16x16x32_bf16 v[90:93], v[182:185], v[190:193], v[90:93]
	v_mfma_f32_16x16x32_bf16 v[86:89], v[160:163], v[198:201], v[86:89]
	v_mfma_f32_16x16x32_bf16 v[82:85], v[182:185], v[198:201], v[82:85]
	v_mfma_f32_16x16x32_bf16 v[78:81], v[160:163], v[206:209], v[78:81]
	v_mfma_f32_16x16x32_bf16 v[74:77], v[182:185], v[206:209], v[74:77]
	v_mfma_f32_16x16x32_bf16 v[70:73], v[160:163], v[214:217], v[70:73]
	v_mfma_f32_16x16x32_bf16 v[66:69], v[182:185], v[214:217], v[66:69]
	s_setprio 0
	s_barrier
; #define PG8_STAGE(bufoff, gbase, voff) do { _Pragma("unroll") for (int _i = 0; _i < 2; ++_i) \
;         __builtin_amdgcn_global_load_lds((const unsigned*)((const char*)(gbase) + (voff)[_i]), (PG8_LAS unsigned*)(lds + (bufoff) + ldsw + _i * 8192), 16, 0, 0); } while (0)
; #define PG8_LDA(dst, b, h) do { _Pragma("unroll") for (int m = 0; m < 4; ++m) _Pragma("unroll") for (int k = 0; k < 2; ++k) dst[m][k] = *(const PG8_LAS bf16x8*)(lds + PG8_SA(b, h) + aoff + m * 2048 + k * 1024); } while (0)
; #define PG8_MMA(ai, bj, At, Bt) do { __builtin_amdgcn_s_setprio(1); _Pragma("unroll") for (int m = 0; m < 4; ++m) _Pragma("unroll") for (int n = 0; n < 2; ++n) _Pragma("unroll") for (int k = 0; k < 2; ++k) \
;         acc[ai][bj][m][n] = __builtin_amdgcn_mfma_f32_16x16x32_bf16(Bt[n][k], At[m][k], acc[ai][bj][m][n], 0, 0, 0); __builtin_amdgcn_s_setprio(0); } while (0)
; #define PG8_WAIT_V(n) asm volatile("s_waitcnt vmcnt(" #n ")" ::: "memory")
; #define PG8_WAIT_L(n) asm volatile("s_waitcnt lgkmcnt(" #n ")" ::: "memory")
; #define PG8_BAR __builtin_amdgcn_s_barrier()
; #define PG8_SCHED __builtin_amdgcn_sched_barrier(0)
; template <class Epi, class Sched, bool ALIGN_EPI = false, bool SP2 = false>
; __device__ __forceinline__ void gemm_phase(PG8_LAS unsigned char* lds, const Gemm g, const Sched& S, const Epi& E, int tid_in) {
;     ...
;         for (int t = 0; t < nt; t += 2) {
;             const bool last = (t == nt - 2);
;             const char* a1 = cA + (size_t)(t + 1) * kstep;
;             const char* a2 = last ? nA : cA + (size_t)(t + 2) * kstep; const char* b2 = last ? nB : cB + (size_t)(t + 2) * kstep;
;     ...
;             PG8_LDA(At, 1, 1); PG8_STAGE(PG8_SB(1, 0), b3, voffB); PG8_STAGE(PG8_SB(1, 1), b3 + hstep, voffB); PG8_STAGE(PG8_SA(1, 0), a3, voffA);
;             PG8_WAIT_V(8); PG8_WAIT_L(0); PG8_BAR; PG8_MMA(1, 0, At, B0); PG8_MMA(1, 1, At, B1); PG8_BAR; PG8_SCHED;
	s_add_i32 s8, s63, s33
	v_lshl_add_u64 v[168:169], v[168:169], 0, s[90:91]
	s_mov_b32 m0, s8
	ds_read_b128 v[186:189], v147 offset:49152
	ds_read_b128 v[190:193], v147 offset:50176
	ds_read_b128 v[194:197], v147 offset:51200
	ds_read_b128 v[198:201], v147 offset:52224
	ds_read_b128 v[202:205], v147 offset:53248
	ds_read_b128 v[206:209], v147 offset:54272
	ds_read_b128 v[210:213], v147 offset:55296
	ds_read_b128 v[214:217], v147 offset:56320
	global_load_lds_dwordx4 v[168:169], off
	s_add_i32 m0, s8, 0x2000
	s_add_u32 s8, s28, 0x160080
	v_lshl_add_u64 v[168:169], v[218:219], 0, s[90:91]
	s_addc_u32 s9, s29, 0
	s_add_i32 s28, s55, s33
	global_load_lds_dwordx4 v[168:169], off
	v_lshl_add_u64 v[168:169], s[8:9], 0, v[0:1]
	s_mov_b32 m0, s28
	s_nop 0
	global_load_lds_dwordx4 v[168:169], off
	v_lshl_add_u64 v[168:169], s[8:9], 0, v[130:131]
	s_add_i32 m0, s28, 0x2000
	s_nop 0
	global_load_lds_dwordx4 v[168:169], off
	v_lshl_add_u64 v[168:169], v[220:221], 0, s[90:91]
	s_mov_b32 m0, s43
	s_nop 0
	global_load_lds_dwordx4 v[168:169], off
	v_lshl_add_u64 v[168:169], v[222:223], 0, s[90:91]
	s_mov_b32 m0, s44
	s_nop 0
	global_load_lds_dwordx4 v[168:169], off
	s_add_u32 s76, s76, 0x100
	s_addc_u32 s79, s79, 0
	s_cmp_ge_u32 s82, s66
	s_mov_b64 s[8:9], s[26:27]
	s_mov_b32 s28, s82
	s_waitcnt vmcnt(8)
	s_waitcnt lgkmcnt(0)
	s_barrier
	s_setprio 1
	s_waitcnt lgkmcnt(0)
	v_mfma_f32_16x16x32_bf16 v[62:65], v[136:139], v[186:189], v[62:65]
	v_mfma_f32_16x16x32_bf16 v[58:61], v[148:151], v[186:189], v[58:61]
	v_mfma_f32_16x16x32_bf16 v[54:57], v[136:139], v[194:197], v[54:57]
	v_mfma_f32_16x16x32_bf16 v[50:53], v[148:151], v[194:197], v[50:53]
	v_mfma_f32_16x16x32_bf16 v[46:49], v[136:139], v[202:205], v[46:49]
	v_mfma_f32_16x16x32_bf16 v[42:45], v[148:151], v[202:205], v[42:45]
	v_mfma_f32_16x16x32_bf16 v[38:41], v[136:139], v[210:213], v[38:41]
	v_mfma_f32_16x16x32_bf16 v[34:37], v[148:151], v[210:213], v[34:37]
	v_mfma_f32_16x16x32_bf16 v[62:65], v[140:143], v[190:193], v[62:65]
	v_mfma_f32_16x16x32_bf16 v[58:61], v[152:155], v[190:193], v[58:61]
	v_mfma_f32_16x16x32_bf16 v[54:57], v[140:143], v[198:201], v[54:57]
	v_mfma_f32_16x16x32_bf16 v[50:53], v[152:155], v[198:201], v[50:53]
	v_mfma_f32_16x16x32_bf16 v[46:49], v[140:143], v[206:209], v[46:49]
	v_mfma_f32_16x16x32_bf16 v[42:45], v[152:155], v[206:209], v[42:45]
	v_mfma_f32_16x16x32_bf16 v[38:41], v[140:143], v[214:217], v[38:41]
	v_mfma_f32_16x16x32_bf16 v[34:37], v[152:155], v[214:217], v[34:37]
	s_setprio 0
	s_setprio 1
	v_mfma_f32_16x16x32_bf16 v[30:33], v[156:159], v[186:189], v[30:33]
	v_mfma_f32_16x16x32_bf16 v[26:29], v[164:167], v[186:189], v[26:29]
	v_mfma_f32_16x16x32_bf16 v[22:25], v[156:159], v[194:197], v[22:25]
	v_mfma_f32_16x16x32_bf16 v[18:21], v[164:167], v[194:197], v[18:21]
	v_mfma_f32_16x16x32_bf16 v[14:17], v[156:159], v[202:205], v[14:17]
	v_mfma_f32_16x16x32_bf16 v[10:13], v[164:167], v[202:205], v[10:13]
	v_mfma_f32_16x16x32_bf16 v[6:9], v[156:159], v[210:213], v[6:9]
	v_mfma_f32_16x16x32_bf16 v[2:5], v[164:167], v[210:213], v[2:5]
	v_mfma_f32_16x16x32_bf16 v[30:33], v[160:163], v[190:193], v[30:33]
	v_mfma_f32_16x16x32_bf16 v[26:29], v[182:185], v[190:193], v[26:29]
	v_mfma_f32_16x16x32_bf16 v[22:25], v[160:163], v[198:201], v[22:25]
	v_mfma_f32_16x16x32_bf16 v[18:21], v[182:185], v[198:201], v[18:21]
	v_mfma_f32_16x16x32_bf16 v[14:17], v[160:163], v[206:209], v[14:17]
	v_mfma_f32_16x16x32_bf16 v[10:13], v[182:185], v[206:209], v[10:13]
	v_mfma_f32_16x16x32_bf16 v[6:9], v[160:163], v[214:217], v[6:9]
	v_mfma_f32_16x16x32_bf16 v[2:5], v[182:185], v[214:217], v[2:5]
	s_setprio 0
	s_barrier
	s_cbranch_scc0 .LBB0_352
	s_and_b64 vcc, exec, s[18:19]
	s_cbranch_vccz .LBB0_355
	s_barrier

; #define PG8_STAGE(bufoff, gbase, voff) do { _Pragma("unroll") for (int _i = 0; _i < 2; ++_i) \
;         __builtin_amdgcn_global_load_lds((const unsigned*)((const char*)(gbase) + (voff)[_i]), (PG8_LAS unsigned*)(lds + (bufoff) + ldsw + _i * 8192), 16, 0, 0); } while (0)
; #define PG8_LDA(dst, b, h) do { _Pragma("unroll") for (int m = 0; m < 4; ++m) _Pragma("unroll") for (int k = 0; k < 2; ++k) dst[m][k] = *(const PG8_LAS bf16x8*)(lds + PG8_SA(b, h) + aoff + m * 2048 + k * 1024); } while (0)
; #define PG8_LDB(dst, b, h) do { _Pragma("unroll") for (int n = 0; n < 2; ++n) _Pragma("unroll") for (int k = 0; k < 2; ++k) dst[n][k] = *(const PG8_LAS bf16x8*)(lds + PG8_SB(b, h) + boff + n * 2048 + k * 1024); } while (0)
; #define PG8_MMA(ai, bj, At, Bt) do { __builtin_amdgcn_s_setprio(1); _Pragma("unroll") for (int m = 0; m < 4; ++m) _Pragma("unroll") for (int n = 0; n < 2; ++n) _Pragma("unroll") for (int k = 0; k < 2; ++k) \
;         acc[ai][bj][m][n] = __builtin_amdgcn_mfma_f32_16x16x32_bf16(Bt[n][k], At[m][k], acc[ai][bj][m][n], 0, 0, 0); __builtin_amdgcn_s_setprio(0); } while (0)
; #define PG8_WAIT_V(n) asm volatile("s_waitcnt vmcnt(" #n ")" ::: "memory")
; #define PG8_WAIT_L(n) asm volatile("s_waitcnt lgkmcnt(" #n ")" ::: "memory")
; #define PG8_BAR __builtin_amdgcn_s_barrier()
; #define PG8_SCHED __builtin_amdgcn_sched_barrier(0)
; template <class Epi, class Sched, bool ALIGN_EPI = false, bool SP2 = false>
; __device__ __forceinline__ void gemm_phase(PG8_LAS unsigned char* lds, const Gemm g, const Sched& S, const Epi& E, int tid_in) {
;     ...
;         for (int t = 0; t < nt; t += 2) {
;             const bool last = (t == nt - 2);
;             const char* a1 = cA + (size_t)(t + 1) * kstep;
;             const char* a2 = last ? nA : cA + (size_t)(t + 2) * kstep; const char* b2 = last ? nB : cB + (size_t)(t + 2) * kstep;
;             const char* a3 = a2 + kstep; const char* b3 = b2 + kstep;
;             if (last && has_next) S.a_ready(nxt);
;             if constexpr (SP2) {
;             PG8_LDB(B0, 0, 0); PG8_LDB(B1, 0, 1); PG8_SCHED; PG8_LDA(At, 0, 0); PG8_STAGE(PG8_SA(1, 1), a1 + hstepA, voffA);
;             PG8_WAIT_V(8); PG8_WAIT_L(0); PG8_BAR; PG8_MMA(0, 0, At, B0); PG8_MMA(0, 1, At, B1); PG8_BAR; PG8_SCHED;
;             PG8_LDA(At, 0, 1); PG8_STAGE(PG8_SB(0, 0), b2, voffB); PG8_STAGE(PG8_SB(0, 1), b2 + hstep, voffB); PG8_STAGE(PG8_SA(0, 0), a2, voffA);
.LBB0_513:
	v_add_u32_e32 v150, s4, v157
	ds_read_b128 v[142:145], v150
	ds_read_b128 v[146:149], v150 offset:1024
	ds_read_b128 v[152:155], v150 offset:2048
	ds_read_b128 v[160:163], v150 offset:3072
	v_add_u32_e32 v150, s5, v157
	ds_read_b128 v[164:167], v150
	ds_read_b128 v[182:185], v150 offset:1024
	ds_read_b128 v[186:189], v150 offset:2048
	ds_read_b128 v[190:193], v150 offset:3072
	s_add_u32 s28, s14, 0xfff80080
	s_addc_u32 s29, s15, -1
	s_cmp_eq_u32 s23, 28
	s_cselect_b32 s31, s25, s29
	s_cselect_b32 s30, s24, s28
	s_cselect_b32 s29, s27, s21
	s_cselect_b32 s28, s26, s13
	v_lshl_add_u64 v[168:169], s[14:15], 0, v[138:139]
	s_add_i32 m0, s38, 0xc000
	ds_read_b128 v[194:197], v158
	ds_read_b128 v[198:201], v158 offset:1024
	ds_read_b128 v[202:205], v158 offset:2048
	ds_read_b128 v[206:209], v158 offset:3072
	ds_read_b128 v[210:213], v158 offset:4096
	ds_read_b128 v[214:217], v158 offset:5120
	ds_read_b128 v[218:221], v158 offset:6144
	ds_read_b128 v[222:225], v158 offset:7168
	global_load_lds_dwordx4 v[168:169], off
	v_lshl_add_u64 v[168:169], s[14:15], 0, v[140:141]
	s_add_i32 m0, s38, 0xe000
	s_nop 0
	global_load_lds_dwordx4 v[168:169], off
	s_waitcnt vmcnt(8)
	s_waitcnt lgkmcnt(0)
	s_barrier
	s_setprio 1
	s_waitcnt lgkmcnt(0)
	v_mfma_f32_16x16x32_bf16 v[126:129], v[142:145], v[194:197], v[126:129]
	v_mfma_f32_16x16x32_bf16 v[122:125], v[152:155], v[194:197], v[122:125]
	v_mfma_f32_16x16x32_bf16 v[110:113], v[142:145], v[202:205], v[110:113]
	v_mfma_f32_16x16x32_bf16 v[106:109], v[152:155], v[202:205], v[106:109]
	v_mfma_f32_16x16x32_bf16 v[94:97], v[142:145], v[210:213], v[94:97]
	v_mfma_f32_16x16x32_bf16 v[90:93], v[152:155], v[210:213], v[90:93]
	v_mfma_f32_16x16x32_bf16 v[78:81], v[142:145], v[218:221], v[78:81]
	v_mfma_f32_16x16x32_bf16 v[74:77], v[152:155], v[218:221], v[74:77]
	v_mfma_f32_16x16x32_bf16 v[126:129], v[146:149], v[198:201], v[126:129]
	v_mfma_f32_16x16x32_bf16 v[122:125], v[160:163], v[198:201], v[122:125]
	v_mfma_f32_16x16x32_bf16 v[110:113], v[146:149], v[206:209], v[110:113]
	v_mfma_f32_16x16x32_bf16 v[106:109], v[160:163], v[206:209], v[106:109]
	v_mfma_f32_16x16x32_bf16 v[94:97], v[146:149], v[214:217], v[94:97]
	v_mfma_f32_16x16x32_bf16 v[90:93], v[160:163], v[214:217], v[90:93]
	v_mfma_f32_16x16x32_bf16 v[78:81], v[146:149], v[222:225], v[78:81]
	v_mfma_f32_16x16x32_bf16 v[74:77], v[160:163], v[222:225], v[74:77]
	s_setprio 0
	s_setprio 1
	v_mfma_f32_16x16x32_bf16 v[118:121], v[164:167], v[194:197], v[118:121]
	v_mfma_f32_16x16x32_bf16 v[114:117], v[186:189], v[194:197], v[114:117]
	v_mfma_f32_16x16x32_bf16 v[102:105], v[164:167], v[202:205], v[102:105]
	v_mfma_f32_16x16x32_bf16 v[98:101], v[186:189], v[202:205], v[98:101]
	v_mfma_f32_16x16x32_bf16 v[86:89], v[164:167], v[210:213], v[86:89]
	v_mfma_f32_16x16x32_bf16 v[82:85], v[186:189], v[210:213], v[82:85]
	v_mfma_f32_16x16x32_bf16 v[70:73], v[164:167], v[218:221], v[70:73]
	v_mfma_f32_16x16x32_bf16 v[66:69], v[186:189], v[218:221], v[66:69]
	v_mfma_f32_16x16x32_bf16 v[118:121], v[182:185], v[198:201], v[118:121]
	v_mfma_f32_16x16x32_bf16 v[114:117], v[190:193], v[198:201], v[114:117]
	v_mfma_f32_16x16x32_bf16 v[102:105], v[182:185], v[206:209], v[102:105]
	v_mfma_f32_16x16x32_bf16 v[98:101], v[190:193], v[206:209], v[98:101]
	v_mfma_f32_16x16x32_bf16 v[86:89], v[182:185], v[214:217], v[86:89]
	v_mfma_f32_16x16x32_bf16 v[82:85], v[190:193], v[214:217], v[82:85]
	v_mfma_f32_16x16x32_bf16 v[70:73], v[182:185], v[222:225], v[70:73]
	v_mfma_f32_16x16x32_bf16 v[66:69], v[190:193], v[222:225], v[66:69]
	s_setprio 0
	s_barrier
	s_add_i32 s46, s4, s37
	v_lshl_add_u64 v[168:169], s[28:29], 0, v[0:1]
	s_mov_b32 m0, s46
	ds_read_b128 v[194:197], v158 offset:16384
	ds_read_b128 v[198:201], v158 offset:17408
	ds_read_b128 v[202:205], v158 offset:18432
	ds_read_b128 v[206:209], v158 offset:19456
	ds_read_b128 v[210:213], v158 offset:20480
	ds_read_b128 v[214:217], v158 offset:21504
	ds_read_b128 v[218:221], v158 offset:22528
	ds_read_b128 v[222:225], v158 offset:23552
	global_load_lds_dwordx4 v[168:169], off
	s_add_i32 m0, s46, 0x2000
	s_add_u32 s46, s28, 0x80000
	v_lshl_add_u64 v[226:227], s[28:29], 0, v[134:135]
	s_addc_u32 s47, s29, 0
	s_add_i32 s64, s5, s37
	global_load_lds_dwordx4 v[226:227], off
	v_lshl_add_u64 v[228:229], s[46:47], 0, v[0:1]
	s_mov_b32 m0, s64
	v_lshl_add_u64 v[240:241], s[30:31], 0, v[132:133]
	global_load_lds_dwordx4 v[228:229], off
	v_lshl_add_u64 v[228:229], s[46:47], 0, v[134:135]
	s_add_i32 m0, s64, 0x2000
	s_nop 0
	global_load_lds_dwordx4 v[228:229], off
	s_waitcnt vmcnt(6)
	s_waitcnt lgkmcnt(0)
	s_barrier
; #define PG8_STAGE(bufoff, gbase, voff) do { _Pragma("unroll") for (int _i = 0; _i < 2; ++_i) \
;         __builtin_amdgcn_global_load_lds((const unsigned*)((const char*)(gbase) + (voff)[_i]), (PG8_LAS unsigned*)(lds + (bufoff) + ldsw + _i * 8192), 16, 0, 0); } while (0)
; #define PG8_LDA(dst, b, h) do { _Pragma("unroll") for (int m = 0; m < 4; ++m) _Pragma("unroll") for (int k = 0; k < 2; ++k) dst[m][k] = *(const PG8_LAS bf16x8*)(lds + PG8_SA(b, h) + aoff + m * 2048 + k * 1024); } while (0)
; #define PG8_LDB(dst, b, h) do { _Pragma("unroll") for (int n = 0; n < 2; ++n) _Pragma("unroll") for (int k = 0; k < 2; ++k) dst[n][k] = *(const PG8_LAS bf16x8*)(lds + PG8_SB(b, h) + boff + n * 2048 + k * 1024); } while (0)
; #define PG8_MMA(ai, bj, At, Bt) do { __builtin_amdgcn_s_setprio(1); _Pragma("unroll") for (int m = 0; m < 4; ++m) _Pragma("unroll") for (int n = 0; n < 2; ++n) _Pragma("unroll") for (int k = 0; k < 2; ++k) \
;         acc[ai][bj][m][n] = __builtin_amdgcn_mfma_f32_16x16x32_bf16(Bt[n][k], At[m][k], acc[ai][bj][m][n], 0, 0, 0); __builtin_amdgcn_s_setprio(0); } while (0)
; #define PG8_WAIT_V(n) asm volatile("s_waitcnt vmcnt(" #n ")" ::: "memory")
; #define PG8_WAIT_L(n) asm volatile("s_waitcnt lgkmcnt(" #n ")" ::: "memory")
; #define PG8_BAR __builtin_amdgcn_s_barrier()
; #define PG8_SCHED __builtin_amdgcn_sched_barrier(0)
; template <class Epi, class Sched, bool ALIGN_EPI = false, bool SP2 = false>
; __device__ __forceinline__ void gemm_phase(PG8_LAS unsigned char* lds, const Gemm g, const Sched& S, const Epi& E, int tid_in) {
;     ...
;             PG8_LDA(At, 0, 1); PG8_STAGE(PG8_SB(0, 0), b2, voffB); PG8_STAGE(PG8_SB(0, 1), b2 + hstep, voffB); PG8_STAGE(PG8_SA(0, 0), a2, voffA);
;             PG8_WAIT_V(8); PG8_WAIT_L(0); PG8_BAR; PG8_MMA(1, 0, At, B0); PG8_MMA(1, 1, At, B1); PG8_BAR; PG8_SCHED;
;             PG8_LDB(B0, 1, 0); PG8_LDB(B1, 1, 1); PG8_SCHED; PG8_LDA(At, 1, 0); PG8_STAGE(PG8_SA(0, 1), a2 + hstepA, voffA);
;             PG8_WAIT_V(8); PG8_WAIT_L(0); PG8_BAR; PG8_MMA(0, 0, At, B0); PG8_MMA(0, 1, At, B1); PG8_BAR; PG8_SCHED;
	s_setprio 1
	s_waitcnt lgkmcnt(0)
	v_mfma_f32_16x16x32_bf16 v[62:65], v[142:145], v[194:197], v[62:65]
	v_mfma_f32_16x16x32_bf16 v[58:61], v[152:155], v[194:197], v[58:61]
	v_mfma_f32_16x16x32_bf16 v[46:49], v[142:145], v[202:205], v[46:49]
	v_mfma_f32_16x16x32_bf16 v[42:45], v[152:155], v[202:205], v[42:45]
	v_mfma_f32_16x16x32_bf16 v[30:33], v[142:145], v[210:213], v[30:33]
	v_mfma_f32_16x16x32_bf16 v[26:29], v[152:155], v[210:213], v[26:29]
	v_mfma_f32_16x16x32_bf16 v[14:17], v[142:145], v[218:221], v[14:17]
	v_mfma_f32_16x16x32_bf16 v[10:13], v[152:155], v[218:221], v[10:13]
	v_mfma_f32_16x16x32_bf16 v[62:65], v[146:149], v[198:201], v[62:65]
	v_mfma_f32_16x16x32_bf16 v[58:61], v[160:163], v[198:201], v[58:61]
	v_mfma_f32_16x16x32_bf16 v[46:49], v[146:149], v[206:209], v[46:49]
	v_mfma_f32_16x16x32_bf16 v[42:45], v[160:163], v[206:209], v[42:45]
	v_mfma_f32_16x16x32_bf16 v[30:33], v[146:149], v[214:217], v[30:33]
	v_mfma_f32_16x16x32_bf16 v[26:29], v[160:163], v[214:217], v[26:29]
	v_mfma_f32_16x16x32_bf16 v[14:17], v[146:149], v[222:225], v[14:17]
	v_mfma_f32_16x16x32_bf16 v[10:13], v[160:163], v[222:225], v[10:13]
	s_setprio 0
	s_setprio 1
	v_mfma_f32_16x16x32_bf16 v[54:57], v[164:167], v[194:197], v[54:57]
	v_mfma_f32_16x16x32_bf16 v[50:53], v[186:189], v[194:197], v[50:53]
	v_mfma_f32_16x16x32_bf16 v[38:41], v[164:167], v[202:205], v[38:41]
	v_mfma_f32_16x16x32_bf16 v[34:37], v[186:189], v[202:205], v[34:37]
	v_mfma_f32_16x16x32_bf16 v[22:25], v[164:167], v[210:213], v[22:25]
	v_mfma_f32_16x16x32_bf16 v[18:21], v[186:189], v[210:213], v[18:21]
	v_mfma_f32_16x16x32_bf16 v[6:9], v[164:167], v[218:221], v[6:9]
	v_mfma_f32_16x16x32_bf16 v[2:5], v[186:189], v[218:221], v[2:5]
	v_mfma_f32_16x16x32_bf16 v[54:57], v[182:185], v[198:201], v[54:57]
	v_mfma_f32_16x16x32_bf16 v[50:53], v[190:193], v[198:201], v[50:53]
	v_mfma_f32_16x16x32_bf16 v[38:41], v[182:185], v[206:209], v[38:41]
	v_mfma_f32_16x16x32_bf16 v[34:37], v[190:193], v[206:209], v[34:37]
	v_mfma_f32_16x16x32_bf16 v[22:25], v[182:185], v[214:217], v[22:25]
	v_mfma_f32_16x16x32_bf16 v[18:21], v[190:193], v[214:217], v[18:21]
	v_mfma_f32_16x16x32_bf16 v[6:9], v[182:185], v[222:225], v[6:9]
	v_mfma_f32_16x16x32_bf16 v[2:5], v[190:193], v[222:225], v[2:5]
	s_setprio 0
	s_barrier
	v_lshl_add_u64 v[228:229], s[30:31], 0, v[130:131]
	s_mov_b32 m0, s38
	s_nop 0
	global_load_lds_dwordx4 v[228:229], off
	s_mov_b32 m0, s39
	s_nop 0
	global_load_lds_dwordx4 v[240:241], off
	v_add_u32_e32 v150, s63, v157
	ds_read_b128 v[142:145], v150
	ds_read_b128 v[146:149], v150 offset:1024
	ds_read_b128 v[152:155], v150 offset:2048
	ds_read_b128 v[160:163], v150 offset:3072
	v_add_u32_e32 v150, s55, v157
	ds_read_b128 v[164:167], v150
	ds_read_b128 v[182:185], v150 offset:1024
	ds_read_b128 v[186:189], v150 offset:2048
	ds_read_b128 v[190:193], v150 offset:3072
	s_add_u32 s30, s30, 0x80000
	s_addc_u32 s31, s31, 0
	s_mov_b32 m0, s40
	v_lshl_add_u64 v[242:243], s[30:31], 0, v[130:131]
	ds_read_b128 v[194:197], v158 offset:32768
	ds_read_b128 v[198:201], v158 offset:33792
	ds_read_b128 v[202:205], v158 offset:34816
	ds_read_b128 v[206:209], v158 offset:35840
	ds_read_b128 v[210:213], v158 offset:36864
	ds_read_b128 v[214:217], v158 offset:37888
	ds_read_b128 v[218:221], v158 offset:38912
	ds_read_b128 v[222:225], v158 offset:39936
	global_load_lds_dwordx4 v[242:243], off
	v_lshl_add_u64 v[242:243], s[30:31], 0, v[132:133]
	s_mov_b32 m0, s41
	s_nop 0
	global_load_lds_dwordx4 v[242:243], off
	s_waitcnt vmcnt(8)
	s_waitcnt lgkmcnt(0)
	s_barrier
	s_setprio 1
	s_waitcnt lgkmcnt(0)
	v_mfma_f32_16x16x32_bf16 v[126:129], v[142:145], v[194:197], v[126:129]
	v_mfma_f32_16x16x32_bf16 v[122:125], v[152:155], v[194:197], v[122:125]
	v_mfma_f32_16x16x32_bf16 v[110:113], v[142:145], v[202:205], v[110:113]
	v_mfma_f32_16x16x32_bf16 v[106:109], v[152:155], v[202:205], v[106:109]
	v_mfma_f32_16x16x32_bf16 v[94:97], v[142:145], v[210:213], v[94:97]
	v_mfma_f32_16x16x32_bf16 v[90:93], v[152:155], v[210:213], v[90:93]
	v_mfma_f32_16x16x32_bf16 v[78:81], v[142:145], v[218:221], v[78:81]
	v_mfma_f32_16x16x32_bf16 v[74:77], v[152:155], v[218:221], v[74:77]
	v_mfma_f32_16x16x32_bf16 v[126:129], v[146:149], v[198:201], v[126:129]
	v_mfma_f32_16x16x32_bf16 v[122:125], v[160:163], v[198:201], v[122:125]
	v_mfma_f32_16x16x32_bf16 v[110:113], v[146:149], v[206:209], v[110:113]
	v_mfma_f32_16x16x32_bf16 v[106:109], v[160:163], v[206:209], v[106:109]
	v_mfma_f32_16x16x32_bf16 v[94:97], v[146:149], v[214:217], v[94:97]
	v_mfma_f32_16x16x32_bf16 v[90:93], v[160:163], v[214:217], v[90:93]
	v_mfma_f32_16x16x32_bf16 v[78:81], v[146:149], v[222:225], v[78:81]
	v_mfma_f32_16x16x32_bf16 v[74:77], v[160:163], v[222:225], v[74:77]
	s_setprio 0
	s_setprio 1
	v_mfma_f32_16x16x32_bf16 v[118:121], v[164:167], v[194:197], v[118:121]
	v_mfma_f32_16x16x32_bf16 v[114:117], v[186:189], v[194:197], v[114:117]
	v_mfma_f32_16x16x32_bf16 v[102:105], v[164:167], v[202:205], v[102:105]
	v_mfma_f32_16x16x32_bf16 v[98:101], v[186:189], v[202:205], v[98:101]
	v_mfma_f32_16x16x32_bf16 v[86:89], v[164:167], v[210:213], v[86:89]
	v_mfma_f32_16x16x32_bf16 v[82:85], v[186:189], v[210:213], v[82:85]
	v_mfma_f32_16x16x32_bf16 v[70:73], v[164:167], v[218:221], v[70:73]
	v_mfma_f32_16x16x32_bf16 v[66:69], v[186:189], v[218:221], v[66:69]
	v_mfma_f32_16x16x32_bf16 v[118:121], v[182:185], v[198:201], v[118:121]
	v_mfma_f32_16x16x32_bf16 v[114:117], v[190:193], v[198:201], v[114:117]
	v_mfma_f32_16x16x32_bf16 v[102:105], v[182:185], v[206:209], v[102:105]
	v_mfma_f32_16x16x32_bf16 v[98:101], v[190:193], v[206:209], v[98:101]
	v_mfma_f32_16x16x32_bf16 v[86:89], v[182:185], v[214:217], v[86:89]
	v_mfma_f32_16x16x32_bf16 v[82:85], v[190:193], v[214:217], v[82:85]
	v_mfma_f32_16x16x32_bf16 v[70:73], v[182:185], v[222:225], v[70:73]
	v_mfma_f32_16x16x32_bf16 v[66:69], v[190:193], v[222:225], v[66:69]
	s_setprio 0
	s_barrier
; #define PG8_STAGE(bufoff, gbase, voff) do { _Pragma("unroll") for (int _i = 0; _i < 2; ++_i) \
;         __builtin_amdgcn_global_load_lds((const unsigned*)((const char*)(gbase) + (voff)[_i]), (PG8_LAS unsigned*)(lds + (bufoff) + ldsw + _i * 8192), 16, 0, 0); } while (0)
; #define PG8_LDA(dst, b, h) do { _Pragma("unroll") for (int m = 0; m < 4; ++m) _Pragma("unroll") for (int k = 0; k < 2; ++k) dst[m][k] = *(const PG8_LAS bf16x8*)(lds + PG8_SA(b, h) + aoff + m * 2048 + k * 1024); } while (0)
; #define PG8_WAIT_V(n) asm volatile("s_waitcnt vmcnt(" #n ")" ::: "memory")
; #define PG8_WAIT_L(n) asm volatile("s_waitcnt lgkmcnt(" #n ")" ::: "memory")
; #define PG8_BAR __builtin_amdgcn_s_barrier()
; template <class Epi, class Sched, bool ALIGN_EPI = false, bool SP2 = false>
; __device__ __forceinline__ void gemm_phase(PG8_LAS unsigned char* lds, const Gemm g, const Sched& S, const Epi& E, int tid_in) {
;     ...
;         for (int t = 0; t < nt; t += 2) {
;             const bool last = (t == nt - 2);
;             const char* a1 = cA + (size_t)(t + 1) * kstep;
;             const char* a2 = last ? nA : cA + (size_t)(t + 2) * kstep; const char* b2 = last ? nB : cB + (size_t)(t + 2) * kstep;
;             const char* a3 = a2 + kstep; const char* b3 = b2 + kstep;
;             if (last && has_next) S.a_ready(nxt);
;             if constexpr (SP2) {
;             PG8_LDB(B0, 0, 0); PG8_LDB(B1, 0, 1); PG8_SCHED; PG8_LDA(At, 0, 0); PG8_STAGE(PG8_SA(1, 1), a1 + hstepA, voffA);
;             PG8_WAIT_V(8); PG8_WAIT_L(0); PG8_BAR; PG8_MMA(0, 0, At, B0); PG8_MMA(0, 1, At, B1); PG8_BAR; PG8_SCHED;
;             PG8_LDA(At, 0, 1); PG8_STAGE(PG8_SB(0, 0), b2, voffB); PG8_STAGE(PG8_SB(0, 1), b2 + hstep, voffB); PG8_STAGE(PG8_SA(0, 0), a2, voffA);
;             PG8_WAIT_V(8); PG8_WAIT_L(0); PG8_BAR; PG8_MMA(1, 0, At, B0); PG8_MMA(1, 1, At, B1); PG8_BAR; PG8_SCHED;
;             PG8_LDB(B0, 1, 0); PG8_LDB(B1, 1, 1); PG8_SCHED; PG8_LDA(At, 1, 0); PG8_STAGE(PG8_SA(0, 1), a2 + hstepA, voffA);
;             PG8_WAIT_V(8); PG8_WAIT_L(0); PG8_BAR; PG8_MMA(0, 0, At, B0); PG8_MMA(0, 1, At, B1); PG8_BAR; PG8_SCHED;
;             PG8_LDA(At, 1, 1); PG8_STAGE(PG8_SB(1, 0), b3, voffB); PG8_STAGE(PG8_SB(1, 1), b3 + hstep, voffB); PG8_STAGE(PG8_SA(1, 0), a3, voffA);
;             PG8_WAIT_V(8); PG8_WAIT_L(0); PG8_BAR; PG8_MMA(1, 0, At, B0); PG8_MMA(1, 1, At, B1); PG8_BAR; PG8_SCHED;
	s_add_i32 s30, s63, s37
	v_lshl_add_u64 v[168:169], v[168:169], 0, s[90:91]
	s_mov_b32 m0, s30
	ds_read_b128 v[194:197], v158 offset:49152
	ds_read_b128 v[198:201], v158 offset:50176
	ds_read_b128 v[202:205], v158 offset:51200
	ds_read_b128 v[206:209], v158 offset:52224
	ds_read_b128 v[210:213], v158 offset:53248
	ds_read_b128 v[214:217], v158 offset:54272
	ds_read_b128 v[218:221], v158 offset:55296
	ds_read_b128 v[222:225], v158 offset:56320
	global_load_lds_dwordx4 v[168:169], off
	s_add_i32 m0, s30, 0x2000
	s_add_u32 s28, s28, 0x80080
	v_lshl_add_u64 v[168:169], v[226:227], 0, s[90:91]
	s_addc_u32 s29, s29, 0
	s_add_i32 s30, s55, s37
	global_load_lds_dwordx4 v[168:169], off
	v_lshl_add_u64 v[168:169], s[28:29], 0, v[0:1]
	s_mov_b32 m0, s30
	s_nop 0
	global_load_lds_dwordx4 v[168:169], off
	v_lshl_add_u64 v[168:169], s[28:29], 0, v[134:135]
	s_add_i32 m0, s30, 0x2000
	s_nop 0
	global_load_lds_dwordx4 v[168:169], off
	v_lshl_add_u64 v[168:169], v[228:229], 0, s[90:91]
	s_mov_b32 m0, s45
	s_nop 0
	global_load_lds_dwordx4 v[168:169], off
	v_lshl_add_u64 v[168:169], v[240:241], 0, s[90:91]
	s_mov_b32 m0, s48
	s_nop 0
	global_load_lds_dwordx4 v[168:169], off
	s_add_i32 s23, s23, 2
	s_add_u32 s14, s14, 0x100
	s_addc_u32 s15, s15, 0
	s_add_u32 s13, s13, 0x100
	s_addc_u32 s21, s21, 0
	s_cmp_gt_u32 s23, 29
	s_waitcnt vmcnt(8)
	s_waitcnt lgkmcnt(0)
	s_barrier
	s_setprio 1
	s_waitcnt lgkmcnt(0)
	v_mfma_f32_16x16x32_bf16 v[62:65], v[142:145], v[194:197], v[62:65]
	v_mfma_f32_16x16x32_bf16 v[58:61], v[152:155], v[194:197], v[58:61]
	v_mfma_f32_16x16x32_bf16 v[46:49], v[142:145], v[202:205], v[46:49]
	v_mfma_f32_16x16x32_bf16 v[42:45], v[152:155], v[202:205], v[42:45]
	v_mfma_f32_16x16x32_bf16 v[30:33], v[142:145], v[210:213], v[30:33]
	v_mfma_f32_16x16x32_bf16 v[26:29], v[152:155], v[210:213], v[26:29]
	v_mfma_f32_16x16x32_bf16 v[14:17], v[142:145], v[218:221], v[14:17]
	v_mfma_f32_16x16x32_bf16 v[10:13], v[152:155], v[218:221], v[10:13]
	v_mfma_f32_16x16x32_bf16 v[62:65], v[146:149], v[198:201], v[62:65]
	v_mfma_f32_16x16x32_bf16 v[58:61], v[160:163], v[198:201], v[58:61]
	v_mfma_f32_16x16x32_bf16 v[46:49], v[146:149], v[206:209], v[46:49]
	v_mfma_f32_16x16x32_bf16 v[42:45], v[160:163], v[206:209], v[42:45]
	v_mfma_f32_16x16x32_bf16 v[30:33], v[146:149], v[214:217], v[30:33]
	v_mfma_f32_16x16x32_bf16 v[26:29], v[160:163], v[214:217], v[26:29]
	v_mfma_f32_16x16x32_bf16 v[14:17], v[146:149], v[222:225], v[14:17]
	v_mfma_f32_16x16x32_bf16 v[10:13], v[160:163], v[222:225], v[10:13]
	s_setprio 0
	s_setprio 1
	v_mfma_f32_16x16x32_bf16 v[54:57], v[164:167], v[194:197], v[54:57]
	v_mfma_f32_16x16x32_bf16 v[50:53], v[186:189], v[194:197], v[50:53]
	v_mfma_f32_16x16x32_bf16 v[38:41], v[164:167], v[202:205], v[38:41]
	v_mfma_f32_16x16x32_bf16 v[34:37], v[186:189], v[202:205], v[34:37]
	v_mfma_f32_16x16x32_bf16 v[22:25], v[164:167], v[210:213], v[22:25]
	v_mfma_f32_16x16x32_bf16 v[18:21], v[186:189], v[210:213], v[18:21]
	v_mfma_f32_16x16x32_bf16 v[6:9], v[164:167], v[218:221], v[6:9]
	v_mfma_f32_16x16x32_bf16 v[2:5], v[186:189], v[218:221], v[2:5]
	v_mfma_f32_16x16x32_bf16 v[54:57], v[182:185], v[198:201], v[54:57]
	v_mfma_f32_16x16x32_bf16 v[50:53], v[190:193], v[198:201], v[50:53]
	v_mfma_f32_16x16x32_bf16 v[38:41], v[182:185], v[206:209], v[38:41]
	v_mfma_f32_16x16x32_bf16 v[34:37], v[190:193], v[206:209], v[34:37]
	v_mfma_f32_16x16x32_bf16 v[22:25], v[182:185], v[214:217], v[22:25]
	v_mfma_f32_16x16x32_bf16 v[18:21], v[190:193], v[214:217], v[18:21]
	v_mfma_f32_16x16x32_bf16 v[6:9], v[182:185], v[222:225], v[6:9]
	v_mfma_f32_16x16x32_bf16 v[2:5], v[190:193], v[222:225], v[2:5]
	s_setprio 0
	s_barrier
	s_cbranch_scc0 .LBB0_513
	s_and_b64 vcc, exec, s[18:19]
	s_cbranch_vccz .LBB0_516
	s_barrier

; #define PG8_STAGE(bufoff, gbase, voff) do { _Pragma("unroll") for (int _i = 0; _i < 2; ++_i) \
;         __builtin_amdgcn_global_load_lds((const unsigned*)((const char*)(gbase) + (voff)[_i]), (PG8_LAS unsigned*)(lds + (bufoff) + ldsw + _i * 8192), 16, 0, 0); } while (0)
; #define PG8_LDA(dst, b, h) do { _Pragma("unroll") for (int m = 0; m < 4; ++m) _Pragma("unroll") for (int k = 0; k < 2; ++k) dst[m][k] = *(const PG8_LAS bf16x8*)(lds + PG8_SA(b, h) + aoff + m * 2048 + k * 1024); } while (0)
; #define PG8_LDB(dst, b, h) do { _Pragma("unroll") for (int n = 0; n < 2; ++n) _Pragma("unroll") for (int k = 0; k < 2; ++k) dst[n][k] = *(const PG8_LAS bf16x8*)(lds + PG8_SB(b, h) + boff + n * 2048 + k * 1024); } while (0)
; #define PG8_MMA(ai, bj, At, Bt) do { __builtin_amdgcn_s_setprio(1); _Pragma("unroll") for (int m = 0; m < 4; ++m) _Pragma("unroll") for (int n = 0; n < 2; ++n) _Pragma("unroll") for (int k = 0; k < 2; ++k) \
;         acc[ai][bj][m][n] = __builtin_amdgcn_mfma_f32_16x16x32_bf16(Bt[n][k], At[m][k], acc[ai][bj][m][n], 0, 0, 0); __builtin_amdgcn_s_setprio(0); } while (0)
; #define PG8_WAIT_V(n) asm volatile("s_waitcnt vmcnt(" #n ")" ::: "memory")
; #define PG8_WAIT_L(n) asm volatile("s_waitcnt lgkmcnt(" #n ")" ::: "memory")
; template <class Epi, class Sched, bool ALIGN_EPI = false, bool SP2 = false>
; __device__ __forceinline__ void gemm_phase(PG8_LAS unsigned char* lds, const Gemm g, const Sched& S, const Epi& E, int tid_in) {
;     ...
;             const bool last = (t == nt - 2);
;             const char* a1 = cA + (size_t)(t + 1) * kstep;
;             const char* a2 = last ? nA : cA + (size_t)(t + 2) * kstep; const char* b2 = last ? nB : cB + (size_t)(t + 2) * kstep;
;             const char* a3 = a2 + kstep; const char* b3 = b2 + kstep;
;             if (last && has_next) S.a_ready(nxt);
;             if constexpr (SP2) {
;             PG8_LDB(B0, 0, 0); PG8_LDB(B1, 0, 1); PG8_SCHED; PG8_LDA(At, 0, 0); PG8_STAGE(PG8_SA(1, 1), a1 + hstepA, voffA);
;             PG8_WAIT_V(8); PG8_WAIT_L(0); PG8_BAR; PG8_MMA(0, 0, At, B0); PG8_MMA(0, 1, At, B1); PG8_BAR; PG8_SCHED;
;             PG8_LDA(At, 0, 1); PG8_STAGE(PG8_SB(0, 0), b2, voffB); PG8_STAGE(PG8_SB(0, 1), b2 + hstep, voffB); PG8_STAGE(PG8_SA(0, 0), a2, voffA);
;             PG8_WAIT_V(8); PG8_WAIT_L(0); PG8_BAR; PG8_MMA(1, 0, At, B0); PG8_MMA(1, 1, At, B1); PG8_BAR; PG8_SCHED;
.LBB0_627:
	v_add_u32_e32 v140, s4, v145
	ds_read_b128 v[148:151], v140
	ds_read_b128 v[152:155], v140 offset:1024
	ds_read_b128 v[156:159], v140 offset:2048
	ds_read_b128 v[160:163], v140 offset:3072
	v_add_u32_e32 v140, s5, v145
	ds_read_b128 v[164:167], v140
	ds_read_b128 v[182:185], v140 offset:1024
	ds_read_b128 v[186:189], v140 offset:2048
	ds_read_b128 v[190:193], v140 offset:3072
	s_add_u32 s22, s20, 0x100
	s_addc_u32 s23, s21, 0
	s_cmp_eq_u32 s48, 4
	s_cselect_b32 s27, s17, s23
	s_cselect_b32 s26, s16, s22
	s_cselect_b32 s25, s19, s15
	s_cselect_b32 s24, s18, s0
	v_lshl_add_u64 v[168:169], s[20:21], 0, v[136:137]
	s_add_i32 m0, s34, 0xc000
	ds_read_b128 v[194:197], v147
	ds_read_b128 v[198:201], v147 offset:1024
	ds_read_b128 v[202:205], v147 offset:2048
	ds_read_b128 v[206:209], v147 offset:3072
	ds_read_b128 v[210:213], v147 offset:4096
	ds_read_b128 v[214:217], v147 offset:5120
	ds_read_b128 v[218:221], v147 offset:6144
	ds_read_b128 v[222:225], v147 offset:7168
	global_load_lds_dwordx4 v[168:169], off
	v_lshl_add_u64 v[168:169], s[20:21], 0, v[138:139]
	s_add_i32 m0, s34, 0xe000
	s_nop 0
	global_load_lds_dwordx4 v[168:169], off
	s_waitcnt vmcnt(8)
	s_waitcnt lgkmcnt(0)
	s_barrier
	s_setprio 1
	s_waitcnt lgkmcnt(0)
	v_mfma_f32_16x16x32_bf16 v[126:129], v[148:151], v[194:197], v[126:129]
	v_mfma_f32_16x16x32_bf16 v[122:125], v[156:159], v[194:197], v[122:125]
	v_mfma_f32_16x16x32_bf16 v[114:117], v[148:151], v[202:205], v[114:117]
	v_mfma_f32_16x16x32_bf16 v[106:109], v[156:159], v[202:205], v[106:109]
	v_mfma_f32_16x16x32_bf16 v[98:101], v[148:151], v[210:213], v[98:101]
	v_mfma_f32_16x16x32_bf16 v[90:93], v[156:159], v[210:213], v[90:93]
	v_mfma_f32_16x16x32_bf16 v[82:85], v[148:151], v[218:221], v[82:85]
	v_mfma_f32_16x16x32_bf16 v[74:77], v[156:159], v[218:221], v[74:77]
	v_mfma_f32_16x16x32_bf16 v[126:129], v[152:155], v[198:201], v[126:129]
	v_mfma_f32_16x16x32_bf16 v[122:125], v[160:163], v[198:201], v[122:125]
	v_mfma_f32_16x16x32_bf16 v[114:117], v[152:155], v[206:209], v[114:117]
	v_mfma_f32_16x16x32_bf16 v[106:109], v[160:163], v[206:209], v[106:109]
	v_mfma_f32_16x16x32_bf16 v[98:101], v[152:155], v[214:217], v[98:101]
	v_mfma_f32_16x16x32_bf16 v[90:93], v[160:163], v[214:217], v[90:93]
	v_mfma_f32_16x16x32_bf16 v[82:85], v[152:155], v[222:225], v[82:85]
	v_mfma_f32_16x16x32_bf16 v[74:77], v[160:163], v[222:225], v[74:77]
	s_setprio 0
	s_setprio 1
	v_mfma_f32_16x16x32_bf16 v[118:121], v[164:167], v[194:197], v[118:121]
	v_mfma_f32_16x16x32_bf16 v[110:113], v[186:189], v[194:197], v[110:113]
	v_mfma_f32_16x16x32_bf16 v[102:105], v[164:167], v[202:205], v[102:105]
	v_mfma_f32_16x16x32_bf16 v[94:97], v[186:189], v[202:205], v[94:97]
	v_mfma_f32_16x16x32_bf16 v[86:89], v[164:167], v[210:213], v[86:89]
	v_mfma_f32_16x16x32_bf16 v[78:81], v[186:189], v[210:213], v[78:81]
	v_mfma_f32_16x16x32_bf16 v[70:73], v[164:167], v[218:221], v[70:73]
	v_mfma_f32_16x16x32_bf16 v[66:69], v[186:189], v[218:221], v[66:69]
	v_mfma_f32_16x16x32_bf16 v[118:121], v[182:185], v[198:201], v[118:121]
	v_mfma_f32_16x16x32_bf16 v[110:113], v[190:193], v[198:201], v[110:113]
	v_mfma_f32_16x16x32_bf16 v[102:105], v[182:185], v[206:209], v[102:105]
	v_mfma_f32_16x16x32_bf16 v[94:97], v[190:193], v[206:209], v[94:97]
	v_mfma_f32_16x16x32_bf16 v[86:89], v[182:185], v[214:217], v[86:89]
	v_mfma_f32_16x16x32_bf16 v[78:81], v[190:193], v[214:217], v[78:81]
	v_mfma_f32_16x16x32_bf16 v[70:73], v[182:185], v[222:225], v[70:73]
	v_mfma_f32_16x16x32_bf16 v[66:69], v[190:193], v[222:225], v[66:69]
	s_setprio 0
	s_barrier
	s_add_i32 s20, s4, s33
	v_lshl_add_u64 v[168:169], s[24:25], 0, v[0:1]
	s_mov_b32 m0, s20
	ds_read_b128 v[194:197], v147 offset:16384
	ds_read_b128 v[198:201], v147 offset:17408
	ds_read_b128 v[202:205], v147 offset:18432
	ds_read_b128 v[206:209], v147 offset:19456
	ds_read_b128 v[210:213], v147 offset:20480
	ds_read_b128 v[214:217], v147 offset:21504
	ds_read_b128 v[218:221], v147 offset:22528
	ds_read_b128 v[222:225], v147 offset:23552
	global_load_lds_dwordx4 v[168:169], off
	s_add_i32 m0, s20, 0x2000
	s_add_u32 s20, s24, 0x20000
	v_lshl_add_u64 v[226:227], s[24:25], 0, v[134:135]
	s_addc_u32 s21, s25, 0
	s_add_i32 s49, s5, s33
	global_load_lds_dwordx4 v[226:227], off
	v_lshl_add_u64 v[228:229], s[20:21], 0, v[0:1]
	s_mov_b32 m0, s49
	v_lshl_add_u64 v[240:241], s[26:27], 0, v[132:133]
	global_load_lds_dwordx4 v[228:229], off
	v_lshl_add_u64 v[228:229], s[20:21], 0, v[134:135]
	s_add_i32 m0, s49, 0x2000
	s_nop 0
	global_load_lds_dwordx4 v[228:229], off
	s_waitcnt vmcnt(6)
	s_waitcnt lgkmcnt(0)
	s_barrier
; #define PG8_STAGE(bufoff, gbase, voff) do { _Pragma("unroll") for (int _i = 0; _i < 2; ++_i) \
;         __builtin_amdgcn_global_load_lds((const unsigned*)((const char*)(gbase) + (voff)[_i]), (PG8_LAS unsigned*)(lds + (bufoff) + ldsw + _i * 8192), 16, 0, 0); } while (0)
; #define PG8_LDA(dst, b, h) do { _Pragma("unroll") for (int m = 0; m < 4; ++m) _Pragma("unroll") for (int k = 0; k < 2; ++k) dst[m][k] = *(const PG8_LAS bf16x8*)(lds + PG8_SA(b, h) + aoff + m * 2048 + k * 1024); } while (0)
; #define PG8_LDB(dst, b, h) do { _Pragma("unroll") for (int n = 0; n < 2; ++n) _Pragma("unroll") for (int k = 0; k < 2; ++k) dst[n][k] = *(const PG8_LAS bf16x8*)(lds + PG8_SB(b, h) + boff + n * 2048 + k * 1024); } while (0)
; #define PG8_MMA(ai, bj, At, Bt) do { __builtin_amdgcn_s_setprio(1); _Pragma("unroll") for (int m = 0; m < 4; ++m) _Pragma("unroll") for (int n = 0; n < 2; ++n) _Pragma("unroll") for (int k = 0; k < 2; ++k) \
;         acc[ai][bj][m][n] = __builtin_amdgcn_mfma_f32_16x16x32_bf16(Bt[n][k], At[m][k], acc[ai][bj][m][n], 0, 0, 0); __builtin_amdgcn_s_setprio(0); } while (0)
; #define PG8_WAIT_V(n) asm volatile("s_waitcnt vmcnt(" #n ")" ::: "memory")
; #define PG8_WAIT_L(n) asm volatile("s_waitcnt lgkmcnt(" #n ")" ::: "memory")
; #define PG8_BAR __builtin_amdgcn_s_barrier()
; #define PG8_SCHED __builtin_amdgcn_sched_barrier(0)
; template <class Epi, class Sched, bool ALIGN_EPI = false, bool SP2 = false>
; __device__ __forceinline__ void gemm_phase(PG8_LAS unsigned char* lds, const Gemm g, const Sched& S, const Epi& E, int tid_in) {
;     ...
;             PG8_WAIT_V(8); PG8_WAIT_L(0); PG8_BAR; PG8_MMA(1, 0, At, B0); PG8_MMA(1, 1, At, B1); PG8_BAR; PG8_SCHED;
;             PG8_LDB(B0, 1, 0); PG8_LDB(B1, 1, 1); PG8_SCHED; PG8_LDA(At, 1, 0); PG8_STAGE(PG8_SA(0, 1), a2 + hstepA, voffA);
;             PG8_WAIT_V(8); PG8_WAIT_L(0); PG8_BAR; PG8_MMA(0, 0, At, B0); PG8_MMA(0, 1, At, B1); PG8_BAR; PG8_SCHED;
	s_setprio 1
	s_waitcnt lgkmcnt(0)
	v_mfma_f32_16x16x32_bf16 v[62:65], v[148:151], v[194:197], v[62:65]
	v_mfma_f32_16x16x32_bf16 v[58:61], v[156:159], v[194:197], v[58:61]
	v_mfma_f32_16x16x32_bf16 v[50:53], v[148:151], v[202:205], v[50:53]
	v_mfma_f32_16x16x32_bf16 v[42:45], v[156:159], v[202:205], v[42:45]
	v_mfma_f32_16x16x32_bf16 v[34:37], v[148:151], v[210:213], v[34:37]
	v_mfma_f32_16x16x32_bf16 v[26:29], v[156:159], v[210:213], v[26:29]
	v_mfma_f32_16x16x32_bf16 v[18:21], v[148:151], v[218:221], v[18:21]
	v_mfma_f32_16x16x32_bf16 v[10:13], v[156:159], v[218:221], v[10:13]
	v_mfma_f32_16x16x32_bf16 v[62:65], v[152:155], v[198:201], v[62:65]
	v_mfma_f32_16x16x32_bf16 v[58:61], v[160:163], v[198:201], v[58:61]
	v_mfma_f32_16x16x32_bf16 v[50:53], v[152:155], v[206:209], v[50:53]
	v_mfma_f32_16x16x32_bf16 v[42:45], v[160:163], v[206:209], v[42:45]
	v_mfma_f32_16x16x32_bf16 v[34:37], v[152:155], v[214:217], v[34:37]
	v_mfma_f32_16x16x32_bf16 v[26:29], v[160:163], v[214:217], v[26:29]
	v_mfma_f32_16x16x32_bf16 v[18:21], v[152:155], v[222:225], v[18:21]
	v_mfma_f32_16x16x32_bf16 v[10:13], v[160:163], v[222:225], v[10:13]
	s_setprio 0
	s_setprio 1
	v_mfma_f32_16x16x32_bf16 v[54:57], v[164:167], v[194:197], v[54:57]
	v_mfma_f32_16x16x32_bf16 v[46:49], v[186:189], v[194:197], v[46:49]
	v_mfma_f32_16x16x32_bf16 v[38:41], v[164:167], v[202:205], v[38:41]
	v_mfma_f32_16x16x32_bf16 v[30:33], v[186:189], v[202:205], v[30:33]
	v_mfma_f32_16x16x32_bf16 v[22:25], v[164:167], v[210:213], v[22:25]
	v_mfma_f32_16x16x32_bf16 v[14:17], v[186:189], v[210:213], v[14:17]
	v_mfma_f32_16x16x32_bf16 v[6:9], v[164:167], v[218:221], v[6:9]
	v_mfma_f32_16x16x32_bf16 v[2:5], v[186:189], v[218:221], v[2:5]
	v_mfma_f32_16x16x32_bf16 v[54:57], v[182:185], v[198:201], v[54:57]
	v_mfma_f32_16x16x32_bf16 v[46:49], v[190:193], v[198:201], v[46:49]
	v_mfma_f32_16x16x32_bf16 v[38:41], v[182:185], v[206:209], v[38:41]
	v_mfma_f32_16x16x32_bf16 v[30:33], v[190:193], v[206:209], v[30:33]
	v_mfma_f32_16x16x32_bf16 v[22:25], v[182:185], v[214:217], v[22:25]
	v_mfma_f32_16x16x32_bf16 v[14:17], v[190:193], v[214:217], v[14:17]
	v_mfma_f32_16x16x32_bf16 v[6:9], v[182:185], v[222:225], v[6:9]
	v_mfma_f32_16x16x32_bf16 v[2:5], v[190:193], v[222:225], v[2:5]
	s_setprio 0
	s_barrier
	v_lshl_add_u64 v[228:229], s[26:27], 0, v[130:131]
	s_mov_b32 m0, s34
	s_nop 0
	global_load_lds_dwordx4 v[228:229], off
	s_mov_b32 m0, s35
	s_nop 0
	global_load_lds_dwordx4 v[240:241], off
	v_add_u32_e32 v140, s63, v145
	ds_read_b128 v[148:151], v140
	ds_read_b128 v[152:155], v140 offset:1024
	ds_read_b128 v[156:159], v140 offset:2048
	ds_read_b128 v[160:163], v140 offset:3072
	v_add_u32_e32 v140, s55, v145
	ds_read_b128 v[164:167], v140
	ds_read_b128 v[182:185], v140 offset:1024
	ds_read_b128 v[186:189], v140 offset:2048
	ds_read_b128 v[190:193], v140 offset:3072
	s_add_u32 s20, s26, 0x2e0000
	s_addc_u32 s21, s27, 0
	s_mov_b32 m0, s36
	v_lshl_add_u64 v[242:243], s[20:21], 0, v[130:131]
	ds_read_b128 v[194:197], v147 offset:32768
	ds_read_b128 v[198:201], v147 offset:33792
	ds_read_b128 v[202:205], v147 offset:34816
	ds_read_b128 v[206:209], v147 offset:35840
	ds_read_b128 v[210:213], v147 offset:36864
	ds_read_b128 v[214:217], v147 offset:37888
	ds_read_b128 v[218:221], v147 offset:38912
	ds_read_b128 v[222:225], v147 offset:39936
	global_load_lds_dwordx4 v[242:243], off
	v_lshl_add_u64 v[242:243], s[20:21], 0, v[132:133]
	s_mov_b32 m0, s37
	s_nop 0
	global_load_lds_dwordx4 v[242:243], off
	s_waitcnt vmcnt(8)
	s_waitcnt lgkmcnt(0)
	s_barrier
	s_setprio 1
	s_waitcnt lgkmcnt(0)
	v_mfma_f32_16x16x32_bf16 v[126:129], v[148:151], v[194:197], v[126:129]
	v_mfma_f32_16x16x32_bf16 v[122:125], v[156:159], v[194:197], v[122:125]
	v_mfma_f32_16x16x32_bf16 v[114:117], v[148:151], v[202:205], v[114:117]
	v_mfma_f32_16x16x32_bf16 v[106:109], v[156:159], v[202:205], v[106:109]
	v_mfma_f32_16x16x32_bf16 v[98:101], v[148:151], v[210:213], v[98:101]
	v_mfma_f32_16x16x32_bf16 v[90:93], v[156:159], v[210:213], v[90:93]
	v_mfma_f32_16x16x32_bf16 v[82:85], v[148:151], v[218:221], v[82:85]
	v_mfma_f32_16x16x32_bf16 v[74:77], v[156:159], v[218:221], v[74:77]
	v_mfma_f32_16x16x32_bf16 v[126:129], v[152:155], v[198:201], v[126:129]
	v_mfma_f32_16x16x32_bf16 v[122:125], v[160:163], v[198:201], v[122:125]
	v_mfma_f32_16x16x32_bf16 v[114:117], v[152:155], v[206:209], v[114:117]
	v_mfma_f32_16x16x32_bf16 v[106:109], v[160:163], v[206:209], v[106:109]
	v_mfma_f32_16x16x32_bf16 v[98:101], v[152:155], v[214:217], v[98:101]
	v_mfma_f32_16x16x32_bf16 v[90:93], v[160:163], v[214:217], v[90:93]
	v_mfma_f32_16x16x32_bf16 v[82:85], v[152:155], v[222:225], v[82:85]
	v_mfma_f32_16x16x32_bf16 v[74:77], v[160:163], v[222:225], v[74:77]
	s_setprio 0
	s_setprio 1
	v_mfma_f32_16x16x32_bf16 v[118:121], v[164:167], v[194:197], v[118:121]
	v_mfma_f32_16x16x32_bf16 v[110:113], v[186:189], v[194:197], v[110:113]
	v_mfma_f32_16x16x32_bf16 v[102:105], v[164:167], v[202:205], v[102:105]
	v_mfma_f32_16x16x32_bf16 v[94:97], v[186:189], v[202:205], v[94:97]
	v_mfma_f32_16x16x32_bf16 v[86:89], v[164:167], v[210:213], v[86:89]
	v_mfma_f32_16x16x32_bf16 v[78:81], v[186:189], v[210:213], v[78:81]
	v_mfma_f32_16x16x32_bf16 v[70:73], v[164:167], v[218:221], v[70:73]
	v_mfma_f32_16x16x32_bf16 v[66:69], v[186:189], v[218:221], v[66:69]
	v_mfma_f32_16x16x32_bf16 v[118:121], v[182:185], v[198:201], v[118:121]
	v_mfma_f32_16x16x32_bf16 v[110:113], v[190:193], v[198:201], v[110:113]
	v_mfma_f32_16x16x32_bf16 v[102:105], v[182:185], v[206:209], v[102:105]
	v_mfma_f32_16x16x32_bf16 v[94:97], v[190:193], v[206:209], v[94:97]
	v_mfma_f32_16x16x32_bf16 v[86:89], v[182:185], v[214:217], v[86:89]
	v_mfma_f32_16x16x32_bf16 v[78:81], v[190:193], v[214:217], v[78:81]
	v_mfma_f32_16x16x32_bf16 v[70:73], v[182:185], v[222:225], v[70:73]
	v_mfma_f32_16x16x32_bf16 v[66:69], v[190:193], v[222:225], v[66:69]
	s_setprio 0
	s_barrier
; #define PG8_STAGE(bufoff, gbase, voff) do { _Pragma("unroll") for (int _i = 0; _i < 2; ++_i) \
;         __builtin_amdgcn_global_load_lds((const unsigned*)((const char*)(gbase) + (voff)[_i]), (PG8_LAS unsigned*)(lds + (bufoff) + ldsw + _i * 8192), 16, 0, 0); } while (0)
; #define PG8_LDA(dst, b, h) do { _Pragma("unroll") for (int m = 0; m < 4; ++m) _Pragma("unroll") for (int k = 0; k < 2; ++k) dst[m][k] = *(const PG8_LAS bf16x8*)(lds + PG8_SA(b, h) + aoff + m * 2048 + k * 1024); } while (0)
; #define PG8_WAIT_V(n) asm volatile("s_waitcnt vmcnt(" #n ")" ::: "memory")
; #define PG8_WAIT_L(n) asm volatile("s_waitcnt lgkmcnt(" #n ")" ::: "memory")
; #define PG8_BAR __builtin_amdgcn_s_barrier()
; template <class Epi, class Sched, bool ALIGN_EPI = false, bool SP2 = false>
; __device__ __forceinline__ void gemm_phase(PG8_LAS unsigned char* lds, const Gemm g, const Sched& S, const Epi& E, int tid_in) {
;     ...
;         for (int t = 0; t < nt; t += 2) {
;             const bool last = (t == nt - 2);
;             const char* a1 = cA + (size_t)(t + 1) * kstep;
;             const char* a2 = last ? nA : cA + (size_t)(t + 2) * kstep; const char* b2 = last ? nB : cB + (size_t)(t + 2) * kstep;
;             const char* a3 = a2 + kstep; const char* b3 = b2 + kstep;
;             if (last && has_next) S.a_ready(nxt);
;             if constexpr (SP2) {
;             PG8_LDB(B0, 0, 0); PG8_LDB(B1, 0, 1); PG8_SCHED; PG8_LDA(At, 0, 0); PG8_STAGE(PG8_SA(1, 1), a1 + hstepA, voffA);
;             PG8_WAIT_V(8); PG8_WAIT_L(0); PG8_BAR; PG8_MMA(0, 0, At, B0); PG8_MMA(0, 1, At, B1); PG8_BAR; PG8_SCHED;
;             PG8_LDA(At, 0, 1); PG8_STAGE(PG8_SB(0, 0), b2, voffB); PG8_STAGE(PG8_SB(0, 1), b2 + hstep, voffB); PG8_STAGE(PG8_SA(0, 0), a2, voffA);
;             PG8_WAIT_V(8); PG8_WAIT_L(0); PG8_BAR; PG8_MMA(1, 0, At, B0); PG8_MMA(1, 1, At, B1); PG8_BAR; PG8_SCHED;
;             PG8_LDB(B0, 1, 0); PG8_LDB(B1, 1, 1); PG8_SCHED; PG8_LDA(At, 1, 0); PG8_STAGE(PG8_SA(0, 1), a2 + hstepA, voffA);
;             PG8_WAIT_V(8); PG8_WAIT_L(0); PG8_BAR; PG8_MMA(0, 0, At, B0); PG8_MMA(0, 1, At, B1); PG8_BAR; PG8_SCHED;
;             PG8_LDA(At, 1, 1); PG8_STAGE(PG8_SB(1, 0), b3, voffB); PG8_STAGE(PG8_SB(1, 1), b3 + hstep, voffB); PG8_STAGE(PG8_SA(1, 0), a3, voffA);
;             PG8_WAIT_V(8); PG8_WAIT_L(0); PG8_BAR; PG8_MMA(1, 0, At, B0); PG8_MMA(1, 1, At, B1); PG8_BAR; PG8_SCHED;
	s_add_i32 s20, s63, s33
	v_lshl_add_u64 v[168:169], v[168:169], 0, s[90:91]
	s_mov_b32 m0, s20
	ds_read_b128 v[194:197], v147 offset:49152
	ds_read_b128 v[198:201], v147 offset:50176
	ds_read_b128 v[202:205], v147 offset:51200
	ds_read_b128 v[206:209], v147 offset:52224
	ds_read_b128 v[210:213], v147 offset:53248
	ds_read_b128 v[214:217], v147 offset:54272
	ds_read_b128 v[218:221], v147 offset:55296
	ds_read_b128 v[222:225], v147 offset:56320
	global_load_lds_dwordx4 v[168:169], off
	s_add_i32 m0, s20, 0x2000
	s_add_u32 s20, s24, 0x20080
	v_lshl_add_u64 v[168:169], v[226:227], 0, s[90:91]
	s_addc_u32 s21, s25, 0
	s_add_i32 s24, s55, s33
	global_load_lds_dwordx4 v[168:169], off
	v_lshl_add_u64 v[168:169], s[20:21], 0, v[0:1]
	s_mov_b32 m0, s24
	s_nop 0
	global_load_lds_dwordx4 v[168:169], off
	v_lshl_add_u64 v[168:169], s[20:21], 0, v[134:135]
	s_add_i32 m0, s24, 0x2000
	s_nop 0
	global_load_lds_dwordx4 v[168:169], off
	v_lshl_add_u64 v[168:169], v[228:229], 0, s[90:91]
	s_mov_b32 m0, s42
	s_nop 0
	global_load_lds_dwordx4 v[168:169], off
	v_lshl_add_u64 v[168:169], v[240:241], 0, s[90:91]
	s_mov_b32 m0, s43
	s_nop 0
	global_load_lds_dwordx4 v[168:169], off
	s_add_i32 s48, s48, 2
	s_add_u32 s0, s0, 0x100
	s_addc_u32 s15, s15, 0
	s_cmp_gt_u32 s48, 5
	s_mov_b64 s[20:21], s[22:23]
	s_waitcnt vmcnt(8)
	s_waitcnt lgkmcnt(0)
	s_barrier
	s_setprio 1
	s_waitcnt lgkmcnt(0)
	v_mfma_f32_16x16x32_bf16 v[62:65], v[148:151], v[194:197], v[62:65]
	v_mfma_f32_16x16x32_bf16 v[58:61], v[156:159], v[194:197], v[58:61]
	v_mfma_f32_16x16x32_bf16 v[50:53], v[148:151], v[202:205], v[50:53]
	v_mfma_f32_16x16x32_bf16 v[42:45], v[156:159], v[202:205], v[42:45]
	v_mfma_f32_16x16x32_bf16 v[34:37], v[148:151], v[210:213], v[34:37]
	v_mfma_f32_16x16x32_bf16 v[26:29], v[156:159], v[210:213], v[26:29]
	v_mfma_f32_16x16x32_bf16 v[18:21], v[148:151], v[218:221], v[18:21]
	v_mfma_f32_16x16x32_bf16 v[10:13], v[156:159], v[218:221], v[10:13]
	v_mfma_f32_16x16x32_bf16 v[62:65], v[152:155], v[198:201], v[62:65]
	v_mfma_f32_16x16x32_bf16 v[58:61], v[160:163], v[198:201], v[58:61]
	v_mfma_f32_16x16x32_bf16 v[50:53], v[152:155], v[206:209], v[50:53]
	v_mfma_f32_16x16x32_bf16 v[42:45], v[160:163], v[206:209], v[42:45]
	v_mfma_f32_16x16x32_bf16 v[34:37], v[152:155], v[214:217], v[34:37]
	v_mfma_f32_16x16x32_bf16 v[26:29], v[160:163], v[214:217], v[26:29]
	v_mfma_f32_16x16x32_bf16 v[18:21], v[152:155], v[222:225], v[18:21]
	v_mfma_f32_16x16x32_bf16 v[10:13], v[160:163], v[222:225], v[10:13]
	s_setprio 0
	s_setprio 1
	v_mfma_f32_16x16x32_bf16 v[54:57], v[164:167], v[194:197], v[54:57]
	v_mfma_f32_16x16x32_bf16 v[46:49], v[186:189], v[194:197], v[46:49]
	v_mfma_f32_16x16x32_bf16 v[38:41], v[164:167], v[202:205], v[38:41]
	v_mfma_f32_16x16x32_bf16 v[30:33], v[186:189], v[202:205], v[30:33]
	v_mfma_f32_16x16x32_bf16 v[22:25], v[164:167], v[210:213], v[22:25]
	v_mfma_f32_16x16x32_bf16 v[14:17], v[186:189], v[210:213], v[14:17]
	v_mfma_f32_16x16x32_bf16 v[6:9], v[164:167], v[218:221], v[6:9]
	v_mfma_f32_16x16x32_bf16 v[2:5], v[186:189], v[218:221], v[2:5]
	v_mfma_f32_16x16x32_bf16 v[54:57], v[182:185], v[198:201], v[54:57]
	v_mfma_f32_16x16x32_bf16 v[46:49], v[190:193], v[198:201], v[46:49]
	v_mfma_f32_16x16x32_bf16 v[38:41], v[182:185], v[206:209], v[38:41]
	v_mfma_f32_16x16x32_bf16 v[30:33], v[190:193], v[206:209], v[30:33]
	v_mfma_f32_16x16x32_bf16 v[22:25], v[182:185], v[214:217], v[22:25]
	v_mfma_f32_16x16x32_bf16 v[14:17], v[190:193], v[214:217], v[14:17]
	v_mfma_f32_16x16x32_bf16 v[6:9], v[182:185], v[222:225], v[6:9]
	v_mfma_f32_16x16x32_bf16 v[2:5], v[190:193], v[222:225], v[2:5]
	s_setprio 0
	s_barrier
	s_cbranch_scc0 .LBB0_627
	s_and_b64 vcc, exec, s[12:13]
	s_cbranch_vccz .LBB0_630
	s_barrier

; #define PG8_STAGE(bufoff, gbase, voff) do { _Pragma("unroll") for (int _i = 0; _i < 2; ++_i) \
;         __builtin_amdgcn_global_load_lds((const unsigned*)((const char*)(gbase) + (voff)[_i]), (PG8_LAS unsigned*)(lds + (bufoff) + ldsw + _i * 8192), 16, 0, 0); } while (0)
; #define PG8_LDA(dst, b, h) do { _Pragma("unroll") for (int m = 0; m < 4; ++m) _Pragma("unroll") for (int k = 0; k < 2; ++k) dst[m][k] = *(const PG8_LAS bf16x8*)(lds + PG8_SA(b, h) + aoff + m * 2048 + k * 1024); } while (0)
; #define PG8_LDB(dst, b, h) do { _Pragma("unroll") for (int n = 0; n < 2; ++n) _Pragma("unroll") for (int k = 0; k < 2; ++k) dst[n][k] = *(const PG8_LAS bf16x8*)(lds + PG8_SB(b, h) + boff + n * 2048 + k * 1024); } while (0)
; #define PG8_MMA(ai, bj, At, Bt) do { __builtin_amdgcn_s_setprio(1); _Pragma("unroll") for (int m = 0; m < 4; ++m) _Pragma("unroll") for (int n = 0; n < 2; ++n) _Pragma("unroll") for (int k = 0; k < 2; ++k) \
;         acc[ai][bj][m][n] = __builtin_amdgcn_mfma_f32_16x16x32_bf16(Bt[n][k], At[m][k], acc[ai][bj][m][n], 0, 0, 0); __builtin_amdgcn_s_setprio(0); } while (0)
; #define PG8_WAIT_V(n) asm volatile("s_waitcnt vmcnt(" #n ")" ::: "memory")
; #define PG8_WAIT_L(n) asm volatile("s_waitcnt lgkmcnt(" #n ")" ::: "memory")
; template <class Epi, class Sched, bool ALIGN_EPI = false, bool SP2 = false>
; __device__ __forceinline__ void gemm_phase(PG8_LAS unsigned char* lds, const Gemm g, const Sched& S, const Epi& E, int tid_in) {
;     ...
;             const bool last = (t == nt - 2);
;             const char* a1 = cA + (size_t)(t + 1) * kstep;
;             const char* a2 = last ? nA : cA + (size_t)(t + 2) * kstep; const char* b2 = last ? nB : cB + (size_t)(t + 2) * kstep;
;             const char* a3 = a2 + kstep; const char* b3 = b2 + kstep;
;             if (last && has_next) S.a_ready(nxt);
;             if constexpr (SP2) {
;             PG8_LDB(B0, 0, 0); PG8_LDB(B1, 0, 1); PG8_SCHED; PG8_LDA(At, 0, 0); PG8_STAGE(PG8_SA(1, 1), a1 + hstepA, voffA);
;             PG8_WAIT_V(8); PG8_WAIT_L(0); PG8_BAR; PG8_MMA(0, 0, At, B0); PG8_MMA(0, 1, At, B1); PG8_BAR; PG8_SCHED;
;             PG8_LDA(At, 0, 1); PG8_STAGE(PG8_SB(0, 0), b2, voffB); PG8_STAGE(PG8_SB(0, 1), b2 + hstep, voffB); PG8_STAGE(PG8_SA(0, 0), a2, voffA);
;             PG8_WAIT_V(8); PG8_WAIT_L(0); PG8_BAR; PG8_MMA(1, 0, At, B0); PG8_MMA(1, 1, At, B1); PG8_BAR; PG8_SCHED;
.LBB0_900:
	v_add_u32_e32 v0, s4, v242
	ds_read_b128 v[132:135], v0
	ds_read_b128 v[144:147], v0 offset:1024
	ds_read_b128 v[148:151], v0 offset:2048
	ds_read_b128 v[152:155], v0 offset:3072
	v_add_u32_e32 v0, s5, v242
	ds_read_b128 v[156:159], v0
	ds_read_b128 v[160:163], v0 offset:1024
	ds_read_b128 v[164:167], v0 offset:2048
	ds_read_b128 v[182:185], v0 offset:3072
	s_add_i32 vcc_hi, s10, 2
	s_add_u32 s11, s8, 0xfffc0080
	s_addc_u32 s12, s9, -1
	s_cmp_eq_u32 s68, s10
	s_cselect_b32 s10, s47, s76
	s_cselect_b32 s13, s30, s12
	s_cselect_b32 s12, s31, s11
	s_cselect_b32 s11, s46, vcc_lo
	v_lshl_add_u64 v[2:3], s[8:9], 0, v[140:141]
	s_add_i32 m0, s37, 0xc000
	ds_read_b128 v[186:189], v243
	ds_read_b128 v[190:193], v243 offset:1024
	ds_read_b128 v[194:197], v243 offset:2048
	ds_read_b128 v[198:201], v243 offset:3072
	ds_read_b128 v[202:205], v243 offset:4096
	ds_read_b128 v[206:209], v243 offset:5120
	ds_read_b128 v[210:213], v243 offset:6144
	ds_read_b128 v[214:217], v243 offset:7168
	global_load_lds_dwordx4 v[2:3], off
	v_lshl_add_u64 v[2:3], s[8:9], 0, v[142:143]
	s_add_i32 m0, s37, 0xe000
	s_nop 0
	global_load_lds_dwordx4 v[2:3], off
	s_waitcnt vmcnt(8)
	s_waitcnt lgkmcnt(0)
	s_barrier
	s_setprio 1
	s_waitcnt lgkmcnt(0)
	v_mfma_f32_16x16x32_bf16 v[128:131], v[132:135], v[186:189], v[128:131]
	v_mfma_f32_16x16x32_bf16 v[124:127], v[148:151], v[186:189], v[124:127]
	v_mfma_f32_16x16x32_bf16 v[120:123], v[132:135], v[194:197], v[120:123]
	v_mfma_f32_16x16x32_bf16 v[116:119], v[148:151], v[194:197], v[116:119]
	v_mfma_f32_16x16x32_bf16 v[112:115], v[132:135], v[202:205], v[112:115]
	v_mfma_f32_16x16x32_bf16 v[108:111], v[148:151], v[202:205], v[108:111]
	v_mfma_f32_16x16x32_bf16 v[104:107], v[132:135], v[210:213], v[104:107]
	v_mfma_f32_16x16x32_bf16 v[100:103], v[148:151], v[210:213], v[100:103]
	v_mfma_f32_16x16x32_bf16 v[128:131], v[144:147], v[190:193], v[128:131]
	v_mfma_f32_16x16x32_bf16 v[124:127], v[152:155], v[190:193], v[124:127]
	v_mfma_f32_16x16x32_bf16 v[120:123], v[144:147], v[198:201], v[120:123]
	v_mfma_f32_16x16x32_bf16 v[116:119], v[152:155], v[198:201], v[116:119]
	v_mfma_f32_16x16x32_bf16 v[112:115], v[144:147], v[206:209], v[112:115]
	v_mfma_f32_16x16x32_bf16 v[108:111], v[152:155], v[206:209], v[108:111]
	v_mfma_f32_16x16x32_bf16 v[104:107], v[144:147], v[214:217], v[104:107]
	v_mfma_f32_16x16x32_bf16 v[100:103], v[152:155], v[214:217], v[100:103]
	s_setprio 0
	s_setprio 1
	v_mfma_f32_16x16x32_bf16 v[96:99], v[156:159], v[186:189], v[96:99]
	v_mfma_f32_16x16x32_bf16 v[92:95], v[164:167], v[186:189], v[92:95]
	v_mfma_f32_16x16x32_bf16 v[88:91], v[156:159], v[194:197], v[88:91]
	v_mfma_f32_16x16x32_bf16 v[84:87], v[164:167], v[194:197], v[84:87]
	v_mfma_f32_16x16x32_bf16 v[80:83], v[156:159], v[202:205], v[80:83]
	v_mfma_f32_16x16x32_bf16 v[76:79], v[164:167], v[202:205], v[76:79]
	v_mfma_f32_16x16x32_bf16 v[72:75], v[156:159], v[210:213], v[72:75]
	v_mfma_f32_16x16x32_bf16 v[68:71], v[164:167], v[210:213], v[68:71]
	v_mfma_f32_16x16x32_bf16 v[96:99], v[160:163], v[190:193], v[96:99]
	v_mfma_f32_16x16x32_bf16 v[92:95], v[182:185], v[190:193], v[92:95]
	v_mfma_f32_16x16x32_bf16 v[88:91], v[160:163], v[198:201], v[88:91]
	v_mfma_f32_16x16x32_bf16 v[84:87], v[182:185], v[198:201], v[84:87]
	v_mfma_f32_16x16x32_bf16 v[80:83], v[160:163], v[206:209], v[80:83]
	v_mfma_f32_16x16x32_bf16 v[76:79], v[182:185], v[206:209], v[76:79]
	v_mfma_f32_16x16x32_bf16 v[72:75], v[160:163], v[214:217], v[72:75]
	v_mfma_f32_16x16x32_bf16 v[68:71], v[182:185], v[214:217], v[68:71]
	s_setprio 0
	s_barrier
	s_add_i32 s64, s4, s36
	v_lshl_add_u64 v[168:169], s[10:11], 0, v[136:137]
	s_mov_b32 m0, s64
	ds_read_b128 v[186:189], v243 offset:16384
	ds_read_b128 v[190:193], v243 offset:17408
	ds_read_b128 v[194:197], v243 offset:18432
	ds_read_b128 v[198:201], v243 offset:19456
	ds_read_b128 v[202:205], v243 offset:20480
	ds_read_b128 v[206:209], v243 offset:21504
	ds_read_b128 v[210:213], v243 offset:22528
	ds_read_b128 v[214:217], v243 offset:23552
	global_load_lds_dwordx4 v[168:169], off
	s_add_i32 m0, s64, 0x2000
	s_add_u32 s64, s10, 0x40000
	v_lshl_add_u64 v[218:219], s[10:11], 0, v[138:139]
	s_addc_u32 s65, s11, 0
	s_add_i32 s95, s5, s36
	global_load_lds_dwordx4 v[218:219], off
	v_lshl_add_u64 v[2:3], s[64:65], 0, v[136:137]
	s_mov_b32 m0, s95
	v_lshl_add_u64 v[220:221], s[12:13], 0, v[136:137]
	global_load_lds_dwordx4 v[2:3], off
	v_lshl_add_u64 v[2:3], s[64:65], 0, v[138:139]
	s_add_i32 m0, s95, 0x2000
	v_lshl_add_u64 v[222:223], s[12:13], 0, v[138:139]
	global_load_lds_dwordx4 v[2:3], off
	s_waitcnt vmcnt(6)
	s_waitcnt lgkmcnt(0)
	s_barrier
; #define PG8_STAGE(bufoff, gbase, voff) do { _Pragma("unroll") for (int _i = 0; _i < 2; ++_i) \
;         __builtin_amdgcn_global_load_lds((const unsigned*)((const char*)(gbase) + (voff)[_i]), (PG8_LAS unsigned*)(lds + (bufoff) + ldsw + _i * 8192), 16, 0, 0); } while (0)
; #define PG8_LDA(dst, b, h) do { _Pragma("unroll") for (int m = 0; m < 4; ++m) _Pragma("unroll") for (int k = 0; k < 2; ++k) dst[m][k] = *(const PG8_LAS bf16x8*)(lds + PG8_SA(b, h) + aoff + m * 2048 + k * 1024); } while (0)
; #define PG8_LDB(dst, b, h) do { _Pragma("unroll") for (int n = 0; n < 2; ++n) _Pragma("unroll") for (int k = 0; k < 2; ++k) dst[n][k] = *(const PG8_LAS bf16x8*)(lds + PG8_SB(b, h) + boff + n * 2048 + k * 1024); } while (0)
; #define PG8_MMA(ai, bj, At, Bt) do { __builtin_amdgcn_s_setprio(1); _Pragma("unroll") for (int m = 0; m < 4; ++m) _Pragma("unroll") for (int n = 0; n < 2; ++n) _Pragma("unroll") for (int k = 0; k < 2; ++k) \
;         acc[ai][bj][m][n] = __builtin_amdgcn_mfma_f32_16x16x32_bf16(Bt[n][k], At[m][k], acc[ai][bj][m][n], 0, 0, 0); __builtin_amdgcn_s_setprio(0); } while (0)
; #define PG8_WAIT_V(n) asm volatile("s_waitcnt vmcnt(" #n ")" ::: "memory")
; #define PG8_WAIT_L(n) asm volatile("s_waitcnt lgkmcnt(" #n ")" ::: "memory")
; #define PG8_BAR __builtin_amdgcn_s_barrier()
; #define PG8_SCHED __builtin_amdgcn_sched_barrier(0)
; template <class Epi, class Sched, bool ALIGN_EPI = false, bool SP2 = false>
; __device__ __forceinline__ void gemm_phase(PG8_LAS unsigned char* lds, const Gemm g, const Sched& S, const Epi& E, int tid_in) {
;     ...
;             PG8_WAIT_V(8); PG8_WAIT_L(0); PG8_BAR; PG8_MMA(1, 0, At, B0); PG8_MMA(1, 1, At, B1); PG8_BAR; PG8_SCHED;
;             PG8_LDB(B0, 1, 0); PG8_LDB(B1, 1, 1); PG8_SCHED; PG8_LDA(At, 1, 0); PG8_STAGE(PG8_SA(0, 1), a2 + hstepA, voffA);
;             PG8_WAIT_V(8); PG8_WAIT_L(0); PG8_BAR; PG8_MMA(0, 0, At, B0); PG8_MMA(0, 1, At, B1); PG8_BAR; PG8_SCHED;
	s_setprio 1
	s_waitcnt lgkmcnt(0)
	v_mfma_f32_16x16x32_bf16 v[64:67], v[132:135], v[186:189], v[64:67]
	v_mfma_f32_16x16x32_bf16 v[60:63], v[148:151], v[186:189], v[60:63]
	v_mfma_f32_16x16x32_bf16 v[56:59], v[132:135], v[194:197], v[56:59]
	v_mfma_f32_16x16x32_bf16 v[52:55], v[148:151], v[194:197], v[52:55]
	v_mfma_f32_16x16x32_bf16 v[48:51], v[132:135], v[202:205], v[48:51]
	v_mfma_f32_16x16x32_bf16 v[44:47], v[148:151], v[202:205], v[44:47]
	v_mfma_f32_16x16x32_bf16 v[40:43], v[132:135], v[210:213], v[40:43]
	v_mfma_f32_16x16x32_bf16 v[36:39], v[148:151], v[210:213], v[36:39]
	v_mfma_f32_16x16x32_bf16 v[64:67], v[144:147], v[190:193], v[64:67]
	v_mfma_f32_16x16x32_bf16 v[60:63], v[152:155], v[190:193], v[60:63]
	v_mfma_f32_16x16x32_bf16 v[56:59], v[144:147], v[198:201], v[56:59]
	v_mfma_f32_16x16x32_bf16 v[52:55], v[152:155], v[198:201], v[52:55]
	v_mfma_f32_16x16x32_bf16 v[48:51], v[144:147], v[206:209], v[48:51]
	v_mfma_f32_16x16x32_bf16 v[44:47], v[152:155], v[206:209], v[44:47]
	v_mfma_f32_16x16x32_bf16 v[40:43], v[144:147], v[214:217], v[40:43]
	v_mfma_f32_16x16x32_bf16 v[36:39], v[152:155], v[214:217], v[36:39]
	s_setprio 0
	s_setprio 1
	v_mfma_f32_16x16x32_bf16 v[32:35], v[156:159], v[186:189], v[32:35]
	v_mfma_f32_16x16x32_bf16 v[28:31], v[164:167], v[186:189], v[28:31]
	v_mfma_f32_16x16x32_bf16 v[24:27], v[156:159], v[194:197], v[24:27]
	v_mfma_f32_16x16x32_bf16 v[20:23], v[164:167], v[194:197], v[20:23]
	v_mfma_f32_16x16x32_bf16 v[16:19], v[156:159], v[202:205], v[16:19]
	v_mfma_f32_16x16x32_bf16 v[12:15], v[164:167], v[202:205], v[12:15]
	v_mfma_f32_16x16x32_bf16 v[8:11], v[156:159], v[210:213], v[8:11]
	v_mfma_f32_16x16x32_bf16 v[2:5], v[164:167], v[210:213], v[4:7]
	v_mfma_f32_16x16x32_bf16 v[32:35], v[160:163], v[190:193], v[32:35]
	v_mfma_f32_16x16x32_bf16 v[28:31], v[182:185], v[190:193], v[28:31]
	v_mfma_f32_16x16x32_bf16 v[24:27], v[160:163], v[198:201], v[24:27]
	v_mfma_f32_16x16x32_bf16 v[20:23], v[182:185], v[198:201], v[20:23]
	v_mfma_f32_16x16x32_bf16 v[16:19], v[160:163], v[206:209], v[16:19]
	v_mfma_f32_16x16x32_bf16 v[12:15], v[182:185], v[206:209], v[12:15]
	v_mfma_f32_16x16x32_bf16 v[8:11], v[160:163], v[214:217], v[8:11]
	v_mfma_f32_16x16x32_bf16 v[2:5], v[182:185], v[214:217], v[2:5]
	s_setprio 0
	s_barrier
	s_mov_b32 m0, s37
	s_nop 0
	global_load_lds_dwordx4 v[220:221], off
	s_mov_b32 m0, s38
	s_nop 0
	global_load_lds_dwordx4 v[222:223], off
	v_add_u32_e32 v0, s63, v242
	ds_read_b128 v[132:135], v0
	ds_read_b128 v[144:147], v0 offset:1024
	ds_read_b128 v[148:151], v0 offset:2048
	ds_read_b128 v[152:155], v0 offset:3072
	v_add_u32_e32 v0, s55, v242
	ds_read_b128 v[156:159], v0
	ds_read_b128 v[160:163], v0 offset:1024
	ds_read_b128 v[164:167], v0 offset:2048
	ds_read_b128 v[182:185], v0 offset:3072
	s_add_u32 s12, s12, 0x40000
	s_addc_u32 s13, s13, 0
	s_mov_b32 m0, s39
	v_lshl_add_u64 v[6:7], s[12:13], 0, v[136:137]
	ds_read_b128 v[186:189], v243 offset:32768
	ds_read_b128 v[190:193], v243 offset:33792
	ds_read_b128 v[194:197], v243 offset:34816
	ds_read_b128 v[198:201], v243 offset:35840
	ds_read_b128 v[202:205], v243 offset:36864
	ds_read_b128 v[206:209], v243 offset:37888
	ds_read_b128 v[210:213], v243 offset:38912
	ds_read_b128 v[214:217], v243 offset:39936
	global_load_lds_dwordx4 v[6:7], off
	v_lshl_add_u64 v[6:7], s[12:13], 0, v[138:139]
	s_mov_b32 m0, s40
	s_nop 0
	global_load_lds_dwordx4 v[6:7], off
	s_waitcnt vmcnt(8)
	s_waitcnt lgkmcnt(0)
	s_barrier
	s_setprio 1
	s_waitcnt lgkmcnt(0)
	v_mfma_f32_16x16x32_bf16 v[128:131], v[132:135], v[186:189], v[128:131]
	v_mfma_f32_16x16x32_bf16 v[124:127], v[148:151], v[186:189], v[124:127]
	v_mfma_f32_16x16x32_bf16 v[120:123], v[132:135], v[194:197], v[120:123]
	v_mfma_f32_16x16x32_bf16 v[116:119], v[148:151], v[194:197], v[116:119]
	v_mfma_f32_16x16x32_bf16 v[112:115], v[132:135], v[202:205], v[112:115]
	v_mfma_f32_16x16x32_bf16 v[108:111], v[148:151], v[202:205], v[108:111]
	v_mfma_f32_16x16x32_bf16 v[104:107], v[132:135], v[210:213], v[104:107]
	v_mfma_f32_16x16x32_bf16 v[100:103], v[148:151], v[210:213], v[100:103]
	v_mfma_f32_16x16x32_bf16 v[128:131], v[144:147], v[190:193], v[128:131]
	v_mfma_f32_16x16x32_bf16 v[124:127], v[152:155], v[190:193], v[124:127]
	v_mfma_f32_16x16x32_bf16 v[120:123], v[144:147], v[198:201], v[120:123]
	v_mfma_f32_16x16x32_bf16 v[116:119], v[152:155], v[198:201], v[116:119]
	v_mfma_f32_16x16x32_bf16 v[112:115], v[144:147], v[206:209], v[112:115]
	v_mfma_f32_16x16x32_bf16 v[108:111], v[152:155], v[206:209], v[108:111]
	v_mfma_f32_16x16x32_bf16 v[104:107], v[144:147], v[214:217], v[104:107]
	v_mfma_f32_16x16x32_bf16 v[100:103], v[152:155], v[214:217], v[100:103]
	s_setprio 0
	s_setprio 1
	v_mfma_f32_16x16x32_bf16 v[96:99], v[156:159], v[186:189], v[96:99]
	v_mfma_f32_16x16x32_bf16 v[92:95], v[164:167], v[186:189], v[92:95]
	v_mfma_f32_16x16x32_bf16 v[88:91], v[156:159], v[194:197], v[88:91]
	v_mfma_f32_16x16x32_bf16 v[84:87], v[164:167], v[194:197], v[84:87]
	v_mfma_f32_16x16x32_bf16 v[80:83], v[156:159], v[202:205], v[80:83]
	v_mfma_f32_16x16x32_bf16 v[76:79], v[164:167], v[202:205], v[76:79]
	v_mfma_f32_16x16x32_bf16 v[72:75], v[156:159], v[210:213], v[72:75]
	v_mfma_f32_16x16x32_bf16 v[68:71], v[164:167], v[210:213], v[68:71]
	v_mfma_f32_16x16x32_bf16 v[96:99], v[160:163], v[190:193], v[96:99]
	v_mfma_f32_16x16x32_bf16 v[92:95], v[182:185], v[190:193], v[92:95]
	v_mfma_f32_16x16x32_bf16 v[88:91], v[160:163], v[198:201], v[88:91]
	v_mfma_f32_16x16x32_bf16 v[84:87], v[182:185], v[198:201], v[84:87]
	v_mfma_f32_16x16x32_bf16 v[80:83], v[160:163], v[206:209], v[80:83]
	v_mfma_f32_16x16x32_bf16 v[76:79], v[182:185], v[206:209], v[76:79]
	v_mfma_f32_16x16x32_bf16 v[72:75], v[160:163], v[214:217], v[72:75]
	v_mfma_f32_16x16x32_bf16 v[68:71], v[182:185], v[214:217], v[68:71]
	s_setprio 0
	s_barrier
; #define PG8_STAGE(bufoff, gbase, voff) do { _Pragma("unroll") for (int _i = 0; _i < 2; ++_i) \
;         __builtin_amdgcn_global_load_lds((const unsigned*)((const char*)(gbase) + (voff)[_i]), (PG8_LAS unsigned*)(lds + (bufoff) + ldsw + _i * 8192), 16, 0, 0); } while (0)
; #define PG8_LDA(dst, b, h) do { _Pragma("unroll") for (int m = 0; m < 4; ++m) _Pragma("unroll") for (int k = 0; k < 2; ++k) dst[m][k] = *(const PG8_LAS bf16x8*)(lds + PG8_SA(b, h) + aoff + m * 2048 + k * 1024); } while (0)
; #define PG8_WAIT_V(n) asm volatile("s_waitcnt vmcnt(" #n ")" ::: "memory")
; #define PG8_WAIT_L(n) asm volatile("s_waitcnt lgkmcnt(" #n ")" ::: "memory")
; #define PG8_BAR __builtin_amdgcn_s_barrier()
; template <class Epi, class Sched, bool ALIGN_EPI = false, bool SP2 = false>
; __device__ __forceinline__ void gemm_phase(PG8_LAS unsigned char* lds, const Gemm g, const Sched& S, const Epi& E, int tid_in) {
;     ...
;         for (int t = 0; t < nt; t += 2) {
;             const bool last = (t == nt - 2);
;             const char* a1 = cA + (size_t)(t + 1) * kstep;
;             const char* a2 = last ? nA : cA + (size_t)(t + 2) * kstep; const char* b2 = last ? nB : cB + (size_t)(t + 2) * kstep;
;             const char* a3 = a2 + kstep; const char* b3 = b2 + kstep;
;             if (last && has_next) S.a_ready(nxt);
;             if constexpr (SP2) {
;             PG8_LDB(B0, 0, 0); PG8_LDB(B1, 0, 1); PG8_SCHED; PG8_LDA(At, 0, 0); PG8_STAGE(PG8_SA(1, 1), a1 + hstepA, voffA);
;             PG8_WAIT_V(8); PG8_WAIT_L(0); PG8_BAR; PG8_MMA(0, 0, At, B0); PG8_MMA(0, 1, At, B1); PG8_BAR; PG8_SCHED;
;             PG8_LDA(At, 0, 1); PG8_STAGE(PG8_SB(0, 0), b2, voffB); PG8_STAGE(PG8_SB(0, 1), b2 + hstep, voffB); PG8_STAGE(PG8_SA(0, 0), a2, voffA);
;             PG8_WAIT_V(8); PG8_WAIT_L(0); PG8_BAR; PG8_MMA(1, 0, At, B0); PG8_MMA(1, 1, At, B1); PG8_BAR; PG8_SCHED;
;             PG8_LDB(B0, 1, 0); PG8_LDB(B1, 1, 1); PG8_SCHED; PG8_LDA(At, 1, 0); PG8_STAGE(PG8_SA(0, 1), a2 + hstepA, voffA);
;             PG8_WAIT_V(8); PG8_WAIT_L(0); PG8_BAR; PG8_MMA(0, 0, At, B0); PG8_MMA(0, 1, At, B1); PG8_BAR; PG8_SCHED;
;             PG8_LDA(At, 1, 1); PG8_STAGE(PG8_SB(1, 0), b3, voffB); PG8_STAGE(PG8_SB(1, 1), b3 + hstep, voffB); PG8_STAGE(PG8_SA(1, 0), a3, voffA);
;             PG8_WAIT_V(8); PG8_WAIT_L(0); PG8_BAR; PG8_MMA(1, 0, At, B0); PG8_MMA(1, 1, At, B1); PG8_BAR; PG8_SCHED;
	s_add_i32 s12, s63, s36
	v_lshl_add_u64 v[6:7], v[168:169], 0, s[90:91]
	s_mov_b32 m0, s12
	ds_read_b128 v[186:189], v243 offset:49152
	ds_read_b128 v[190:193], v243 offset:50176
	ds_read_b128 v[194:197], v243 offset:51200
	ds_read_b128 v[198:201], v243 offset:52224
	ds_read_b128 v[202:205], v243 offset:53248
	ds_read_b128 v[206:209], v243 offset:54272
	ds_read_b128 v[210:213], v243 offset:55296
	ds_read_b128 v[214:217], v243 offset:56320
	global_load_lds_dwordx4 v[6:7], off
	s_add_i32 m0, s12, 0x2000
	s_add_u32 s10, s10, 0x40080
	v_lshl_add_u64 v[6:7], v[218:219], 0, s[90:91]
	s_addc_u32 s11, s11, 0
	s_add_i32 s12, s55, s36
	global_load_lds_dwordx4 v[6:7], off
	v_lshl_add_u64 v[6:7], s[10:11], 0, v[136:137]
	s_mov_b32 m0, s12
	s_nop 0
	global_load_lds_dwordx4 v[6:7], off
	v_lshl_add_u64 v[6:7], s[10:11], 0, v[138:139]
	s_add_i32 m0, s12, 0x2000
	s_nop 0
	global_load_lds_dwordx4 v[6:7], off
	v_lshl_add_u64 v[6:7], v[220:221], 0, s[90:91]
	s_mov_b32 m0, s49
	s_nop 0
	global_load_lds_dwordx4 v[6:7], off
	v_lshl_add_u64 v[6:7], v[222:223], 0, s[90:91]
	s_mov_b32 m0, s79
	s_nop 0
	global_load_lds_dwordx4 v[6:7], off
	s_add_u32 s8, s8, 0x100
	s_addc_u32 s9, s9, 0
	s_add_u32 s76, s76, 0x100
	s_addc_u32 vcc_lo, vcc_lo, 0
	s_cmp_ge_i32 vcc_hi, s14
	s_mov_b32 s10, vcc_hi
	s_waitcnt vmcnt(8)
	s_waitcnt lgkmcnt(0)
	s_barrier
	s_setprio 1
	s_waitcnt lgkmcnt(0)
	v_mfma_f32_16x16x32_bf16 v[64:67], v[132:135], v[186:189], v[64:67]
	v_mfma_f32_16x16x32_bf16 v[60:63], v[148:151], v[186:189], v[60:63]
	v_mfma_f32_16x16x32_bf16 v[56:59], v[132:135], v[194:197], v[56:59]
	v_mfma_f32_16x16x32_bf16 v[52:55], v[148:151], v[194:197], v[52:55]
	v_mfma_f32_16x16x32_bf16 v[48:51], v[132:135], v[202:205], v[48:51]
	v_mfma_f32_16x16x32_bf16 v[44:47], v[148:151], v[202:205], v[44:47]
	v_mfma_f32_16x16x32_bf16 v[40:43], v[132:135], v[210:213], v[40:43]
	v_mfma_f32_16x16x32_bf16 v[36:39], v[148:151], v[210:213], v[36:39]
	v_mfma_f32_16x16x32_bf16 v[64:67], v[144:147], v[190:193], v[64:67]
	v_mfma_f32_16x16x32_bf16 v[60:63], v[152:155], v[190:193], v[60:63]
	v_mfma_f32_16x16x32_bf16 v[56:59], v[144:147], v[198:201], v[56:59]
	v_mfma_f32_16x16x32_bf16 v[52:55], v[152:155], v[198:201], v[52:55]
	v_mfma_f32_16x16x32_bf16 v[48:51], v[144:147], v[206:209], v[48:51]
	v_mfma_f32_16x16x32_bf16 v[44:47], v[152:155], v[206:209], v[44:47]
	v_mfma_f32_16x16x32_bf16 v[40:43], v[144:147], v[214:217], v[40:43]
	v_mfma_f32_16x16x32_bf16 v[36:39], v[152:155], v[214:217], v[36:39]
	s_setprio 0
	s_setprio 1
	v_mfma_f32_16x16x32_bf16 v[32:35], v[156:159], v[186:189], v[32:35]
	v_mfma_f32_16x16x32_bf16 v[28:31], v[164:167], v[186:189], v[28:31]
	v_mfma_f32_16x16x32_bf16 v[24:27], v[156:159], v[194:197], v[24:27]
	v_mfma_f32_16x16x32_bf16 v[20:23], v[164:167], v[194:197], v[20:23]
	v_mfma_f32_16x16x32_bf16 v[16:19], v[156:159], v[202:205], v[16:19]
	v_mfma_f32_16x16x32_bf16 v[12:15], v[164:167], v[202:205], v[12:15]
	v_mfma_f32_16x16x32_bf16 v[6:9], v[156:159], v[210:213], v[8:11]
	v_mfma_f32_16x16x32_bf16 v[2:5], v[164:167], v[210:213], v[2:5]
	v_mfma_f32_16x16x32_bf16 v[32:35], v[160:163], v[190:193], v[32:35]
	v_mfma_f32_16x16x32_bf16 v[28:31], v[182:185], v[190:193], v[28:31]
	v_mfma_f32_16x16x32_bf16 v[24:27], v[160:163], v[198:201], v[24:27]
	v_mfma_f32_16x16x32_bf16 v[20:23], v[182:185], v[198:201], v[20:23]
	v_mfma_f32_16x16x32_bf16 v[16:19], v[160:163], v[206:209], v[16:19]
	v_mfma_f32_16x16x32_bf16 v[12:15], v[182:185], v[206:209], v[12:15]
	v_mfma_f32_16x16x32_bf16 v[8:11], v[160:163], v[214:217], v[6:9]
	v_mfma_f32_16x16x32_bf16 v[4:7], v[182:185], v[214:217], v[2:5]
	s_setprio 0
	s_barrier
	s_cbranch_scc0 .LBB0_900
	s_and_b64 vcc, exec, s[18:19]
	s_cbranch_vccz .LBB0_903
	s_barrier

; #define PG8_STAGE(bufoff, gbase, voff) do { _Pragma("unroll") for (int _i = 0; _i < 2; ++_i) \
;         __builtin_amdgcn_global_load_lds((const unsigned*)((const char*)(gbase) + (voff)[_i]), (PG8_LAS unsigned*)(lds + (bufoff) + ldsw + _i * 8192), 16, 0, 0); } while (0)
; #define PG8_LDA(dst, b, h) do { _Pragma("unroll") for (int m = 0; m < 4; ++m) _Pragma("unroll") for (int k = 0; k < 2; ++k) dst[m][k] = *(const PG8_LAS bf16x8*)(lds + PG8_SA(b, h) + aoff + m * 2048 + k * 1024); } while (0)
; #define PG8_LDB(dst, b, h) do { _Pragma("unroll") for (int n = 0; n < 2; ++n) _Pragma("unroll") for (int k = 0; k < 2; ++k) dst[n][k] = *(const PG8_LAS bf16x8*)(lds + PG8_SB(b, h) + boff + n * 2048 + k * 1024); } while (0)
; #define PG8_MMA(ai, bj, At, Bt) do { __builtin_amdgcn_s_setprio(1); _Pragma("unroll") for (int m = 0; m < 4; ++m) _Pragma("unroll") for (int n = 0; n < 2; ++n) _Pragma("unroll") for (int k = 0; k < 2; ++k) \
;         acc[ai][bj][m][n] = __builtin_amdgcn_mfma_f32_16x16x32_bf16(Bt[n][k], At[m][k], acc[ai][bj][m][n], 0, 0, 0); __builtin_amdgcn_s_setprio(0); } while (0)
; #define PG8_WAIT_V(n) asm volatile("s_waitcnt vmcnt(" #n ")" ::: "memory")
; #define PG8_WAIT_L(n) asm volatile("s_waitcnt lgkmcnt(" #n ")" ::: "memory")
; template <class Epi, class Sched, bool ALIGN_EPI = false, bool SP2 = false>
; __device__ __forceinline__ void gemm_phase(PG8_LAS unsigned char* lds, const Gemm g, const Sched& S, const Epi& E, int tid_in) {
;     ...
;             const bool last = (t == nt - 2);
;             const char* a1 = cA + (size_t)(t + 1) * kstep;
;             const char* a2 = last ? nA : cA + (size_t)(t + 2) * kstep; const char* b2 = last ? nB : cB + (size_t)(t + 2) * kstep;
;             const char* a3 = a2 + kstep; const char* b3 = b2 + kstep;
;             if (last && has_next) S.a_ready(nxt);
;             if constexpr (SP2) {
;             PG8_LDB(B0, 0, 0); PG8_LDB(B1, 0, 1); PG8_SCHED; PG8_LDA(At, 0, 0); PG8_STAGE(PG8_SA(1, 1), a1 + hstepA, voffA);
;             PG8_WAIT_V(8); PG8_WAIT_L(0); PG8_BAR; PG8_MMA(0, 0, At, B0); PG8_MMA(0, 1, At, B1); PG8_BAR; PG8_SCHED;
;             PG8_LDA(At, 0, 1); PG8_STAGE(PG8_SB(0, 0), b2, voffB); PG8_STAGE(PG8_SB(0, 1), b2 + hstep, voffB); PG8_STAGE(PG8_SA(0, 0), a2, voffA);
;             PG8_WAIT_V(8); PG8_WAIT_L(0); PG8_BAR; PG8_MMA(1, 0, At, B0); PG8_MMA(1, 1, At, B1); PG8_BAR; PG8_SCHED;
.LBB0_1348:
	v_add_u32_e32 v152, s4, v146
	v_add_u32_e32 v168, s5, v146
	ds_read_b128 v[136:139], v152
	ds_read_b128 v[140:143], v152 offset:1024
	ds_read_b128 v[148:151], v152 offset:2048
	ds_read_b128 v[152:155], v152 offset:3072
	ds_read_b128 v[156:159], v168
	ds_read_b128 v[160:163], v168 offset:1024
	ds_read_b128 v[164:167], v168 offset:2048
	ds_read_b128 v[182:185], v168 offset:3072
	s_add_i32 s76, s26, 2
	s_add_u32 s27, s24, 0xfff80080
	s_addc_u32 s28, s25, -1
	s_cmp_eq_u32 s67, s26
	s_cselect_b32 s26, s66, s68
	s_cselect_b32 s29, s46, s28
	s_cselect_b32 s28, s47, s27
	s_cselect_b32 s27, s49, s70
	v_lshl_add_u64 v[168:169], s[24:25], 0, v[132:133]
	s_add_i32 m0, s31, 0xc000
	ds_read_b128 v[186:189], v147
	ds_read_b128 v[190:193], v147 offset:1024
	ds_read_b128 v[194:197], v147 offset:2048
	ds_read_b128 v[198:201], v147 offset:3072
	ds_read_b128 v[202:205], v147 offset:4096
	ds_read_b128 v[206:209], v147 offset:5120
	ds_read_b128 v[210:213], v147 offset:6144
	ds_read_b128 v[214:217], v147 offset:7168
	global_load_lds_dwordx4 v[168:169], off
	v_lshl_add_u64 v[168:169], s[24:25], 0, v[134:135]
	s_add_i32 m0, s31, 0xe000
	s_nop 0
	global_load_lds_dwordx4 v[168:169], off
	s_waitcnt vmcnt(8)
	s_waitcnt lgkmcnt(0)
	s_barrier
	s_setprio 1
	s_waitcnt lgkmcnt(0)
	v_mfma_f32_16x16x32_bf16 v[126:129], v[136:139], v[186:189], v[126:129]
	v_mfma_f32_16x16x32_bf16 v[122:125], v[148:151], v[186:189], v[122:125]
	v_mfma_f32_16x16x32_bf16 v[118:121], v[136:139], v[194:197], v[118:121]
	v_mfma_f32_16x16x32_bf16 v[114:117], v[148:151], v[194:197], v[114:117]
	v_mfma_f32_16x16x32_bf16 v[110:113], v[136:139], v[202:205], v[110:113]
	v_mfma_f32_16x16x32_bf16 v[106:109], v[148:151], v[202:205], v[106:109]
	v_mfma_f32_16x16x32_bf16 v[102:105], v[136:139], v[210:213], v[102:105]
	v_mfma_f32_16x16x32_bf16 v[98:101], v[148:151], v[210:213], v[98:101]
	v_mfma_f32_16x16x32_bf16 v[126:129], v[140:143], v[190:193], v[126:129]
	v_mfma_f32_16x16x32_bf16 v[122:125], v[152:155], v[190:193], v[122:125]
	v_mfma_f32_16x16x32_bf16 v[118:121], v[140:143], v[198:201], v[118:121]
	v_mfma_f32_16x16x32_bf16 v[114:117], v[152:155], v[198:201], v[114:117]
	v_mfma_f32_16x16x32_bf16 v[110:113], v[140:143], v[206:209], v[110:113]
	v_mfma_f32_16x16x32_bf16 v[106:109], v[152:155], v[206:209], v[106:109]
	v_mfma_f32_16x16x32_bf16 v[102:105], v[140:143], v[214:217], v[102:105]
	v_mfma_f32_16x16x32_bf16 v[98:101], v[152:155], v[214:217], v[98:101]
	s_setprio 0
	s_setprio 1
	v_mfma_f32_16x16x32_bf16 v[94:97], v[156:159], v[186:189], v[94:97]
	v_mfma_f32_16x16x32_bf16 v[90:93], v[164:167], v[186:189], v[90:93]
	v_mfma_f32_16x16x32_bf16 v[86:89], v[156:159], v[194:197], v[86:89]
	v_mfma_f32_16x16x32_bf16 v[82:85], v[164:167], v[194:197], v[82:85]
	v_mfma_f32_16x16x32_bf16 v[78:81], v[156:159], v[202:205], v[78:81]
	v_mfma_f32_16x16x32_bf16 v[74:77], v[164:167], v[202:205], v[74:77]
	v_mfma_f32_16x16x32_bf16 v[70:73], v[156:159], v[210:213], v[70:73]
	v_mfma_f32_16x16x32_bf16 v[66:69], v[164:167], v[210:213], v[66:69]
	v_mfma_f32_16x16x32_bf16 v[94:97], v[160:163], v[190:193], v[94:97]
	v_mfma_f32_16x16x32_bf16 v[90:93], v[182:185], v[190:193], v[90:93]
	v_mfma_f32_16x16x32_bf16 v[86:89], v[160:163], v[198:201], v[86:89]
	v_mfma_f32_16x16x32_bf16 v[82:85], v[182:185], v[198:201], v[82:85]
	v_mfma_f32_16x16x32_bf16 v[78:81], v[160:163], v[206:209], v[78:81]
	v_mfma_f32_16x16x32_bf16 v[74:77], v[182:185], v[206:209], v[74:77]
	v_mfma_f32_16x16x32_bf16 v[70:73], v[160:163], v[214:217], v[70:73]
	v_mfma_f32_16x16x32_bf16 v[66:69], v[182:185], v[214:217], v[66:69]
	s_setprio 0
	s_barrier
	s_add_i32 s64, s4, s30
	v_lshl_add_u64 v[168:169], s[26:27], 0, v[0:1]
	s_mov_b32 m0, s64
	ds_read_b128 v[186:189], v147 offset:16384
	ds_read_b128 v[190:193], v147 offset:17408
	ds_read_b128 v[194:197], v147 offset:18432
	ds_read_b128 v[198:201], v147 offset:19456
	ds_read_b128 v[202:205], v147 offset:20480
	ds_read_b128 v[206:209], v147 offset:21504
	ds_read_b128 v[210:213], v147 offset:22528
	ds_read_b128 v[214:217], v147 offset:23552
	global_load_lds_dwordx4 v[168:169], off
	s_add_i32 m0, s64, 0x2000
	s_add_u32 s64, s26, 0x80000
	v_lshl_add_u64 v[218:219], s[26:27], 0, v[130:131]
	s_addc_u32 s65, s27, 0
	s_add_i32 s79, s5, s30
	global_load_lds_dwordx4 v[218:219], off
	v_lshl_add_u64 v[220:221], s[64:65], 0, v[0:1]
	s_mov_b32 m0, s79
	v_lshl_add_u64 v[222:223], s[28:29], 0, v[130:131]
	global_load_lds_dwordx4 v[220:221], off
	v_lshl_add_u64 v[220:221], s[64:65], 0, v[130:131]
	s_add_i32 m0, s79, 0x2000
	s_nop 0
	global_load_lds_dwordx4 v[220:221], off
	s_waitcnt vmcnt(6)
	s_waitcnt lgkmcnt(0)
	s_barrier
; #define PG8_STAGE(bufoff, gbase, voff) do { _Pragma("unroll") for (int _i = 0; _i < 2; ++_i) \
;         __builtin_amdgcn_global_load_lds((const unsigned*)((const char*)(gbase) + (voff)[_i]), (PG8_LAS unsigned*)(lds + (bufoff) + ldsw + _i * 8192), 16, 0, 0); } while (0)
; #define PG8_LDA(dst, b, h) do { _Pragma("unroll") for (int m = 0; m < 4; ++m) _Pragma("unroll") for (int k = 0; k < 2; ++k) dst[m][k] = *(const PG8_LAS bf16x8*)(lds + PG8_SA(b, h) + aoff + m * 2048 + k * 1024); } while (0)
; #define PG8_LDB(dst, b, h) do { _Pragma("unroll") for (int n = 0; n < 2; ++n) _Pragma("unroll") for (int k = 0; k < 2; ++k) dst[n][k] = *(const PG8_LAS bf16x8*)(lds + PG8_SB(b, h) + boff + n * 2048 + k * 1024); } while (0)
; #define PG8_MMA(ai, bj, At, Bt) do { __builtin_amdgcn_s_setprio(1); _Pragma("unroll") for (int m = 0; m < 4; ++m) _Pragma("unroll") for (int n = 0; n < 2; ++n) _Pragma("unroll") for (int k = 0; k < 2; ++k) \
;         acc[ai][bj][m][n] = __builtin_amdgcn_mfma_f32_16x16x32_bf16(Bt[n][k], At[m][k], acc[ai][bj][m][n], 0, 0, 0); __builtin_amdgcn_s_setprio(0); } while (0)
; #define PG8_WAIT_V(n) asm volatile("s_waitcnt vmcnt(" #n ")" ::: "memory")
; #define PG8_WAIT_L(n) asm volatile("s_waitcnt lgkmcnt(" #n ")" ::: "memory")
; #define PG8_BAR __builtin_amdgcn_s_barrier()
; #define PG8_SCHED __builtin_amdgcn_sched_barrier(0)
; template <class Epi, class Sched, bool ALIGN_EPI = false, bool SP2 = false>
; __device__ __forceinline__ void gemm_phase(PG8_LAS unsigned char* lds, const Gemm g, const Sched& S, const Epi& E, int tid_in) {
;     ...
;             PG8_WAIT_V(8); PG8_WAIT_L(0); PG8_BAR; PG8_MMA(1, 0, At, B0); PG8_MMA(1, 1, At, B1); PG8_BAR; PG8_SCHED;
;             PG8_LDB(B0, 1, 0); PG8_LDB(B1, 1, 1); PG8_SCHED; PG8_LDA(At, 1, 0); PG8_STAGE(PG8_SA(0, 1), a2 + hstepA, voffA);
;             PG8_WAIT_V(8); PG8_WAIT_L(0); PG8_BAR; PG8_MMA(0, 0, At, B0); PG8_MMA(0, 1, At, B1); PG8_BAR; PG8_SCHED;
	s_setprio 1
	s_waitcnt lgkmcnt(0)
	v_mfma_f32_16x16x32_bf16 v[62:65], v[136:139], v[186:189], v[62:65]
	v_mfma_f32_16x16x32_bf16 v[58:61], v[148:151], v[186:189], v[58:61]
	v_mfma_f32_16x16x32_bf16 v[54:57], v[136:139], v[194:197], v[54:57]
	v_mfma_f32_16x16x32_bf16 v[50:53], v[148:151], v[194:197], v[50:53]
	v_mfma_f32_16x16x32_bf16 v[46:49], v[136:139], v[202:205], v[46:49]
	v_mfma_f32_16x16x32_bf16 v[42:45], v[148:151], v[202:205], v[42:45]
	v_mfma_f32_16x16x32_bf16 v[38:41], v[136:139], v[210:213], v[38:41]
	v_mfma_f32_16x16x32_bf16 v[34:37], v[148:151], v[210:213], v[34:37]
	v_mfma_f32_16x16x32_bf16 v[62:65], v[140:143], v[190:193], v[62:65]
	v_mfma_f32_16x16x32_bf16 v[58:61], v[152:155], v[190:193], v[58:61]
	v_mfma_f32_16x16x32_bf16 v[54:57], v[140:143], v[198:201], v[54:57]
	v_mfma_f32_16x16x32_bf16 v[50:53], v[152:155], v[198:201], v[50:53]
	v_mfma_f32_16x16x32_bf16 v[46:49], v[140:143], v[206:209], v[46:49]
	v_mfma_f32_16x16x32_bf16 v[42:45], v[152:155], v[206:209], v[42:45]
	v_mfma_f32_16x16x32_bf16 v[38:41], v[140:143], v[214:217], v[38:41]
	v_mfma_f32_16x16x32_bf16 v[34:37], v[152:155], v[214:217], v[34:37]
	s_setprio 0
	s_setprio 1
	v_mfma_f32_16x16x32_bf16 v[30:33], v[156:159], v[186:189], v[30:33]
	v_mfma_f32_16x16x32_bf16 v[26:29], v[164:167], v[186:189], v[26:29]
	v_mfma_f32_16x16x32_bf16 v[22:25], v[156:159], v[194:197], v[22:25]
	v_mfma_f32_16x16x32_bf16 v[18:21], v[164:167], v[194:197], v[18:21]
	v_mfma_f32_16x16x32_bf16 v[14:17], v[156:159], v[202:205], v[14:17]
	v_mfma_f32_16x16x32_bf16 v[10:13], v[164:167], v[202:205], v[10:13]
	v_mfma_f32_16x16x32_bf16 v[6:9], v[156:159], v[210:213], v[6:9]
	v_mfma_f32_16x16x32_bf16 v[2:5], v[164:167], v[210:213], v[2:5]
	v_mfma_f32_16x16x32_bf16 v[30:33], v[160:163], v[190:193], v[30:33]
	v_mfma_f32_16x16x32_bf16 v[26:29], v[182:185], v[190:193], v[26:29]
	v_mfma_f32_16x16x32_bf16 v[22:25], v[160:163], v[198:201], v[22:25]
	v_mfma_f32_16x16x32_bf16 v[18:21], v[182:185], v[198:201], v[18:21]
	v_mfma_f32_16x16x32_bf16 v[14:17], v[160:163], v[206:209], v[14:17]
	v_mfma_f32_16x16x32_bf16 v[10:13], v[182:185], v[206:209], v[10:13]
	v_mfma_f32_16x16x32_bf16 v[6:9], v[160:163], v[214:217], v[6:9]
	v_mfma_f32_16x16x32_bf16 v[2:5], v[182:185], v[214:217], v[2:5]
	s_setprio 0
	s_barrier
	v_lshl_add_u64 v[220:221], s[28:29], 0, v[0:1]
	s_mov_b32 m0, s31
	s_nop 0
	global_load_lds_dwordx4 v[220:221], off
	s_mov_b32 m0, s33
	s_nop 0
	global_load_lds_dwordx4 v[222:223], off
	v_add_u32_e32 v152, s63, v146
	v_add_u32_e32 v182, s55, v146
	ds_read_b128 v[136:139], v152
	ds_read_b128 v[140:143], v152 offset:1024
	ds_read_b128 v[148:151], v152 offset:2048
	ds_read_b128 v[152:155], v152 offset:3072
	ds_read_b128 v[156:159], v182
	ds_read_b128 v[160:163], v182 offset:1024
	ds_read_b128 v[164:167], v182 offset:2048
	ds_read_b128 v[182:185], v182 offset:3072
	s_add_u32 s28, s28, 0x80000
	s_addc_u32 s29, s29, 0
	s_mov_b32 m0, s34
	v_lshl_add_u64 v[224:225], s[28:29], 0, v[0:1]
	ds_read_b128 v[186:189], v147 offset:32768
	ds_read_b128 v[190:193], v147 offset:33792
	ds_read_b128 v[194:197], v147 offset:34816
	ds_read_b128 v[198:201], v147 offset:35840
	ds_read_b128 v[202:205], v147 offset:36864
	ds_read_b128 v[206:209], v147 offset:37888
	ds_read_b128 v[210:213], v147 offset:38912
	ds_read_b128 v[214:217], v147 offset:39936
	global_load_lds_dwordx4 v[224:225], off
	v_lshl_add_u64 v[224:225], s[28:29], 0, v[130:131]
	s_mov_b32 m0, s35
	s_nop 0
	global_load_lds_dwordx4 v[224:225], off
	s_waitcnt vmcnt(8)
	s_waitcnt lgkmcnt(0)
	s_barrier
	s_setprio 1
	s_waitcnt lgkmcnt(0)
	v_mfma_f32_16x16x32_bf16 v[126:129], v[136:139], v[186:189], v[126:129]
	v_mfma_f32_16x16x32_bf16 v[122:125], v[148:151], v[186:189], v[122:125]
	v_mfma_f32_16x16x32_bf16 v[118:121], v[136:139], v[194:197], v[118:121]
	v_mfma_f32_16x16x32_bf16 v[114:117], v[148:151], v[194:197], v[114:117]
	v_mfma_f32_16x16x32_bf16 v[110:113], v[136:139], v[202:205], v[110:113]
	v_mfma_f32_16x16x32_bf16 v[106:109], v[148:151], v[202:205], v[106:109]
	v_mfma_f32_16x16x32_bf16 v[102:105], v[136:139], v[210:213], v[102:105]
	v_mfma_f32_16x16x32_bf16 v[98:101], v[148:151], v[210:213], v[98:101]
	v_mfma_f32_16x16x32_bf16 v[126:129], v[140:143], v[190:193], v[126:129]
	v_mfma_f32_16x16x32_bf16 v[122:125], v[152:155], v[190:193], v[122:125]
	v_mfma_f32_16x16x32_bf16 v[118:121], v[140:143], v[198:201], v[118:121]
	v_mfma_f32_16x16x32_bf16 v[114:117], v[152:155], v[198:201], v[114:117]
	v_mfma_f32_16x16x32_bf16 v[110:113], v[140:143], v[206:209], v[110:113]
	v_mfma_f32_16x16x32_bf16 v[106:109], v[152:155], v[206:209], v[106:109]
	v_mfma_f32_16x16x32_bf16 v[102:105], v[140:143], v[214:217], v[102:105]
	v_mfma_f32_16x16x32_bf16 v[98:101], v[152:155], v[214:217], v[98:101]
	s_setprio 0
	s_setprio 1
	v_mfma_f32_16x16x32_bf16 v[94:97], v[156:159], v[186:189], v[94:97]
	v_mfma_f32_16x16x32_bf16 v[90:93], v[164:167], v[186:189], v[90:93]
	v_mfma_f32_16x16x32_bf16 v[86:89], v[156:159], v[194:197], v[86:89]
	v_mfma_f32_16x16x32_bf16 v[82:85], v[164:167], v[194:197], v[82:85]
	v_mfma_f32_16x16x32_bf16 v[78:81], v[156:159], v[202:205], v[78:81]
	v_mfma_f32_16x16x32_bf16 v[74:77], v[164:167], v[202:205], v[74:77]
	v_mfma_f32_16x16x32_bf16 v[70:73], v[156:159], v[210:213], v[70:73]
	v_mfma_f32_16x16x32_bf16 v[66:69], v[164:167], v[210:213], v[66:69]
	v_mfma_f32_16x16x32_bf16 v[94:97], v[160:163], v[190:193], v[94:97]
	v_mfma_f32_16x16x32_bf16 v[90:93], v[182:185], v[190:193], v[90:93]
	v_mfma_f32_16x16x32_bf16 v[86:89], v[160:163], v[198:201], v[86:89]
	v_mfma_f32_16x16x32_bf16 v[82:85], v[182:185], v[198:201], v[82:85]
	v_mfma_f32_16x16x32_bf16 v[78:81], v[160:163], v[206:209], v[78:81]
	v_mfma_f32_16x16x32_bf16 v[74:77], v[182:185], v[206:209], v[74:77]
	v_mfma_f32_16x16x32_bf16 v[70:73], v[160:163], v[214:217], v[70:73]
	v_mfma_f32_16x16x32_bf16 v[66:69], v[182:185], v[214:217], v[66:69]
	s_setprio 0
	s_barrier
; #define PG8_STAGE(bufoff, gbase, voff) do { _Pragma("unroll") for (int _i = 0; _i < 2; ++_i) \
;         __builtin_amdgcn_global_load_lds((const unsigned*)((const char*)(gbase) + (voff)[_i]), (PG8_LAS unsigned*)(lds + (bufoff) + ldsw + _i * 8192), 16, 0, 0); } while (0)
; #define PG8_LDA(dst, b, h) do { _Pragma("unroll") for (int m = 0; m < 4; ++m) _Pragma("unroll") for (int k = 0; k < 2; ++k) dst[m][k] = *(const PG8_LAS bf16x8*)(lds + PG8_SA(b, h) + aoff + m * 2048 + k * 1024); } while (0)
; #define PG8_WAIT_V(n) asm volatile("s_waitcnt vmcnt(" #n ")" ::: "memory")
; #define PG8_WAIT_L(n) asm volatile("s_waitcnt lgkmcnt(" #n ")" ::: "memory")
; #define PG8_BAR __builtin_amdgcn_s_barrier()
; template <class Epi, class Sched, bool ALIGN_EPI = false, bool SP2 = false>
; __device__ __forceinline__ void gemm_phase(PG8_LAS unsigned char* lds, const Gemm g, const Sched& S, const Epi& E, int tid_in) {
;     ...
;         for (int t = 0; t < nt; t += 2) {
;             const bool last = (t == nt - 2);
;             const char* a1 = cA + (size_t)(t + 1) * kstep;
;             const char* a2 = last ? nA : cA + (size_t)(t + 2) * kstep; const char* b2 = last ? nB : cB + (size_t)(t + 2) * kstep;
;             const char* a3 = a2 + kstep; const char* b3 = b2 + kstep;
;             if (last && has_next) S.a_ready(nxt);
;             if constexpr (SP2) {
;             PG8_LDB(B0, 0, 0); PG8_LDB(B1, 0, 1); PG8_SCHED; PG8_LDA(At, 0, 0); PG8_STAGE(PG8_SA(1, 1), a1 + hstepA, voffA);
;             PG8_WAIT_V(8); PG8_WAIT_L(0); PG8_BAR; PG8_MMA(0, 0, At, B0); PG8_MMA(0, 1, At, B1); PG8_BAR; PG8_SCHED;
;             PG8_LDA(At, 0, 1); PG8_STAGE(PG8_SB(0, 0), b2, voffB); PG8_STAGE(PG8_SB(0, 1), b2 + hstep, voffB); PG8_STAGE(PG8_SA(0, 0), a2, voffA);
;             PG8_WAIT_V(8); PG8_WAIT_L(0); PG8_BAR; PG8_MMA(1, 0, At, B0); PG8_MMA(1, 1, At, B1); PG8_BAR; PG8_SCHED;
;             PG8_LDB(B0, 1, 0); PG8_LDB(B1, 1, 1); PG8_SCHED; PG8_LDA(At, 1, 0); PG8_STAGE(PG8_SA(0, 1), a2 + hstepA, voffA);
;             PG8_WAIT_V(8); PG8_WAIT_L(0); PG8_BAR; PG8_MMA(0, 0, At, B0); PG8_MMA(0, 1, At, B1); PG8_BAR; PG8_SCHED;
;             PG8_LDA(At, 1, 1); PG8_STAGE(PG8_SB(1, 0), b3, voffB); PG8_STAGE(PG8_SB(1, 1), b3 + hstep, voffB); PG8_STAGE(PG8_SA(1, 0), a3, voffA);
;             PG8_WAIT_V(8); PG8_WAIT_L(0); PG8_BAR; PG8_MMA(1, 0, At, B0); PG8_MMA(1, 1, At, B1); PG8_BAR; PG8_SCHED;
	s_add_i32 s28, s63, s30
	v_lshl_add_u64 v[168:169], v[168:169], 0, s[90:91]
	s_mov_b32 m0, s28
	ds_read_b128 v[186:189], v147 offset:49152
	ds_read_b128 v[190:193], v147 offset:50176
	ds_read_b128 v[194:197], v147 offset:51200
	ds_read_b128 v[198:201], v147 offset:52224
	ds_read_b128 v[202:205], v147 offset:53248
	ds_read_b128 v[206:209], v147 offset:54272
	ds_read_b128 v[210:213], v147 offset:55296
	ds_read_b128 v[214:217], v147 offset:56320
	global_load_lds_dwordx4 v[168:169], off
	s_add_i32 m0, s28, 0x2000
	s_add_u32 s26, s26, 0x80080
	v_lshl_add_u64 v[168:169], v[218:219], 0, s[90:91]
	s_addc_u32 s27, s27, 0
	s_add_i32 s28, s55, s30
	global_load_lds_dwordx4 v[168:169], off
	v_lshl_add_u64 v[168:169], s[26:27], 0, v[0:1]
	s_mov_b32 m0, s28
	s_nop 0
	global_load_lds_dwordx4 v[168:169], off
	v_lshl_add_u64 v[168:169], s[26:27], 0, v[130:131]
	s_add_i32 m0, s28, 0x2000
	s_nop 0
	global_load_lds_dwordx4 v[168:169], off
	v_lshl_add_u64 v[168:169], v[220:221], 0, s[90:91]
	s_mov_b32 m0, s41
	s_nop 0
	global_load_lds_dwordx4 v[168:169], off
	v_lshl_add_u64 v[168:169], v[222:223], 0, s[90:91]
	s_mov_b32 m0, s42
	s_nop 0
	global_load_lds_dwordx4 v[168:169], off
	s_add_u32 s24, s24, 0x100
	s_addc_u32 s25, s25, 0
	s_add_u32 s68, s68, 0x100
	s_addc_u32 s70, s70, 0
	s_cmp_ge_u32 s76, s45
	s_mov_b32 s26, s76
	s_waitcnt vmcnt(8)
	s_waitcnt lgkmcnt(0)
	s_barrier
	s_setprio 1
	s_waitcnt lgkmcnt(0)
	v_mfma_f32_16x16x32_bf16 v[62:65], v[136:139], v[186:189], v[62:65]
	v_mfma_f32_16x16x32_bf16 v[58:61], v[148:151], v[186:189], v[58:61]
	v_mfma_f32_16x16x32_bf16 v[54:57], v[136:139], v[194:197], v[54:57]
	v_mfma_f32_16x16x32_bf16 v[50:53], v[148:151], v[194:197], v[50:53]
	v_mfma_f32_16x16x32_bf16 v[46:49], v[136:139], v[202:205], v[46:49]
	v_mfma_f32_16x16x32_bf16 v[42:45], v[148:151], v[202:205], v[42:45]
	v_mfma_f32_16x16x32_bf16 v[38:41], v[136:139], v[210:213], v[38:41]
	v_mfma_f32_16x16x32_bf16 v[34:37], v[148:151], v[210:213], v[34:37]
	v_mfma_f32_16x16x32_bf16 v[62:65], v[140:143], v[190:193], v[62:65]
	v_mfma_f32_16x16x32_bf16 v[58:61], v[152:155], v[190:193], v[58:61]
	v_mfma_f32_16x16x32_bf16 v[54:57], v[140:143], v[198:201], v[54:57]
	v_mfma_f32_16x16x32_bf16 v[50:53], v[152:155], v[198:201], v[50:53]
	v_mfma_f32_16x16x32_bf16 v[46:49], v[140:143], v[206:209], v[46:49]
	v_mfma_f32_16x16x32_bf16 v[42:45], v[152:155], v[206:209], v[42:45]
	v_mfma_f32_16x16x32_bf16 v[38:41], v[140:143], v[214:217], v[38:41]
	v_mfma_f32_16x16x32_bf16 v[34:37], v[152:155], v[214:217], v[34:37]
	s_setprio 0
	s_setprio 1
	v_mfma_f32_16x16x32_bf16 v[30:33], v[156:159], v[186:189], v[30:33]
	v_mfma_f32_16x16x32_bf16 v[26:29], v[164:167], v[186:189], v[26:29]
	v_mfma_f32_16x16x32_bf16 v[22:25], v[156:159], v[194:197], v[22:25]
	v_mfma_f32_16x16x32_bf16 v[18:21], v[164:167], v[194:197], v[18:21]
	v_mfma_f32_16x16x32_bf16 v[14:17], v[156:159], v[202:205], v[14:17]
	v_mfma_f32_16x16x32_bf16 v[10:13], v[164:167], v[202:205], v[10:13]
	v_mfma_f32_16x16x32_bf16 v[6:9], v[156:159], v[210:213], v[6:9]
	v_mfma_f32_16x16x32_bf16 v[2:5], v[164:167], v[210:213], v[2:5]
	v_mfma_f32_16x16x32_bf16 v[30:33], v[160:163], v[190:193], v[30:33]
	v_mfma_f32_16x16x32_bf16 v[26:29], v[182:185], v[190:193], v[26:29]
	v_mfma_f32_16x16x32_bf16 v[22:25], v[160:163], v[198:201], v[22:25]
	v_mfma_f32_16x16x32_bf16 v[18:21], v[182:185], v[198:201], v[18:21]
	v_mfma_f32_16x16x32_bf16 v[14:17], v[160:163], v[206:209], v[14:17]
	v_mfma_f32_16x16x32_bf16 v[10:13], v[182:185], v[206:209], v[10:13]
	v_mfma_f32_16x16x32_bf16 v[6:9], v[160:163], v[214:217], v[6:9]
	v_mfma_f32_16x16x32_bf16 v[2:5], v[182:185], v[214:217], v[2:5]
	s_setprio 0
	s_barrier
	s_cbranch_scc0 .LBB0_1348
	s_and_b64 vcc, exec, s[16:17]
	s_cbranch_vccz .LBB0_1351
	s_barrier

; #define PG8_STAGE(bufoff, gbase, voff) do { _Pragma("unroll") for (int _i = 0; _i < 2; ++_i) \
;         __builtin_amdgcn_global_load_lds((const unsigned*)((const char*)(gbase) + (voff)[_i]), (PG8_LAS unsigned*)(lds + (bufoff) + ldsw + _i * 8192), 16, 0, 0); } while (0)
; #define PG8_LDA(dst, b, h) do { _Pragma("unroll") for (int m = 0; m < 4; ++m) _Pragma("unroll") for (int k = 0; k < 2; ++k) dst[m][k] = *(const PG8_LAS bf16x8*)(lds + PG8_SA(b, h) + aoff + m * 2048 + k * 1024); } while (0)
; #define PG8_LDB(dst, b, h) do { _Pragma("unroll") for (int n = 0; n < 2; ++n) _Pragma("unroll") for (int k = 0; k < 2; ++k) dst[n][k] = *(const PG8_LAS bf16x8*)(lds + PG8_SB(b, h) + boff + n * 2048 + k * 1024); } while (0)
; #define PG8_MMA(ai, bj, At, Bt) do { __builtin_amdgcn_s_setprio(1); _Pragma("unroll") for (int m = 0; m < 4; ++m) _Pragma("unroll") for (int n = 0; n < 2; ++n) _Pragma("unroll") for (int k = 0; k < 2; ++k) \
;         acc[ai][bj][m][n] = __builtin_amdgcn_mfma_f32_16x16x32_bf16(Bt[n][k], At[m][k], acc[ai][bj][m][n], 0, 0, 0); __builtin_amdgcn_s_setprio(0); } while (0)
; #define PG8_WAIT_V(n) asm volatile("s_waitcnt vmcnt(" #n ")" ::: "memory")
; #define PG8_WAIT_L(n) asm volatile("s_waitcnt lgkmcnt(" #n ")" ::: "memory")
; template <class Epi, class Sched, bool ALIGN_EPI = false, bool SP2 = false>
; __device__ __forceinline__ void gemm_phase(PG8_LAS unsigned char* lds, const Gemm g, const Sched& S, const Epi& E, int tid_in) {
;     ...
;             const bool last = (t == nt - 2);
;             const char* a1 = cA + (size_t)(t + 1) * kstep;
;             const char* a2 = last ? nA : cA + (size_t)(t + 2) * kstep; const char* b2 = last ? nB : cB + (size_t)(t + 2) * kstep;
;             const char* a3 = a2 + kstep; const char* b3 = b2 + kstep;
;             if (last && has_next) S.a_ready(nxt);
;             if constexpr (SP2) {
;             PG8_LDB(B0, 0, 0); PG8_LDB(B1, 0, 1); PG8_SCHED; PG8_LDA(At, 0, 0); PG8_STAGE(PG8_SA(1, 1), a1 + hstepA, voffA);
;             PG8_WAIT_V(8); PG8_WAIT_L(0); PG8_BAR; PG8_MMA(0, 0, At, B0); PG8_MMA(0, 1, At, B1); PG8_BAR; PG8_SCHED;
;             PG8_LDA(At, 0, 1); PG8_STAGE(PG8_SB(0, 0), b2, voffB); PG8_STAGE(PG8_SB(0, 1), b2 + hstep, voffB); PG8_STAGE(PG8_SA(0, 0), a2, voffA);
;             PG8_WAIT_V(8); PG8_WAIT_L(0); PG8_BAR; PG8_MMA(1, 0, At, B0); PG8_MMA(1, 1, At, B1); PG8_BAR; PG8_SCHED;
.LBB0_1507:
	v_add_u32_e32 v158, s4, v152
	v_add_u32_e32 v186, s5, v152
	ds_read_b128 v[142:145], v158
	ds_read_b128 v[146:149], v158 offset:1024
	ds_read_b128 v[154:157], v158 offset:2048
	ds_read_b128 v[158:161], v158 offset:3072
	ds_read_b128 v[162:165], v186
	ds_read_b128 v[166:169], v186 offset:1024
	ds_read_b128 v[182:185], v186 offset:2048
	ds_read_b128 v[186:189], v186 offset:3072
	s_add_u32 s26, s24, 0xfff80080
	s_addc_u32 s27, s25, -1
	s_cmp_eq_u32 s23, 28
	s_cselect_b32 s29, s19, s27
	s_cselect_b32 s28, s18, s26
	s_cselect_b32 s27, s21, s17
	s_cselect_b32 s26, s20, s15
	v_lshl_add_u64 v[222:223], s[24:25], 0, v[138:139]
	s_add_i32 m0, s35, 0xc000
	ds_read_b128 v[190:193], v153
	ds_read_b128 v[194:197], v153 offset:1024
	ds_read_b128 v[198:201], v153 offset:2048
	ds_read_b128 v[202:205], v153 offset:3072
	ds_read_b128 v[206:209], v153 offset:4096
	ds_read_b128 v[210:213], v153 offset:5120
	ds_read_b128 v[214:217], v153 offset:6144
	ds_read_b128 v[218:221], v153 offset:7168
	global_load_lds_dwordx4 v[222:223], off
	v_lshl_add_u64 v[222:223], s[24:25], 0, v[140:141]
	s_add_i32 m0, s35, 0xe000
	s_nop 0
	global_load_lds_dwordx4 v[222:223], off
	s_waitcnt vmcnt(8)
	s_waitcnt lgkmcnt(0)
	s_barrier
	s_setprio 1
	s_waitcnt lgkmcnt(0)
	v_mfma_f32_16x16x32_bf16 v[126:129], v[142:145], v[190:193], v[126:129]
	v_mfma_f32_16x16x32_bf16 v[118:121], v[154:157], v[190:193], v[118:121]
	v_mfma_f32_16x16x32_bf16 v[110:113], v[142:145], v[198:201], v[110:113]
	v_mfma_f32_16x16x32_bf16 v[102:105], v[154:157], v[198:201], v[102:105]
	v_mfma_f32_16x16x32_bf16 v[94:97], v[142:145], v[206:209], v[94:97]
	v_mfma_f32_16x16x32_bf16 v[86:89], v[154:157], v[206:209], v[86:89]
	v_mfma_f32_16x16x32_bf16 v[78:81], v[142:145], v[214:217], v[78:81]
	v_mfma_f32_16x16x32_bf16 v[70:73], v[154:157], v[214:217], v[70:73]
	v_mfma_f32_16x16x32_bf16 v[126:129], v[146:149], v[194:197], v[126:129]
	v_mfma_f32_16x16x32_bf16 v[118:121], v[158:161], v[194:197], v[118:121]
	v_mfma_f32_16x16x32_bf16 v[110:113], v[146:149], v[202:205], v[110:113]
	v_mfma_f32_16x16x32_bf16 v[102:105], v[158:161], v[202:205], v[102:105]
	v_mfma_f32_16x16x32_bf16 v[94:97], v[146:149], v[210:213], v[94:97]
	v_mfma_f32_16x16x32_bf16 v[86:89], v[158:161], v[210:213], v[86:89]
	v_mfma_f32_16x16x32_bf16 v[78:81], v[146:149], v[218:221], v[78:81]
	v_mfma_f32_16x16x32_bf16 v[70:73], v[158:161], v[218:221], v[70:73]
	s_setprio 0
	s_setprio 1
	v_mfma_f32_16x16x32_bf16 v[122:125], v[162:165], v[190:193], v[122:125]
	v_mfma_f32_16x16x32_bf16 v[114:117], v[182:185], v[190:193], v[114:117]
	v_mfma_f32_16x16x32_bf16 v[106:109], v[162:165], v[198:201], v[106:109]
	v_mfma_f32_16x16x32_bf16 v[98:101], v[182:185], v[198:201], v[98:101]
	v_mfma_f32_16x16x32_bf16 v[90:93], v[162:165], v[206:209], v[90:93]
	v_mfma_f32_16x16x32_bf16 v[82:85], v[182:185], v[206:209], v[82:85]
	v_mfma_f32_16x16x32_bf16 v[74:77], v[162:165], v[214:217], v[74:77]
	v_mfma_f32_16x16x32_bf16 v[66:69], v[182:185], v[214:217], v[66:69]
	v_mfma_f32_16x16x32_bf16 v[122:125], v[166:169], v[194:197], v[122:125]
	v_mfma_f32_16x16x32_bf16 v[114:117], v[186:189], v[194:197], v[114:117]
	v_mfma_f32_16x16x32_bf16 v[106:109], v[166:169], v[202:205], v[106:109]
	v_mfma_f32_16x16x32_bf16 v[98:101], v[186:189], v[202:205], v[98:101]
	v_mfma_f32_16x16x32_bf16 v[90:93], v[166:169], v[210:213], v[90:93]
	v_mfma_f32_16x16x32_bf16 v[82:85], v[186:189], v[210:213], v[82:85]
	v_mfma_f32_16x16x32_bf16 v[74:77], v[166:169], v[218:221], v[74:77]
	v_mfma_f32_16x16x32_bf16 v[66:69], v[186:189], v[218:221], v[66:69]
	s_setprio 0
	s_barrier
	s_add_i32 s47, s4, s34
	v_lshl_add_u64 v[222:223], s[26:27], 0, v[0:1]
	s_mov_b32 m0, s47
	ds_read_b128 v[190:193], v153 offset:16384
	ds_read_b128 v[194:197], v153 offset:17408
	ds_read_b128 v[198:201], v153 offset:18432
	ds_read_b128 v[202:205], v153 offset:19456
	ds_read_b128 v[206:209], v153 offset:20480
	ds_read_b128 v[210:213], v153 offset:21504
	ds_read_b128 v[214:217], v153 offset:22528
	ds_read_b128 v[218:221], v153 offset:23552
	global_load_lds_dwordx4 v[222:223], off
	s_add_i32 m0, s47, 0x2000
	s_add_u32 s48, s26, 0x80000
	v_lshl_add_u64 v[224:225], s[26:27], 0, v[130:131]
	s_addc_u32 s49, s27, 0
	s_add_i32 s47, s5, s34
	global_load_lds_dwordx4 v[224:225], off
	v_lshl_add_u64 v[226:227], s[48:49], 0, v[0:1]
	s_mov_b32 m0, s47
	v_lshl_add_u64 v[228:229], s[28:29], 0, v[132:133]
	global_load_lds_dwordx4 v[226:227], off
	v_lshl_add_u64 v[226:227], s[48:49], 0, v[130:131]
	s_add_i32 m0, s47, 0x2000
	s_nop 0
	global_load_lds_dwordx4 v[226:227], off
	s_waitcnt vmcnt(6)
	s_waitcnt lgkmcnt(0)
	s_barrier
; #define PG8_STAGE(bufoff, gbase, voff) do { _Pragma("unroll") for (int _i = 0; _i < 2; ++_i) \
;         __builtin_amdgcn_global_load_lds((const unsigned*)((const char*)(gbase) + (voff)[_i]), (PG8_LAS unsigned*)(lds + (bufoff) + ldsw + _i * 8192), 16, 0, 0); } while (0)
; #define PG8_LDA(dst, b, h) do { _Pragma("unroll") for (int m = 0; m < 4; ++m) _Pragma("unroll") for (int k = 0; k < 2; ++k) dst[m][k] = *(const PG8_LAS bf16x8*)(lds + PG8_SA(b, h) + aoff + m * 2048 + k * 1024); } while (0)
; #define PG8_LDB(dst, b, h) do { _Pragma("unroll") for (int n = 0; n < 2; ++n) _Pragma("unroll") for (int k = 0; k < 2; ++k) dst[n][k] = *(const PG8_LAS bf16x8*)(lds + PG8_SB(b, h) + boff + n * 2048 + k * 1024); } while (0)
; #define PG8_MMA(ai, bj, At, Bt) do { __builtin_amdgcn_s_setprio(1); _Pragma("unroll") for (int m = 0; m < 4; ++m) _Pragma("unroll") for (int n = 0; n < 2; ++n) _Pragma("unroll") for (int k = 0; k < 2; ++k) \
;         acc[ai][bj][m][n] = __builtin_amdgcn_mfma_f32_16x16x32_bf16(Bt[n][k], At[m][k], acc[ai][bj][m][n], 0, 0, 0); __builtin_amdgcn_s_setprio(0); } while (0)
; #define PG8_WAIT_V(n) asm volatile("s_waitcnt vmcnt(" #n ")" ::: "memory")
; #define PG8_WAIT_L(n) asm volatile("s_waitcnt lgkmcnt(" #n ")" ::: "memory")
; #define PG8_BAR __builtin_amdgcn_s_barrier()
; #define PG8_SCHED __builtin_amdgcn_sched_barrier(0)
; template <class Epi, class Sched, bool ALIGN_EPI = false, bool SP2 = false>
; __device__ __forceinline__ void gemm_phase(PG8_LAS unsigned char* lds, const Gemm g, const Sched& S, const Epi& E, int tid_in) {
;     ...
;             PG8_WAIT_V(8); PG8_WAIT_L(0); PG8_BAR; PG8_MMA(1, 0, At, B0); PG8_MMA(1, 1, At, B1); PG8_BAR; PG8_SCHED;
;             PG8_LDB(B0, 1, 0); PG8_LDB(B1, 1, 1); PG8_SCHED; PG8_LDA(At, 1, 0); PG8_STAGE(PG8_SA(0, 1), a2 + hstepA, voffA);
;             PG8_WAIT_V(8); PG8_WAIT_L(0); PG8_BAR; PG8_MMA(0, 0, At, B0); PG8_MMA(0, 1, At, B1); PG8_BAR; PG8_SCHED;
	s_setprio 1
	s_waitcnt lgkmcnt(0)
	v_mfma_f32_16x16x32_bf16 v[62:65], v[142:145], v[190:193], v[62:65]
	v_mfma_f32_16x16x32_bf16 v[54:57], v[154:157], v[190:193], v[54:57]
	v_mfma_f32_16x16x32_bf16 v[46:49], v[142:145], v[198:201], v[46:49]
	v_mfma_f32_16x16x32_bf16 v[38:41], v[154:157], v[198:201], v[38:41]
	v_mfma_f32_16x16x32_bf16 v[30:33], v[142:145], v[206:209], v[30:33]
	v_mfma_f32_16x16x32_bf16 v[22:25], v[154:157], v[206:209], v[22:25]
	v_mfma_f32_16x16x32_bf16 v[14:17], v[142:145], v[214:217], v[14:17]
	v_mfma_f32_16x16x32_bf16 v[6:9], v[154:157], v[214:217], v[6:9]
	v_mfma_f32_16x16x32_bf16 v[62:65], v[146:149], v[194:197], v[62:65]
	v_mfma_f32_16x16x32_bf16 v[54:57], v[158:161], v[194:197], v[54:57]
	v_mfma_f32_16x16x32_bf16 v[46:49], v[146:149], v[202:205], v[46:49]
	v_mfma_f32_16x16x32_bf16 v[38:41], v[158:161], v[202:205], v[38:41]
	v_mfma_f32_16x16x32_bf16 v[30:33], v[146:149], v[210:213], v[30:33]
	v_mfma_f32_16x16x32_bf16 v[22:25], v[158:161], v[210:213], v[22:25]
	v_mfma_f32_16x16x32_bf16 v[14:17], v[146:149], v[218:221], v[14:17]
	v_mfma_f32_16x16x32_bf16 v[6:9], v[158:161], v[218:221], v[6:9]
	s_setprio 0
	s_setprio 1
	v_mfma_f32_16x16x32_bf16 v[58:61], v[162:165], v[190:193], v[58:61]
	v_mfma_f32_16x16x32_bf16 v[50:53], v[182:185], v[190:193], v[50:53]
	v_mfma_f32_16x16x32_bf16 v[42:45], v[162:165], v[198:201], v[42:45]
	v_mfma_f32_16x16x32_bf16 v[34:37], v[182:185], v[198:201], v[34:37]
	v_mfma_f32_16x16x32_bf16 v[26:29], v[162:165], v[206:209], v[26:29]
	v_mfma_f32_16x16x32_bf16 v[18:21], v[182:185], v[206:209], v[18:21]
	v_mfma_f32_16x16x32_bf16 v[10:13], v[162:165], v[214:217], v[10:13]
	v_mfma_f32_16x16x32_bf16 v[2:5], v[182:185], v[214:217], v[2:5]
	v_mfma_f32_16x16x32_bf16 v[58:61], v[166:169], v[194:197], v[58:61]
	v_mfma_f32_16x16x32_bf16 v[50:53], v[186:189], v[194:197], v[50:53]
	v_mfma_f32_16x16x32_bf16 v[42:45], v[166:169], v[202:205], v[42:45]
	v_mfma_f32_16x16x32_bf16 v[34:37], v[186:189], v[202:205], v[34:37]
	v_mfma_f32_16x16x32_bf16 v[26:29], v[166:169], v[210:213], v[26:29]
	v_mfma_f32_16x16x32_bf16 v[18:21], v[186:189], v[210:213], v[18:21]
	v_mfma_f32_16x16x32_bf16 v[10:13], v[166:169], v[218:221], v[10:13]
	v_mfma_f32_16x16x32_bf16 v[2:5], v[186:189], v[218:221], v[2:5]
	s_setprio 0
	s_barrier
	v_lshl_add_u64 v[226:227], s[28:29], 0, v[134:135]
	s_mov_b32 m0, s35
	s_nop 0
	global_load_lds_dwordx4 v[226:227], off
	s_mov_b32 m0, s36
	s_nop 0
	global_load_lds_dwordx4 v[228:229], off
	v_add_u32_e32 v158, s63, v152
	v_add_u32_e32 v186, s55, v152
	ds_read_b128 v[142:145], v158
	ds_read_b128 v[146:149], v158 offset:1024
	ds_read_b128 v[154:157], v158 offset:2048
	ds_read_b128 v[158:161], v158 offset:3072
	ds_read_b128 v[162:165], v186
	ds_read_b128 v[166:169], v186 offset:1024
	ds_read_b128 v[182:185], v186 offset:2048
	ds_read_b128 v[186:189], v186 offset:3072
	s_add_u32 s28, s28, 0x80000
	s_addc_u32 s29, s29, 0
	s_mov_b32 m0, s37
	v_lshl_add_u64 v[240:241], s[28:29], 0, v[134:135]
	ds_read_b128 v[190:193], v153 offset:32768
	ds_read_b128 v[194:197], v153 offset:33792
	ds_read_b128 v[198:201], v153 offset:34816
	ds_read_b128 v[202:205], v153 offset:35840
	ds_read_b128 v[206:209], v153 offset:36864
	ds_read_b128 v[210:213], v153 offset:37888
	ds_read_b128 v[214:217], v153 offset:38912
	ds_read_b128 v[218:221], v153 offset:39936
	global_load_lds_dwordx4 v[240:241], off
	v_lshl_add_u64 v[240:241], s[28:29], 0, v[132:133]
	s_mov_b32 m0, s38
	s_nop 0
	global_load_lds_dwordx4 v[240:241], off
	s_waitcnt vmcnt(8)
	s_waitcnt lgkmcnt(0)
	s_barrier
	s_setprio 1
	s_waitcnt lgkmcnt(0)
	v_mfma_f32_16x16x32_bf16 v[126:129], v[142:145], v[190:193], v[126:129]
	v_mfma_f32_16x16x32_bf16 v[118:121], v[154:157], v[190:193], v[118:121]
	v_mfma_f32_16x16x32_bf16 v[110:113], v[142:145], v[198:201], v[110:113]
	v_mfma_f32_16x16x32_bf16 v[102:105], v[154:157], v[198:201], v[102:105]
	v_mfma_f32_16x16x32_bf16 v[94:97], v[142:145], v[206:209], v[94:97]
	v_mfma_f32_16x16x32_bf16 v[86:89], v[154:157], v[206:209], v[86:89]
	v_mfma_f32_16x16x32_bf16 v[78:81], v[142:145], v[214:217], v[78:81]
	v_mfma_f32_16x16x32_bf16 v[70:73], v[154:157], v[214:217], v[70:73]
	v_mfma_f32_16x16x32_bf16 v[126:129], v[146:149], v[194:197], v[126:129]
	v_mfma_f32_16x16x32_bf16 v[118:121], v[158:161], v[194:197], v[118:121]
	v_mfma_f32_16x16x32_bf16 v[110:113], v[146:149], v[202:205], v[110:113]
	v_mfma_f32_16x16x32_bf16 v[102:105], v[158:161], v[202:205], v[102:105]
	v_mfma_f32_16x16x32_bf16 v[94:97], v[146:149], v[210:213], v[94:97]
	v_mfma_f32_16x16x32_bf16 v[86:89], v[158:161], v[210:213], v[86:89]
	v_mfma_f32_16x16x32_bf16 v[78:81], v[146:149], v[218:221], v[78:81]
	v_mfma_f32_16x16x32_bf16 v[70:73], v[158:161], v[218:221], v[70:73]
	s_setprio 0
	s_setprio 1
	v_mfma_f32_16x16x32_bf16 v[122:125], v[162:165], v[190:193], v[122:125]
	v_mfma_f32_16x16x32_bf16 v[114:117], v[182:185], v[190:193], v[114:117]
	v_mfma_f32_16x16x32_bf16 v[106:109], v[162:165], v[198:201], v[106:109]
	v_mfma_f32_16x16x32_bf16 v[98:101], v[182:185], v[198:201], v[98:101]
	v_mfma_f32_16x16x32_bf16 v[90:93], v[162:165], v[206:209], v[90:93]
	v_mfma_f32_16x16x32_bf16 v[82:85], v[182:185], v[206:209], v[82:85]
	v_mfma_f32_16x16x32_bf16 v[74:77], v[162:165], v[214:217], v[74:77]
	v_mfma_f32_16x16x32_bf16 v[66:69], v[182:185], v[214:217], v[66:69]
	v_mfma_f32_16x16x32_bf16 v[122:125], v[166:169], v[194:197], v[122:125]
	v_mfma_f32_16x16x32_bf16 v[114:117], v[186:189], v[194:197], v[114:117]
	v_mfma_f32_16x16x32_bf16 v[106:109], v[166:169], v[202:205], v[106:109]
	v_mfma_f32_16x16x32_bf16 v[98:101], v[186:189], v[202:205], v[98:101]
	v_mfma_f32_16x16x32_bf16 v[90:93], v[166:169], v[210:213], v[90:93]
	v_mfma_f32_16x16x32_bf16 v[82:85], v[186:189], v[210:213], v[82:85]
	v_mfma_f32_16x16x32_bf16 v[74:77], v[166:169], v[218:221], v[74:77]
	v_mfma_f32_16x16x32_bf16 v[66:69], v[186:189], v[218:221], v[66:69]
	s_setprio 0
	s_barrier
; #define PG8_STAGE(bufoff, gbase, voff) do { _Pragma("unroll") for (int _i = 0; _i < 2; ++_i) \
;         __builtin_amdgcn_global_load_lds((const unsigned*)((const char*)(gbase) + (voff)[_i]), (PG8_LAS unsigned*)(lds + (bufoff) + ldsw + _i * 8192), 16, 0, 0); } while (0)
; #define PG8_LDA(dst, b, h) do { _Pragma("unroll") for (int m = 0; m < 4; ++m) _Pragma("unroll") for (int k = 0; k < 2; ++k) dst[m][k] = *(const PG8_LAS bf16x8*)(lds + PG8_SA(b, h) + aoff + m * 2048 + k * 1024); } while (0)
; #define PG8_WAIT_V(n) asm volatile("s_waitcnt vmcnt(" #n ")" ::: "memory")
; #define PG8_WAIT_L(n) asm volatile("s_waitcnt lgkmcnt(" #n ")" ::: "memory")
; #define PG8_BAR __builtin_amdgcn_s_barrier()
; template <class Epi, class Sched, bool ALIGN_EPI = false, bool SP2 = false>
; __device__ __forceinline__ void gemm_phase(PG8_LAS unsigned char* lds, const Gemm g, const Sched& S, const Epi& E, int tid_in) {
;     ...
;         for (int t = 0; t < nt; t += 2) {
;             const bool last = (t == nt - 2);
;             const char* a1 = cA + (size_t)(t + 1) * kstep;
;             const char* a2 = last ? nA : cA + (size_t)(t + 2) * kstep; const char* b2 = last ? nB : cB + (size_t)(t + 2) * kstep;
;             const char* a3 = a2 + kstep; const char* b3 = b2 + kstep;
;             if (last && has_next) S.a_ready(nxt);
;             if constexpr (SP2) {
;             PG8_LDB(B0, 0, 0); PG8_LDB(B1, 0, 1); PG8_SCHED; PG8_LDA(At, 0, 0); PG8_STAGE(PG8_SA(1, 1), a1 + hstepA, voffA);
;             PG8_WAIT_V(8); PG8_WAIT_L(0); PG8_BAR; PG8_MMA(0, 0, At, B0); PG8_MMA(0, 1, At, B1); PG8_BAR; PG8_SCHED;
;             PG8_LDA(At, 0, 1); PG8_STAGE(PG8_SB(0, 0), b2, voffB); PG8_STAGE(PG8_SB(0, 1), b2 + hstep, voffB); PG8_STAGE(PG8_SA(0, 0), a2, voffA);
;             PG8_WAIT_V(8); PG8_WAIT_L(0); PG8_BAR; PG8_MMA(1, 0, At, B0); PG8_MMA(1, 1, At, B1); PG8_BAR; PG8_SCHED;
;             PG8_LDB(B0, 1, 0); PG8_LDB(B1, 1, 1); PG8_SCHED; PG8_LDA(At, 1, 0); PG8_STAGE(PG8_SA(0, 1), a2 + hstepA, voffA);
;             PG8_WAIT_V(8); PG8_WAIT_L(0); PG8_BAR; PG8_MMA(0, 0, At, B0); PG8_MMA(0, 1, At, B1); PG8_BAR; PG8_SCHED;
;             PG8_LDA(At, 1, 1); PG8_STAGE(PG8_SB(1, 0), b3, voffB); PG8_STAGE(PG8_SB(1, 1), b3 + hstep, voffB); PG8_STAGE(PG8_SA(1, 0), a3, voffA);
;             PG8_WAIT_V(8); PG8_WAIT_L(0); PG8_BAR; PG8_MMA(1, 0, At, B0); PG8_MMA(1, 1, At, B1); PG8_BAR; PG8_SCHED;
	s_add_i32 s28, s63, s34
	v_lshl_add_u64 v[222:223], v[222:223], 0, s[90:91]
	s_mov_b32 m0, s28
	ds_read_b128 v[190:193], v153 offset:49152
	ds_read_b128 v[194:197], v153 offset:50176
	ds_read_b128 v[198:201], v153 offset:51200
	ds_read_b128 v[202:205], v153 offset:52224
	ds_read_b128 v[206:209], v153 offset:53248
	ds_read_b128 v[210:213], v153 offset:54272
	ds_read_b128 v[214:217], v153 offset:55296
	ds_read_b128 v[218:221], v153 offset:56320
	global_load_lds_dwordx4 v[222:223], off
	s_add_i32 m0, s28, 0x2000
	s_add_u32 s26, s26, 0x80080
	v_lshl_add_u64 v[222:223], v[224:225], 0, s[90:91]
	s_addc_u32 s27, s27, 0
	s_add_i32 s28, s55, s34
	global_load_lds_dwordx4 v[222:223], off
	v_lshl_add_u64 v[222:223], s[26:27], 0, v[0:1]
	s_mov_b32 m0, s28
	s_nop 0
	global_load_lds_dwordx4 v[222:223], off
	v_lshl_add_u64 v[222:223], s[26:27], 0, v[130:131]
	s_add_i32 m0, s28, 0x2000
	s_nop 0
	global_load_lds_dwordx4 v[222:223], off
	v_lshl_add_u64 v[222:223], v[226:227], 0, s[90:91]
	s_mov_b32 m0, s41
	s_nop 0
	global_load_lds_dwordx4 v[222:223], off
	v_lshl_add_u64 v[222:223], v[228:229], 0, s[90:91]
	s_mov_b32 m0, s42
	s_nop 0
	global_load_lds_dwordx4 v[222:223], off
	s_add_i32 s23, s23, 2
	s_add_u32 s24, s24, 0x100
	s_addc_u32 s25, s25, 0
	s_add_u32 s15, s15, 0x100
	s_addc_u32 s17, s17, 0
	s_cmp_gt_u32 s23, 29
	s_waitcnt vmcnt(8)
	s_waitcnt lgkmcnt(0)
	s_barrier
	s_setprio 1
	s_waitcnt lgkmcnt(0)
	v_mfma_f32_16x16x32_bf16 v[62:65], v[142:145], v[190:193], v[62:65]
	v_mfma_f32_16x16x32_bf16 v[54:57], v[154:157], v[190:193], v[54:57]
	v_mfma_f32_16x16x32_bf16 v[46:49], v[142:145], v[198:201], v[46:49]
	v_mfma_f32_16x16x32_bf16 v[38:41], v[154:157], v[198:201], v[38:41]
	v_mfma_f32_16x16x32_bf16 v[30:33], v[142:145], v[206:209], v[30:33]
	v_mfma_f32_16x16x32_bf16 v[22:25], v[154:157], v[206:209], v[22:25]
	v_mfma_f32_16x16x32_bf16 v[14:17], v[142:145], v[214:217], v[14:17]
	v_mfma_f32_16x16x32_bf16 v[6:9], v[154:157], v[214:217], v[6:9]
	v_mfma_f32_16x16x32_bf16 v[62:65], v[146:149], v[194:197], v[62:65]
	v_mfma_f32_16x16x32_bf16 v[54:57], v[158:161], v[194:197], v[54:57]
	v_mfma_f32_16x16x32_bf16 v[46:49], v[146:149], v[202:205], v[46:49]
	v_mfma_f32_16x16x32_bf16 v[38:41], v[158:161], v[202:205], v[38:41]
	v_mfma_f32_16x16x32_bf16 v[30:33], v[146:149], v[210:213], v[30:33]
	v_mfma_f32_16x16x32_bf16 v[22:25], v[158:161], v[210:213], v[22:25]
	v_mfma_f32_16x16x32_bf16 v[14:17], v[146:149], v[218:221], v[14:17]
	v_mfma_f32_16x16x32_bf16 v[6:9], v[158:161], v[218:221], v[6:9]
	s_setprio 0
	s_setprio 1
	v_mfma_f32_16x16x32_bf16 v[58:61], v[162:165], v[190:193], v[58:61]
	v_mfma_f32_16x16x32_bf16 v[50:53], v[182:185], v[190:193], v[50:53]
	v_mfma_f32_16x16x32_bf16 v[42:45], v[162:165], v[198:201], v[42:45]
	v_mfma_f32_16x16x32_bf16 v[34:37], v[182:185], v[198:201], v[34:37]
	v_mfma_f32_16x16x32_bf16 v[26:29], v[162:165], v[206:209], v[26:29]
	v_mfma_f32_16x16x32_bf16 v[18:21], v[182:185], v[206:209], v[18:21]
	v_mfma_f32_16x16x32_bf16 v[10:13], v[162:165], v[214:217], v[10:13]
	v_mfma_f32_16x16x32_bf16 v[2:5], v[182:185], v[214:217], v[2:5]
	v_mfma_f32_16x16x32_bf16 v[58:61], v[166:169], v[194:197], v[58:61]
	v_mfma_f32_16x16x32_bf16 v[50:53], v[186:189], v[194:197], v[50:53]
	v_mfma_f32_16x16x32_bf16 v[42:45], v[166:169], v[202:205], v[42:45]
	v_mfma_f32_16x16x32_bf16 v[34:37], v[186:189], v[202:205], v[34:37]
	v_mfma_f32_16x16x32_bf16 v[26:29], v[166:169], v[210:213], v[26:29]
	v_mfma_f32_16x16x32_bf16 v[18:21], v[186:189], v[210:213], v[18:21]
	v_mfma_f32_16x16x32_bf16 v[10:13], v[166:169], v[218:221], v[10:13]
	v_mfma_f32_16x16x32_bf16 v[2:5], v[186:189], v[218:221], v[2:5]
	s_setprio 0
	s_barrier
	s_cbranch_scc0 .LBB0_1507
	s_and_b64 vcc, exec, s[12:13]
	s_cbranch_vccz .LBB0_1510
	s_barrier

; #define PG8_STAGE(bufoff, gbase, voff) do { _Pragma("unroll") for (int _i = 0; _i < 2; ++_i) \
;         __builtin_amdgcn_global_load_lds((const unsigned*)((const char*)(gbase) + (voff)[_i]), (PG8_LAS unsigned*)(lds + (bufoff) + ldsw + _i * 8192), 16, 0, 0); } while (0)
; #define PG8_LDA(dst, b, h) do { _Pragma("unroll") for (int m = 0; m < 4; ++m) _Pragma("unroll") for (int k = 0; k < 2; ++k) dst[m][k] = *(const PG8_LAS bf16x8*)(lds + PG8_SA(b, h) + aoff + m * 2048 + k * 1024); } while (0)
; #define PG8_LDB(dst, b, h) do { _Pragma("unroll") for (int n = 0; n < 2; ++n) _Pragma("unroll") for (int k = 0; k < 2; ++k) dst[n][k] = *(const PG8_LAS bf16x8*)(lds + PG8_SB(b, h) + boff + n * 2048 + k * 1024); } while (0)
; #define PG8_MMA(ai, bj, At, Bt) do { __builtin_amdgcn_s_setprio(1); _Pragma("unroll") for (int m = 0; m < 4; ++m) _Pragma("unroll") for (int n = 0; n < 2; ++n) _Pragma("unroll") for (int k = 0; k < 2; ++k) \
;         acc[ai][bj][m][n] = __builtin_amdgcn_mfma_f32_16x16x32_bf16(Bt[n][k], At[m][k], acc[ai][bj][m][n], 0, 0, 0); __builtin_amdgcn_s_setprio(0); } while (0)
; #define PG8_WAIT_V(n) asm volatile("s_waitcnt vmcnt(" #n ")" ::: "memory")
; #define PG8_WAIT_L(n) asm volatile("s_waitcnt lgkmcnt(" #n ")" ::: "memory")
; template <class Epi, class Sched, bool ALIGN_EPI = false, bool SP2 = false>
; __device__ __forceinline__ void gemm_phase(PG8_LAS unsigned char* lds, const Gemm g, const Sched& S, const Epi& E, int tid_in) {
;     ...
;             const bool last = (t == nt - 2);
;             const char* a1 = cA + (size_t)(t + 1) * kstep;
;             const char* a2 = last ? nA : cA + (size_t)(t + 2) * kstep; const char* b2 = last ? nB : cB + (size_t)(t + 2) * kstep;
;             const char* a3 = a2 + kstep; const char* b3 = b2 + kstep;
;             if (last && has_next) S.a_ready(nxt);
;             if constexpr (SP2) {
;             PG8_LDB(B0, 0, 0); PG8_LDB(B1, 0, 1); PG8_SCHED; PG8_LDA(At, 0, 0); PG8_STAGE(PG8_SA(1, 1), a1 + hstepA, voffA);
;             PG8_WAIT_V(8); PG8_WAIT_L(0); PG8_BAR; PG8_MMA(0, 0, At, B0); PG8_MMA(0, 1, At, B1); PG8_BAR; PG8_SCHED;
;             PG8_LDA(At, 0, 1); PG8_STAGE(PG8_SB(0, 0), b2, voffB); PG8_STAGE(PG8_SB(0, 1), b2 + hstep, voffB); PG8_STAGE(PG8_SA(0, 0), a2, voffA);
;             PG8_WAIT_V(8); PG8_WAIT_L(0); PG8_BAR; PG8_MMA(1, 0, At, B0); PG8_MMA(1, 1, At, B1); PG8_BAR; PG8_SCHED;
.LBB0_1577:
	v_add_u32_e32 v0, s4, v164
	ds_read_b128 v[130:133], v0
	ds_read_b128 v[142:145], v0 offset:1024
	ds_read_b128 v[146:149], v0 offset:2048
	ds_read_b128 v[150:153], v0 offset:3072
	v_add_u32_e32 v0, s5, v164
	ds_read_b128 v[154:157], v0
	ds_read_b128 v[158:161], v0 offset:1024
	ds_read_b128 v[166:169], v0 offset:2048
	ds_read_b128 v[182:185], v0 offset:3072
	s_add_i32 vcc_lo, s10, 2
	s_add_u32 s8, s6, 0x100
	s_addc_u32 s9, s7, 0
	s_cmp_eq_u32 s83, s10
	s_cselect_b32 s10, s82, s84
	s_cselect_b32 s37, s46, s9
	s_cselect_b32 s36, s47, s8
	s_cselect_b32 s11, s76, s85
	v_lshl_add_u64 v[218:219], s[6:7], 0, v[138:139]
	s_add_i32 m0, s38, 0xc000
	ds_read_b128 v[186:189], v165
	ds_read_b128 v[190:193], v165 offset:1024
	ds_read_b128 v[194:197], v165 offset:2048
	ds_read_b128 v[198:201], v165 offset:3072
	ds_read_b128 v[202:205], v165 offset:4096
	ds_read_b128 v[206:209], v165 offset:5120
	ds_read_b128 v[210:213], v165 offset:6144
	ds_read_b128 v[214:217], v165 offset:7168
	global_load_lds_dwordx4 v[218:219], off
	v_lshl_add_u64 v[218:219], s[6:7], 0, v[140:141]
	s_add_i32 m0, s38, 0xe000
	s_nop 0
	global_load_lds_dwordx4 v[218:219], off
	s_waitcnt vmcnt(8)
	s_waitcnt lgkmcnt(0)
	s_barrier
	s_setprio 1
	s_waitcnt lgkmcnt(0)
	v_mfma_f32_16x16x32_bf16 v[126:129], v[130:133], v[186:189], v[126:129]
	v_mfma_f32_16x16x32_bf16 v[122:125], v[146:149], v[186:189], v[122:125]
	v_mfma_f32_16x16x32_bf16 v[118:121], v[130:133], v[194:197], v[118:121]
	v_mfma_f32_16x16x32_bf16 v[114:117], v[146:149], v[194:197], v[114:117]
	v_mfma_f32_16x16x32_bf16 v[110:113], v[130:133], v[202:205], v[110:113]
	v_mfma_f32_16x16x32_bf16 v[106:109], v[146:149], v[202:205], v[106:109]
	v_mfma_f32_16x16x32_bf16 v[102:105], v[130:133], v[210:213], v[102:105]
	v_mfma_f32_16x16x32_bf16 v[98:101], v[146:149], v[210:213], v[98:101]
	v_mfma_f32_16x16x32_bf16 v[126:129], v[142:145], v[190:193], v[126:129]
	v_mfma_f32_16x16x32_bf16 v[122:125], v[150:153], v[190:193], v[122:125]
	v_mfma_f32_16x16x32_bf16 v[118:121], v[142:145], v[198:201], v[118:121]
	v_mfma_f32_16x16x32_bf16 v[114:117], v[150:153], v[198:201], v[114:117]
	v_mfma_f32_16x16x32_bf16 v[110:113], v[142:145], v[206:209], v[110:113]
	v_mfma_f32_16x16x32_bf16 v[106:109], v[150:153], v[206:209], v[106:109]
	v_mfma_f32_16x16x32_bf16 v[102:105], v[142:145], v[214:217], v[102:105]
	v_mfma_f32_16x16x32_bf16 v[98:101], v[150:153], v[214:217], v[98:101]
	s_setprio 0
	s_setprio 1
	v_mfma_f32_16x16x32_bf16 v[94:97], v[154:157], v[186:189], v[94:97]
	v_mfma_f32_16x16x32_bf16 v[90:93], v[166:169], v[186:189], v[90:93]
	v_mfma_f32_16x16x32_bf16 v[86:89], v[154:157], v[194:197], v[86:89]
	v_mfma_f32_16x16x32_bf16 v[82:85], v[166:169], v[194:197], v[82:85]
	v_mfma_f32_16x16x32_bf16 v[78:81], v[154:157], v[202:205], v[78:81]
	v_mfma_f32_16x16x32_bf16 v[74:77], v[166:169], v[202:205], v[74:77]
	v_mfma_f32_16x16x32_bf16 v[70:73], v[154:157], v[210:213], v[70:73]
	v_mfma_f32_16x16x32_bf16 v[66:69], v[166:169], v[210:213], v[66:69]
	v_mfma_f32_16x16x32_bf16 v[94:97], v[158:161], v[190:193], v[94:97]
	v_mfma_f32_16x16x32_bf16 v[90:93], v[182:185], v[190:193], v[90:93]
	v_mfma_f32_16x16x32_bf16 v[86:89], v[158:161], v[198:201], v[86:89]
	v_mfma_f32_16x16x32_bf16 v[82:85], v[182:185], v[198:201], v[82:85]
	v_mfma_f32_16x16x32_bf16 v[78:81], v[158:161], v[206:209], v[78:81]
	v_mfma_f32_16x16x32_bf16 v[74:77], v[182:185], v[206:209], v[74:77]
	v_mfma_f32_16x16x32_bf16 v[70:73], v[158:161], v[214:217], v[70:73]
	v_mfma_f32_16x16x32_bf16 v[66:69], v[182:185], v[214:217], v[66:69]
	s_setprio 0
	s_barrier
	s_add_i32 s6, s4, s33
	v_lshl_add_u64 v[218:219], s[10:11], 0, v[134:135]
	s_mov_b32 m0, s6
	ds_read_b128 v[186:189], v165 offset:16384
	ds_read_b128 v[190:193], v165 offset:17408
	ds_read_b128 v[194:197], v165 offset:18432
	ds_read_b128 v[198:201], v165 offset:19456
	ds_read_b128 v[202:205], v165 offset:20480
	ds_read_b128 v[206:209], v165 offset:21504
	ds_read_b128 v[210:213], v165 offset:22528
	ds_read_b128 v[214:217], v165 offset:23552
	global_load_lds_dwordx4 v[218:219], off
	s_add_i32 m0, s6, 0x2000
	s_add_u32 s6, s10, 0x160000
	v_lshl_add_u64 v[220:221], s[10:11], 0, v[136:137]
	s_addc_u32 s7, s11, 0
	s_add_i32 s64, s5, s33
	global_load_lds_dwordx4 v[220:221], off
	v_lshl_add_u64 v[222:223], s[6:7], 0, v[134:135]
	s_mov_b32 m0, s64
	v_lshl_add_u64 v[224:225], s[36:37], 0, v[136:137]
	global_load_lds_dwordx4 v[222:223], off
	v_lshl_add_u64 v[222:223], s[6:7], 0, v[136:137]
	s_add_i32 m0, s64, 0x2000
	s_nop 0
	global_load_lds_dwordx4 v[222:223], off
	s_waitcnt vmcnt(6)
	s_waitcnt lgkmcnt(0)
	s_barrier
; #define PG8_STAGE(bufoff, gbase, voff) do { _Pragma("unroll") for (int _i = 0; _i < 2; ++_i) \
;         __builtin_amdgcn_global_load_lds((const unsigned*)((const char*)(gbase) + (voff)[_i]), (PG8_LAS unsigned*)(lds + (bufoff) + ldsw + _i * 8192), 16, 0, 0); } while (0)
; #define PG8_LDA(dst, b, h) do { _Pragma("unroll") for (int m = 0; m < 4; ++m) _Pragma("unroll") for (int k = 0; k < 2; ++k) dst[m][k] = *(const PG8_LAS bf16x8*)(lds + PG8_SA(b, h) + aoff + m * 2048 + k * 1024); } while (0)
; #define PG8_LDB(dst, b, h) do { _Pragma("unroll") for (int n = 0; n < 2; ++n) _Pragma("unroll") for (int k = 0; k < 2; ++k) dst[n][k] = *(const PG8_LAS bf16x8*)(lds + PG8_SB(b, h) + boff + n * 2048 + k * 1024); } while (0)
; #define PG8_MMA(ai, bj, At, Bt) do { __builtin_amdgcn_s_setprio(1); _Pragma("unroll") for (int m = 0; m < 4; ++m) _Pragma("unroll") for (int n = 0; n < 2; ++n) _Pragma("unroll") for (int k = 0; k < 2; ++k) \
;         acc[ai][bj][m][n] = __builtin_amdgcn_mfma_f32_16x16x32_bf16(Bt[n][k], At[m][k], acc[ai][bj][m][n], 0, 0, 0); __builtin_amdgcn_s_setprio(0); } while (0)
; #define PG8_WAIT_V(n) asm volatile("s_waitcnt vmcnt(" #n ")" ::: "memory")
; #define PG8_WAIT_L(n) asm volatile("s_waitcnt lgkmcnt(" #n ")" ::: "memory")
; #define PG8_BAR __builtin_amdgcn_s_barrier()
; #define PG8_SCHED __builtin_amdgcn_sched_barrier(0)
; template <class Epi, class Sched, bool ALIGN_EPI = false, bool SP2 = false>
; __device__ __forceinline__ void gemm_phase(PG8_LAS unsigned char* lds, const Gemm g, const Sched& S, const Epi& E, int tid_in) {
;     ...
;             PG8_WAIT_V(8); PG8_WAIT_L(0); PG8_BAR; PG8_MMA(1, 0, At, B0); PG8_MMA(1, 1, At, B1); PG8_BAR; PG8_SCHED;
;             PG8_LDB(B0, 1, 0); PG8_LDB(B1, 1, 1); PG8_SCHED; PG8_LDA(At, 1, 0); PG8_STAGE(PG8_SA(0, 1), a2 + hstepA, voffA);
;             PG8_WAIT_V(8); PG8_WAIT_L(0); PG8_BAR; PG8_MMA(0, 0, At, B0); PG8_MMA(0, 1, At, B1); PG8_BAR; PG8_SCHED;
	s_setprio 1
	s_waitcnt lgkmcnt(0)
	v_mfma_f32_16x16x32_bf16 v[62:65], v[130:133], v[186:189], v[62:65]
	v_mfma_f32_16x16x32_bf16 v[58:61], v[146:149], v[186:189], v[58:61]
	v_mfma_f32_16x16x32_bf16 v[54:57], v[130:133], v[194:197], v[54:57]
	v_mfma_f32_16x16x32_bf16 v[50:53], v[146:149], v[194:197], v[50:53]
	v_mfma_f32_16x16x32_bf16 v[46:49], v[130:133], v[202:205], v[46:49]
	v_mfma_f32_16x16x32_bf16 v[42:45], v[146:149], v[202:205], v[42:45]
	v_mfma_f32_16x16x32_bf16 v[38:41], v[130:133], v[210:213], v[38:41]
	v_mfma_f32_16x16x32_bf16 v[34:37], v[146:149], v[210:213], v[34:37]
	v_mfma_f32_16x16x32_bf16 v[62:65], v[142:145], v[190:193], v[62:65]
	v_mfma_f32_16x16x32_bf16 v[58:61], v[150:153], v[190:193], v[58:61]
	v_mfma_f32_16x16x32_bf16 v[54:57], v[142:145], v[198:201], v[54:57]
	v_mfma_f32_16x16x32_bf16 v[50:53], v[150:153], v[198:201], v[50:53]
	v_mfma_f32_16x16x32_bf16 v[46:49], v[142:145], v[206:209], v[46:49]
	v_mfma_f32_16x16x32_bf16 v[42:45], v[150:153], v[206:209], v[42:45]
	v_mfma_f32_16x16x32_bf16 v[38:41], v[142:145], v[214:217], v[38:41]
	v_mfma_f32_16x16x32_bf16 v[34:37], v[150:153], v[214:217], v[34:37]
	s_setprio 0
	s_setprio 1
	v_mfma_f32_16x16x32_bf16 v[30:33], v[154:157], v[186:189], v[30:33]
	v_mfma_f32_16x16x32_bf16 v[26:29], v[166:169], v[186:189], v[26:29]
	v_mfma_f32_16x16x32_bf16 v[22:25], v[154:157], v[194:197], v[22:25]
	v_mfma_f32_16x16x32_bf16 v[18:21], v[166:169], v[194:197], v[18:21]
	v_mfma_f32_16x16x32_bf16 v[14:17], v[154:157], v[202:205], v[14:17]
	v_mfma_f32_16x16x32_bf16 v[10:13], v[166:169], v[202:205], v[10:13]
	v_mfma_f32_16x16x32_bf16 v[6:9], v[154:157], v[210:213], v[6:9]
	v_mfma_f32_16x16x32_bf16 v[2:5], v[166:169], v[210:213], v[2:5]
	v_mfma_f32_16x16x32_bf16 v[30:33], v[158:161], v[190:193], v[30:33]
	v_mfma_f32_16x16x32_bf16 v[26:29], v[182:185], v[190:193], v[26:29]
	v_mfma_f32_16x16x32_bf16 v[22:25], v[158:161], v[198:201], v[22:25]
	v_mfma_f32_16x16x32_bf16 v[18:21], v[182:185], v[198:201], v[18:21]
	v_mfma_f32_16x16x32_bf16 v[14:17], v[158:161], v[206:209], v[14:17]
	v_mfma_f32_16x16x32_bf16 v[10:13], v[182:185], v[206:209], v[10:13]
	v_mfma_f32_16x16x32_bf16 v[6:9], v[158:161], v[214:217], v[6:9]
	v_mfma_f32_16x16x32_bf16 v[2:5], v[182:185], v[214:217], v[2:5]
	s_setprio 0
	s_barrier
	v_lshl_add_u64 v[222:223], s[36:37], 0, v[134:135]
	s_mov_b32 m0, s38
	s_nop 0
	global_load_lds_dwordx4 v[222:223], off
	s_mov_b32 m0, s39
	s_nop 0
	global_load_lds_dwordx4 v[224:225], off
	v_add_u32_e32 v0, s63, v164
	ds_read_b128 v[130:133], v0
	ds_read_b128 v[142:145], v0 offset:1024
	ds_read_b128 v[146:149], v0 offset:2048
	ds_read_b128 v[150:153], v0 offset:3072
	v_add_u32_e32 v0, s55, v164
	ds_read_b128 v[154:157], v0
	ds_read_b128 v[158:161], v0 offset:1024
	ds_read_b128 v[166:169], v0 offset:2048
	ds_read_b128 v[182:185], v0 offset:3072
	s_add_u32 s6, s36, 0x160000
	s_addc_u32 s7, s37, 0
	s_mov_b32 m0, s40
	v_lshl_add_u64 v[226:227], s[6:7], 0, v[134:135]
	ds_read_b128 v[186:189], v165 offset:32768
	ds_read_b128 v[190:193], v165 offset:33792
	ds_read_b128 v[194:197], v165 offset:34816
	ds_read_b128 v[198:201], v165 offset:35840
	ds_read_b128 v[202:205], v165 offset:36864
	ds_read_b128 v[206:209], v165 offset:37888
	ds_read_b128 v[210:213], v165 offset:38912
	ds_read_b128 v[214:217], v165 offset:39936
	global_load_lds_dwordx4 v[226:227], off
	v_lshl_add_u64 v[226:227], s[6:7], 0, v[136:137]
	s_mov_b32 m0, s41
	s_nop 0
	global_load_lds_dwordx4 v[226:227], off
	s_waitcnt vmcnt(8)
	s_waitcnt lgkmcnt(0)
	s_barrier
	s_setprio 1
	s_waitcnt lgkmcnt(0)
	v_mfma_f32_16x16x32_bf16 v[126:129], v[130:133], v[186:189], v[126:129]
	v_mfma_f32_16x16x32_bf16 v[122:125], v[146:149], v[186:189], v[122:125]
	v_mfma_f32_16x16x32_bf16 v[118:121], v[130:133], v[194:197], v[118:121]
	v_mfma_f32_16x16x32_bf16 v[114:117], v[146:149], v[194:197], v[114:117]
	v_mfma_f32_16x16x32_bf16 v[110:113], v[130:133], v[202:205], v[110:113]
	v_mfma_f32_16x16x32_bf16 v[106:109], v[146:149], v[202:205], v[106:109]
	v_mfma_f32_16x16x32_bf16 v[102:105], v[130:133], v[210:213], v[102:105]
	v_mfma_f32_16x16x32_bf16 v[98:101], v[146:149], v[210:213], v[98:101]
	v_mfma_f32_16x16x32_bf16 v[126:129], v[142:145], v[190:193], v[126:129]
	v_mfma_f32_16x16x32_bf16 v[122:125], v[150:153], v[190:193], v[122:125]
	v_mfma_f32_16x16x32_bf16 v[118:121], v[142:145], v[198:201], v[118:121]
	v_mfma_f32_16x16x32_bf16 v[114:117], v[150:153], v[198:201], v[114:117]
	v_mfma_f32_16x16x32_bf16 v[110:113], v[142:145], v[206:209], v[110:113]
	v_mfma_f32_16x16x32_bf16 v[106:109], v[150:153], v[206:209], v[106:109]
	v_mfma_f32_16x16x32_bf16 v[102:105], v[142:145], v[214:217], v[102:105]
	v_mfma_f32_16x16x32_bf16 v[98:101], v[150:153], v[214:217], v[98:101]
	s_setprio 0
	s_setprio 1
	v_mfma_f32_16x16x32_bf16 v[94:97], v[154:157], v[186:189], v[94:97]
	v_mfma_f32_16x16x32_bf16 v[90:93], v[166:169], v[186:189], v[90:93]
	v_mfma_f32_16x16x32_bf16 v[86:89], v[154:157], v[194:197], v[86:89]
	v_mfma_f32_16x16x32_bf16 v[82:85], v[166:169], v[194:197], v[82:85]
	v_mfma_f32_16x16x32_bf16 v[78:81], v[154:157], v[202:205], v[78:81]
	v_mfma_f32_16x16x32_bf16 v[74:77], v[166:169], v[202:205], v[74:77]
	v_mfma_f32_16x16x32_bf16 v[70:73], v[154:157], v[210:213], v[70:73]
	v_mfma_f32_16x16x32_bf16 v[66:69], v[166:169], v[210:213], v[66:69]
	v_mfma_f32_16x16x32_bf16 v[94:97], v[158:161], v[190:193], v[94:97]
	v_mfma_f32_16x16x32_bf16 v[90:93], v[182:185], v[190:193], v[90:93]
	v_mfma_f32_16x16x32_bf16 v[86:89], v[158:161], v[198:201], v[86:89]
	v_mfma_f32_16x16x32_bf16 v[82:85], v[182:185], v[198:201], v[82:85]
	v_mfma_f32_16x16x32_bf16 v[78:81], v[158:161], v[206:209], v[78:81]
	v_mfma_f32_16x16x32_bf16 v[74:77], v[182:185], v[206:209], v[74:77]
	v_mfma_f32_16x16x32_bf16 v[70:73], v[158:161], v[214:217], v[70:73]
	v_mfma_f32_16x16x32_bf16 v[66:69], v[182:185], v[214:217], v[66:69]
	s_setprio 0
	s_barrier
; #define PG8_STAGE(bufoff, gbase, voff) do { _Pragma("unroll") for (int _i = 0; _i < 2; ++_i) \
;         __builtin_amdgcn_global_load_lds((const unsigned*)((const char*)(gbase) + (voff)[_i]), (PG8_LAS unsigned*)(lds + (bufoff) + ldsw + _i * 8192), 16, 0, 0); } while (0)
; #define PG8_LDA(dst, b, h) do { _Pragma("unroll") for (int m = 0; m < 4; ++m) _Pragma("unroll") for (int k = 0; k < 2; ++k) dst[m][k] = *(const PG8_LAS bf16x8*)(lds + PG8_SA(b, h) + aoff + m * 2048 + k * 1024); } while (0)
; #define PG8_WAIT_V(n) asm volatile("s_waitcnt vmcnt(" #n ")" ::: "memory")
; #define PG8_WAIT_L(n) asm volatile("s_waitcnt lgkmcnt(" #n ")" ::: "memory")
; #define PG8_BAR __builtin_amdgcn_s_barrier()
; template <class Epi, class Sched, bool ALIGN_EPI = false, bool SP2 = false>
; __device__ __forceinline__ void gemm_phase(PG8_LAS unsigned char* lds, const Gemm g, const Sched& S, const Epi& E, int tid_in) {
;     ...
;         for (int t = 0; t < nt; t += 2) {
;             const bool last = (t == nt - 2);
;             const char* a1 = cA + (size_t)(t + 1) * kstep;
;             const char* a2 = last ? nA : cA + (size_t)(t + 2) * kstep; const char* b2 = last ? nB : cB + (size_t)(t + 2) * kstep;
;             const char* a3 = a2 + kstep; const char* b3 = b2 + kstep;
;             if (last && has_next) S.a_ready(nxt);
;             if constexpr (SP2) {
;             PG8_LDB(B0, 0, 0); PG8_LDB(B1, 0, 1); PG8_SCHED; PG8_LDA(At, 0, 0); PG8_STAGE(PG8_SA(1, 1), a1 + hstepA, voffA);
;             PG8_WAIT_V(8); PG8_WAIT_L(0); PG8_BAR; PG8_MMA(0, 0, At, B0); PG8_MMA(0, 1, At, B1); PG8_BAR; PG8_SCHED;
;             PG8_LDA(At, 0, 1); PG8_STAGE(PG8_SB(0, 0), b2, voffB); PG8_STAGE(PG8_SB(0, 1), b2 + hstep, voffB); PG8_STAGE(PG8_SA(0, 0), a2, voffA);
;             PG8_WAIT_V(8); PG8_WAIT_L(0); PG8_BAR; PG8_MMA(1, 0, At, B0); PG8_MMA(1, 1, At, B1); PG8_BAR; PG8_SCHED;
;             PG8_LDB(B0, 1, 0); PG8_LDB(B1, 1, 1); PG8_SCHED; PG8_LDA(At, 1, 0); PG8_STAGE(PG8_SA(0, 1), a2 + hstepA, voffA);
;             PG8_WAIT_V(8); PG8_WAIT_L(0); PG8_BAR; PG8_MMA(0, 0, At, B0); PG8_MMA(0, 1, At, B1); PG8_BAR; PG8_SCHED;
;             PG8_LDA(At, 1, 1); PG8_STAGE(PG8_SB(1, 0), b3, voffB); PG8_STAGE(PG8_SB(1, 1), b3 + hstep, voffB); PG8_STAGE(PG8_SA(1, 0), a3, voffA);
;             PG8_WAIT_V(8); PG8_WAIT_L(0); PG8_BAR; PG8_MMA(1, 0, At, B0); PG8_MMA(1, 1, At, B1); PG8_BAR; PG8_SCHED;
	s_add_i32 s6, s63, s33
	v_lshl_add_u64 v[218:219], v[218:219], 0, s[90:91]
	s_mov_b32 m0, s6
	ds_read_b128 v[186:189], v165 offset:49152
	ds_read_b128 v[190:193], v165 offset:50176
	ds_read_b128 v[194:197], v165 offset:51200
	ds_read_b128 v[198:201], v165 offset:52224
	ds_read_b128 v[202:205], v165 offset:53248
	ds_read_b128 v[206:209], v165 offset:54272
	ds_read_b128 v[210:213], v165 offset:55296
	ds_read_b128 v[214:217], v165 offset:56320
	global_load_lds_dwordx4 v[218:219], off
	s_add_i32 m0, s6, 0x2000
	s_add_u32 s6, s10, 0x160080
	v_lshl_add_u64 v[218:219], v[220:221], 0, s[90:91]
	s_addc_u32 s7, s11, 0
	s_add_i32 s10, s55, s33
	global_load_lds_dwordx4 v[218:219], off
	v_lshl_add_u64 v[218:219], s[6:7], 0, v[134:135]
	s_mov_b32 m0, s10
	s_nop 0
	global_load_lds_dwordx4 v[218:219], off
	v_lshl_add_u64 v[218:219], s[6:7], 0, v[136:137]
	s_add_i32 m0, s10, 0x2000
	s_nop 0
	global_load_lds_dwordx4 v[218:219], off
	v_lshl_add_u64 v[218:219], v[222:223], 0, s[90:91]
	s_mov_b32 m0, s49
	s_nop 0
	global_load_lds_dwordx4 v[218:219], off
	v_lshl_add_u64 v[218:219], v[224:225], 0, s[90:91]
	s_mov_b32 m0, s66
	s_nop 0
	global_load_lds_dwordx4 v[218:219], off
	s_add_u32 s84, s84, 0x100
	s_addc_u32 s85, s85, 0
	s_cmp_ge_u32 vcc_lo, s79
	s_mov_b64 s[6:7], s[8:9]
	s_mov_b32 s10, vcc_lo
	s_waitcnt vmcnt(8)
	s_waitcnt lgkmcnt(0)
	s_barrier
	s_setprio 1
	s_waitcnt lgkmcnt(0)
	v_mfma_f32_16x16x32_bf16 v[62:65], v[130:133], v[186:189], v[62:65]
	v_mfma_f32_16x16x32_bf16 v[58:61], v[146:149], v[186:189], v[58:61]
	v_mfma_f32_16x16x32_bf16 v[54:57], v[130:133], v[194:197], v[54:57]
	v_mfma_f32_16x16x32_bf16 v[50:53], v[146:149], v[194:197], v[50:53]
	v_mfma_f32_16x16x32_bf16 v[46:49], v[130:133], v[202:205], v[46:49]
	v_mfma_f32_16x16x32_bf16 v[42:45], v[146:149], v[202:205], v[42:45]
	v_mfma_f32_16x16x32_bf16 v[38:41], v[130:133], v[210:213], v[38:41]
	v_mfma_f32_16x16x32_bf16 v[34:37], v[146:149], v[210:213], v[34:37]
	v_mfma_f32_16x16x32_bf16 v[62:65], v[142:145], v[190:193], v[62:65]
	v_mfma_f32_16x16x32_bf16 v[58:61], v[150:153], v[190:193], v[58:61]
	v_mfma_f32_16x16x32_bf16 v[54:57], v[142:145], v[198:201], v[54:57]
	v_mfma_f32_16x16x32_bf16 v[50:53], v[150:153], v[198:201], v[50:53]
	v_mfma_f32_16x16x32_bf16 v[46:49], v[142:145], v[206:209], v[46:49]
	v_mfma_f32_16x16x32_bf16 v[42:45], v[150:153], v[206:209], v[42:45]
	v_mfma_f32_16x16x32_bf16 v[38:41], v[142:145], v[214:217], v[38:41]
	v_mfma_f32_16x16x32_bf16 v[34:37], v[150:153], v[214:217], v[34:37]
	s_setprio 0
	s_setprio 1
	v_mfma_f32_16x16x32_bf16 v[30:33], v[154:157], v[186:189], v[30:33]
	v_mfma_f32_16x16x32_bf16 v[26:29], v[166:169], v[186:189], v[26:29]
	v_mfma_f32_16x16x32_bf16 v[22:25], v[154:157], v[194:197], v[22:25]
	v_mfma_f32_16x16x32_bf16 v[18:21], v[166:169], v[194:197], v[18:21]
	v_mfma_f32_16x16x32_bf16 v[14:17], v[154:157], v[202:205], v[14:17]
	v_mfma_f32_16x16x32_bf16 v[10:13], v[166:169], v[202:205], v[10:13]
	v_mfma_f32_16x16x32_bf16 v[6:9], v[154:157], v[210:213], v[6:9]
	v_mfma_f32_16x16x32_bf16 v[2:5], v[166:169], v[210:213], v[2:5]
	v_mfma_f32_16x16x32_bf16 v[30:33], v[158:161], v[190:193], v[30:33]
	v_mfma_f32_16x16x32_bf16 v[26:29], v[182:185], v[190:193], v[26:29]
	v_mfma_f32_16x16x32_bf16 v[22:25], v[158:161], v[198:201], v[22:25]
	v_mfma_f32_16x16x32_bf16 v[18:21], v[182:185], v[198:201], v[18:21]
	v_mfma_f32_16x16x32_bf16 v[14:17], v[158:161], v[206:209], v[14:17]
	v_mfma_f32_16x16x32_bf16 v[10:13], v[182:185], v[206:209], v[10:13]
	v_mfma_f32_16x16x32_bf16 v[6:9], v[158:161], v[214:217], v[6:9]
	v_mfma_f32_16x16x32_bf16 v[2:5], v[182:185], v[214:217], v[2:5]
	s_setprio 0
	s_barrier
	s_cbranch_scc0 .LBB0_1577
	s_and_b64 vcc, exec, s[24:25]
	s_cbranch_vccz .LBB0_1580
	s_barrier
